# GEMM phases: first K iteration of each tile peeled (first MFMA into each accumulator takes C=0), the 128 per-tile accumulator zeroing moves removed
# speedup vs baseline: 1.0129x; 1.0129x over previous
.LBB0_74:
	s_ashr_i32 s13, s12, 31
	s_lshl_b64 s[0:1], s[12:13], 19
	v_cmp_lt_i64_e32 vcc, s[14:15], v[142:143]
	s_add_u32 s14, s68, s0
	s_addc_u32 s15, s69, s1
	s_and_b64 s[0:1], vcc, exec
	s_cselect_b32 s0, s15, s25
	s_cselect_b32 s1, s14, s24
	s_ashr_i32 s9, s8, 31
	s_lshl_b64 s[20:21], s[8:9], 19
	s_add_u32 s20, s31, s20
	s_addc_u32 s21, s33, s21
	s_and_b64 s[28:29], vcc, exec
	s_cselect_b32 s9, s21, s27
	s_cselect_b32 s13, s20, s26
	s_add_u32 s24, s24, 0x40080
	s_addc_u32 s25, s25, 0
	s_add_u32 s48, s26, 0x100
	s_addc_u32 s49, s27, 0
	s_mov_b32 s50, -2
	ds_read_b128 v[152:155], v149
	ds_read_b128 v[156:159], v149 offset:1024
	ds_read_b128 v[160:163], v149 offset:2048
	ds_read_b128 v[164:167], v149 offset:3072
	s_add_u32 s26, s24, 0xfffc0080
	s_addc_u32 s27, s25, -1
	s_cmp_eq_u32 s50, 12
	s_cselect_b32 s29, s0, s27
	s_cselect_b32 s28, s1, s26
	s_cselect_b32 s27, s9, s49
	s_cselect_b32 s26, s13, s48
	v_lshl_add_u64 v[200:201], s[24:25], 0, v[138:139]
	s_add_i32 m0, s23, 0xc000
	ds_read_b128 v[168:171], v150
	ds_read_b128 v[172:175], v150 offset:1024
	ds_read_b128 v[176:179], v150 offset:2048
	ds_read_b128 v[180:183], v150 offset:3072
	ds_read_b128 v[184:187], v150 offset:4096
	ds_read_b128 v[188:191], v150 offset:5120
	ds_read_b128 v[192:195], v150 offset:6144
	ds_read_b128 v[196:199], v150 offset:7168
	global_load_lds_dwordx4 v[200:201], off
	v_lshl_add_u64 v[200:201], s[24:25], 0, v[140:141]
	s_add_i32 m0, s23, 0xe000
	s_nop 0
	global_load_lds_dwordx4 v[200:201], off
	s_waitcnt lgkmcnt(8)
	s_barrier
	s_waitcnt lgkmcnt(0)
	s_setprio 1
	s_waitcnt lgkmcnt(0)
	v_mfma_f32_16x16x32_bf16 v[126:129], v[152:155], v[168:171], 0
	v_mfma_f32_16x16x32_bf16 v[122:125], v[160:163], v[168:171], 0
	v_mfma_f32_16x16x32_bf16 v[110:113], v[152:155], v[176:179], 0
	v_mfma_f32_16x16x32_bf16 v[106:109], v[160:163], v[176:179], 0
	v_mfma_f32_16x16x32_bf16 v[94:97], v[152:155], v[184:187], 0
	v_mfma_f32_16x16x32_bf16 v[90:93], v[160:163], v[184:187], 0
	v_mfma_f32_16x16x32_bf16 v[78:81], v[152:155], v[192:195], 0
	v_mfma_f32_16x16x32_bf16 v[74:77], v[160:163], v[192:195], 0
	v_mfma_f32_16x16x32_bf16 v[126:129], v[156:159], v[172:175], v[126:129]
	v_mfma_f32_16x16x32_bf16 v[122:125], v[164:167], v[172:175], v[122:125]
	v_mfma_f32_16x16x32_bf16 v[110:113], v[156:159], v[180:183], v[110:113]
	v_mfma_f32_16x16x32_bf16 v[106:109], v[164:167], v[180:183], v[106:109]
	v_mfma_f32_16x16x32_bf16 v[94:97], v[156:159], v[188:191], v[94:97]
	v_mfma_f32_16x16x32_bf16 v[90:93], v[164:167], v[188:191], v[90:93]
	v_mfma_f32_16x16x32_bf16 v[78:81], v[156:159], v[196:199], v[78:81]
	v_mfma_f32_16x16x32_bf16 v[74:77], v[164:167], v[196:199], v[74:77]
	s_setprio 0
	s_barrier
	s_add_i32 s51, s44, s34
	v_lshl_add_u64 v[216:217], s[26:27], 0, v[134:135]
	s_mov_b32 m0, s51
	ds_read_b128 v[200:203], v151
	ds_read_b128 v[204:207], v151 offset:1024
	ds_read_b128 v[208:211], v151 offset:2048
	ds_read_b128 v[212:215], v151 offset:3072
	global_load_lds_dwordx4 v[216:217], off
	v_lshl_add_u64 v[218:219], s[26:27], 0, v[130:131]
	s_add_i32 m0, s51, 0x2000
	s_nop 0
	global_load_lds_dwordx4 v[218:219], off
	s_barrier
	s_waitcnt lgkmcnt(0)
	s_setprio 1
	s_waitcnt lgkmcnt(0)
	v_mfma_f32_16x16x32_bf16 v[118:121], v[200:203], v[168:171], 0
	v_mfma_f32_16x16x32_bf16 v[114:117], v[208:211], v[168:171], 0
	v_mfma_f32_16x16x32_bf16 v[102:105], v[200:203], v[176:179], 0
	v_mfma_f32_16x16x32_bf16 v[98:101], v[208:211], v[176:179], 0
	v_mfma_f32_16x16x32_bf16 v[86:89], v[200:203], v[184:187], 0
	v_mfma_f32_16x16x32_bf16 v[82:85], v[208:211], v[184:187], 0
	v_mfma_f32_16x16x32_bf16 v[70:73], v[200:203], v[192:195], 0
	v_mfma_f32_16x16x32_bf16 v[66:69], v[208:211], v[192:195], 0
	v_mfma_f32_16x16x32_bf16 v[118:121], v[204:207], v[172:175], v[118:121]
	v_mfma_f32_16x16x32_bf16 v[114:117], v[212:215], v[172:175], v[114:117]
	v_mfma_f32_16x16x32_bf16 v[102:105], v[204:207], v[180:183], v[102:105]
	v_mfma_f32_16x16x32_bf16 v[98:101], v[212:215], v[180:183], v[98:101]
	v_mfma_f32_16x16x32_bf16 v[86:89], v[204:207], v[188:191], v[86:89]
	v_mfma_f32_16x16x32_bf16 v[82:85], v[212:215], v[188:191], v[82:85]
	v_mfma_f32_16x16x32_bf16 v[70:73], v[204:207], v[196:199], v[70:73]
	v_mfma_f32_16x16x32_bf16 v[66:69], v[212:215], v[196:199], v[66:69]
	s_setprio 0
	s_mov_b32 m0, s23
	v_lshl_add_u64 v[220:221], s[28:29], 0, v[136:137]
	s_barrier
	ds_read_b128 v[168:171], v150 offset:16384
	ds_read_b128 v[172:175], v150 offset:17408
	ds_read_b128 v[176:179], v150 offset:18432
	ds_read_b128 v[180:183], v150 offset:19456
	ds_read_b128 v[184:187], v150 offset:20480
	ds_read_b128 v[188:191], v150 offset:21504
	ds_read_b128 v[192:195], v150 offset:22528
	ds_read_b128 v[196:199], v150 offset:23552
	global_load_lds_dwordx4 v[220:221], off
	v_lshl_add_u64 v[222:223], s[28:29], 0, v[132:133]
	s_mov_b32 m0, s37
	s_nop 0
	global_load_lds_dwordx4 v[222:223], off
	s_barrier
	s_waitcnt lgkmcnt(0)
	s_setprio 1
	s_waitcnt lgkmcnt(0)
	v_mfma_f32_16x16x32_bf16 v[62:65], v[152:155], v[168:171], 0
	v_mfma_f32_16x16x32_bf16 v[58:61], v[160:163], v[168:171], 0
	v_mfma_f32_16x16x32_bf16 v[46:49], v[152:155], v[176:179], 0
	v_mfma_f32_16x16x32_bf16 v[42:45], v[160:163], v[176:179], 0
	v_mfma_f32_16x16x32_bf16 v[30:33], v[152:155], v[184:187], 0
	v_mfma_f32_16x16x32_bf16 v[26:29], v[160:163], v[184:187], 0
	v_mfma_f32_16x16x32_bf16 v[14:17], v[152:155], v[192:195], 0
	v_mfma_f32_16x16x32_bf16 v[10:13], v[160:163], v[192:195], 0
	v_mfma_f32_16x16x32_bf16 v[62:65], v[156:159], v[172:175], v[62:65]
	v_mfma_f32_16x16x32_bf16 v[58:61], v[164:167], v[172:175], v[58:61]
	v_mfma_f32_16x16x32_bf16 v[46:49], v[156:159], v[180:183], v[46:49]
	v_mfma_f32_16x16x32_bf16 v[42:45], v[164:167], v[180:183], v[42:45]
	v_mfma_f32_16x16x32_bf16 v[30:33], v[156:159], v[188:191], v[30:33]
	v_mfma_f32_16x16x32_bf16 v[26:29], v[164:167], v[188:191], v[26:29]
	v_mfma_f32_16x16x32_bf16 v[14:17], v[156:159], v[196:199], v[14:17]
	v_mfma_f32_16x16x32_bf16 v[10:13], v[164:167], v[196:199], v[10:13]
	s_setprio 0
	s_barrier
	s_add_u32 s52, s26, 0x40000
	s_addc_u32 s53, s27, 0
	s_add_i32 s51, s45, s34
	v_lshl_add_u64 v[152:153], s[52:53], 0, v[134:135]
	s_mov_b32 m0, s51
	s_nop 0
	global_load_lds_dwordx4 v[152:153], off
	v_lshl_add_u64 v[152:153], s[52:53], 0, v[130:131]
	s_add_i32 m0, s51, 0x2000
	s_nop 0
	global_load_lds_dwordx4 v[152:153], off
	s_waitcnt vmcnt(6)
	s_barrier
	s_setprio 1
	v_mfma_f32_16x16x32_bf16 v[54:57], v[200:203], v[168:171], 0
	v_mfma_f32_16x16x32_bf16 v[50:53], v[208:211], v[168:171], 0
	v_mfma_f32_16x16x32_bf16 v[38:41], v[200:203], v[176:179], 0
	v_mfma_f32_16x16x32_bf16 v[34:37], v[208:211], v[176:179], 0
	v_mfma_f32_16x16x32_bf16 v[22:25], v[200:203], v[184:187], 0
	v_mfma_f32_16x16x32_bf16 v[18:21], v[208:211], v[184:187], 0
	v_mfma_f32_16x16x32_bf16 v[6:9], v[200:203], v[192:195], 0
	v_mfma_f32_16x16x32_bf16 v[2:5], v[208:211], v[192:195], 0
	v_mfma_f32_16x16x32_bf16 v[54:57], v[204:207], v[172:175], v[54:57]
	v_mfma_f32_16x16x32_bf16 v[50:53], v[212:215], v[172:175], v[50:53]
	v_mfma_f32_16x16x32_bf16 v[38:41], v[204:207], v[180:183], v[38:41]
	v_mfma_f32_16x16x32_bf16 v[34:37], v[212:215], v[180:183], v[34:37]
	v_mfma_f32_16x16x32_bf16 v[22:25], v[204:207], v[188:191], v[22:25]
	v_mfma_f32_16x16x32_bf16 v[18:21], v[212:215], v[188:191], v[18:21]
	v_mfma_f32_16x16x32_bf16 v[6:9], v[204:207], v[196:199], v[6:9]
	v_mfma_f32_16x16x32_bf16 v[2:5], v[212:215], v[196:199], v[2:5]
	s_setprio 0
	s_add_i32 s51, 0, 0x18000
	v_add_u32_e32 v164, s51, v147
	s_barrier
	ds_read_b128 v[152:155], v164
	ds_read_b128 v[156:159], v164 offset:1024
	ds_read_b128 v[160:163], v164 offset:2048
	ds_read_b128 v[164:167], v164 offset:3072
	s_add_u32 s28, s28, 0x40000
	s_addc_u32 s29, s29, 0
	s_mov_b32 m0, s38
	v_lshl_add_u64 v[200:201], s[28:29], 0, v[136:137]
	ds_read_b128 v[168:171], v150 offset:32768
	ds_read_b128 v[172:175], v150 offset:33792
	ds_read_b128 v[176:179], v150 offset:34816
	ds_read_b128 v[180:183], v150 offset:35840
	ds_read_b128 v[184:187], v150 offset:36864
	ds_read_b128 v[188:191], v150 offset:37888
	ds_read_b128 v[192:195], v150 offset:38912
	ds_read_b128 v[196:199], v150 offset:39936
	global_load_lds_dwordx4 v[200:201], off
	v_lshl_add_u64 v[200:201], s[28:29], 0, v[132:133]
	s_mov_b32 m0, s39
	s_nop 0
	global_load_lds_dwordx4 v[200:201], off
	s_waitcnt lgkmcnt(8)
	s_barrier
	s_waitcnt lgkmcnt(0)
	s_setprio 1
	s_waitcnt lgkmcnt(0)
	v_mfma_f32_16x16x32_bf16 v[126:129], v[152:155], v[168:171], v[126:129]
	v_mfma_f32_16x16x32_bf16 v[122:125], v[160:163], v[168:171], v[122:125]
	v_mfma_f32_16x16x32_bf16 v[110:113], v[152:155], v[176:179], v[110:113]
	v_mfma_f32_16x16x32_bf16 v[106:109], v[160:163], v[176:179], v[106:109]
	v_mfma_f32_16x16x32_bf16 v[94:97], v[152:155], v[184:187], v[94:97]
	v_mfma_f32_16x16x32_bf16 v[90:93], v[160:163], v[184:187], v[90:93]
	v_mfma_f32_16x16x32_bf16 v[78:81], v[152:155], v[192:195], v[78:81]
	v_mfma_f32_16x16x32_bf16 v[74:77], v[160:163], v[192:195], v[74:77]
	v_mfma_f32_16x16x32_bf16 v[126:129], v[156:159], v[172:175], v[126:129]
	v_mfma_f32_16x16x32_bf16 v[122:125], v[164:167], v[172:175], v[122:125]
	v_mfma_f32_16x16x32_bf16 v[110:113], v[156:159], v[180:183], v[110:113]
	v_mfma_f32_16x16x32_bf16 v[106:109], v[164:167], v[180:183], v[106:109]
	v_mfma_f32_16x16x32_bf16 v[94:97], v[156:159], v[188:191], v[94:97]
	v_mfma_f32_16x16x32_bf16 v[90:93], v[164:167], v[188:191], v[90:93]
	v_mfma_f32_16x16x32_bf16 v[78:81], v[156:159], v[196:199], v[78:81]
	v_mfma_f32_16x16x32_bf16 v[74:77], v[164:167], v[196:199], v[74:77]
	s_setprio 0
	s_barrier
	s_add_i32 s28, 0, 0x1c000
	s_add_i32 s29, s51, s34
	v_add_u32_e32 v212, s28, v147
	v_lshl_add_u64 v[216:217], v[216:217], 0, s[6:7]
	s_mov_b32 m0, s29
	ds_read_b128 v[200:203], v212
	ds_read_b128 v[204:207], v212 offset:1024
	ds_read_b128 v[208:211], v212 offset:2048
	ds_read_b128 v[212:215], v212 offset:3072
	global_load_lds_dwordx4 v[216:217], off
	v_lshl_add_u64 v[216:217], v[218:219], 0, s[6:7]
	s_add_i32 m0, s29, 0x2000
	s_nop 0
	global_load_lds_dwordx4 v[216:217], off
	s_barrier
	s_waitcnt lgkmcnt(0)
	s_setprio 1
	s_waitcnt lgkmcnt(0)
	v_mfma_f32_16x16x32_bf16 v[118:121], v[200:203], v[168:171], v[118:121]
	v_mfma_f32_16x16x32_bf16 v[114:117], v[208:211], v[168:171], v[114:117]
	v_mfma_f32_16x16x32_bf16 v[102:105], v[200:203], v[176:179], v[102:105]
	v_mfma_f32_16x16x32_bf16 v[98:101], v[208:211], v[176:179], v[98:101]
	v_mfma_f32_16x16x32_bf16 v[86:89], v[200:203], v[184:187], v[86:89]
	v_mfma_f32_16x16x32_bf16 v[82:85], v[208:211], v[184:187], v[82:85]
	v_mfma_f32_16x16x32_bf16 v[70:73], v[200:203], v[192:195], v[70:73]
	v_mfma_f32_16x16x32_bf16 v[66:69], v[208:211], v[192:195], v[66:69]
	v_mfma_f32_16x16x32_bf16 v[118:121], v[204:207], v[172:175], v[118:121]
	v_mfma_f32_16x16x32_bf16 v[114:117], v[212:215], v[172:175], v[114:117]
	v_mfma_f32_16x16x32_bf16 v[102:105], v[204:207], v[180:183], v[102:105]
	v_mfma_f32_16x16x32_bf16 v[98:101], v[212:215], v[180:183], v[98:101]
	v_mfma_f32_16x16x32_bf16 v[86:89], v[204:207], v[188:191], v[86:89]
	v_mfma_f32_16x16x32_bf16 v[82:85], v[212:215], v[188:191], v[82:85]
	v_mfma_f32_16x16x32_bf16 v[70:73], v[204:207], v[196:199], v[70:73]
	v_mfma_f32_16x16x32_bf16 v[66:69], v[212:215], v[196:199], v[66:69]
	s_setprio 0
	s_mov_b32 m0, s41
	v_lshl_add_u64 v[216:217], v[220:221], 0, s[6:7]
	s_barrier
	ds_read_b128 v[168:171], v150 offset:49152
	ds_read_b128 v[172:175], v150 offset:50176
	ds_read_b128 v[176:179], v150 offset:51200
	ds_read_b128 v[180:183], v150 offset:52224
	ds_read_b128 v[184:187], v150 offset:53248
	ds_read_b128 v[188:191], v150 offset:54272
	ds_read_b128 v[192:195], v150 offset:55296
	ds_read_b128 v[196:199], v150 offset:56320
	global_load_lds_dwordx4 v[216:217], off
	v_lshl_add_u64 v[216:217], v[222:223], 0, s[6:7]
	s_mov_b32 m0, s42
	s_nop 0
	global_load_lds_dwordx4 v[216:217], off
	s_barrier
	s_waitcnt lgkmcnt(0)
	s_setprio 1
	s_waitcnt lgkmcnt(0)
	v_mfma_f32_16x16x32_bf16 v[62:65], v[152:155], v[168:171], v[62:65]
	v_mfma_f32_16x16x32_bf16 v[58:61], v[160:163], v[168:171], v[58:61]
	v_mfma_f32_16x16x32_bf16 v[46:49], v[152:155], v[176:179], v[46:49]
	v_mfma_f32_16x16x32_bf16 v[42:45], v[160:163], v[176:179], v[42:45]
	v_mfma_f32_16x16x32_bf16 v[30:33], v[152:155], v[184:187], v[30:33]
	v_mfma_f32_16x16x32_bf16 v[26:29], v[160:163], v[184:187], v[26:29]
	v_mfma_f32_16x16x32_bf16 v[14:17], v[152:155], v[192:195], v[14:17]
	v_mfma_f32_16x16x32_bf16 v[10:13], v[160:163], v[192:195], v[10:13]
	v_mfma_f32_16x16x32_bf16 v[62:65], v[156:159], v[172:175], v[62:65]
	v_mfma_f32_16x16x32_bf16 v[58:61], v[164:167], v[172:175], v[58:61]
	v_mfma_f32_16x16x32_bf16 v[46:49], v[156:159], v[180:183], v[46:49]
	v_mfma_f32_16x16x32_bf16 v[42:45], v[164:167], v[180:183], v[42:45]
	v_mfma_f32_16x16x32_bf16 v[30:33], v[156:159], v[188:191], v[30:33]
	v_mfma_f32_16x16x32_bf16 v[26:29], v[164:167], v[188:191], v[26:29]
	v_mfma_f32_16x16x32_bf16 v[14:17], v[156:159], v[196:199], v[14:17]
	v_mfma_f32_16x16x32_bf16 v[10:13], v[164:167], v[196:199], v[10:13]
	s_setprio 0
	s_barrier
	s_add_u32 s26, s26, 0x40080
	s_addc_u32 s27, s27, 0
	s_add_i32 s28, s28, s34
	v_lshl_add_u64 v[152:153], s[26:27], 0, v[134:135]
	s_mov_b32 m0, s28
	s_nop 0
	global_load_lds_dwordx4 v[152:153], off
	v_lshl_add_u64 v[152:153], s[26:27], 0, v[130:131]
	s_add_i32 m0, s28, 0x2000
	s_nop 0
	global_load_lds_dwordx4 v[152:153], off
	s_waitcnt vmcnt(6)
	s_barrier
	s_setprio 1
	v_mfma_f32_16x16x32_bf16 v[54:57], v[200:203], v[168:171], v[54:57]
	v_mfma_f32_16x16x32_bf16 v[50:53], v[208:211], v[168:171], v[50:53]
	v_mfma_f32_16x16x32_bf16 v[38:41], v[200:203], v[176:179], v[38:41]
	v_mfma_f32_16x16x32_bf16 v[34:37], v[208:211], v[176:179], v[34:37]
	v_mfma_f32_16x16x32_bf16 v[22:25], v[200:203], v[184:187], v[22:25]
	v_mfma_f32_16x16x32_bf16 v[18:21], v[208:211], v[184:187], v[18:21]
	v_mfma_f32_16x16x32_bf16 v[6:9], v[200:203], v[192:195], v[6:9]
	v_mfma_f32_16x16x32_bf16 v[2:5], v[208:211], v[192:195], v[2:5]
	v_mfma_f32_16x16x32_bf16 v[54:57], v[204:207], v[172:175], v[54:57]
	v_mfma_f32_16x16x32_bf16 v[50:53], v[212:215], v[172:175], v[50:53]
	v_mfma_f32_16x16x32_bf16 v[38:41], v[204:207], v[180:183], v[38:41]
	v_mfma_f32_16x16x32_bf16 v[34:37], v[212:215], v[180:183], v[34:37]
	v_mfma_f32_16x16x32_bf16 v[22:25], v[204:207], v[188:191], v[22:25]
	v_mfma_f32_16x16x32_bf16 v[18:21], v[212:215], v[188:191], v[18:21]
	v_mfma_f32_16x16x32_bf16 v[6:9], v[204:207], v[196:199], v[6:9]
	v_mfma_f32_16x16x32_bf16 v[2:5], v[212:215], v[196:199], v[2:5]
	s_setprio 0
	s_add_i32 s50, s50, 2
	s_add_u32 s24, s24, 0x100
	s_addc_u32 s25, s25, 0
	s_add_u32 s48, s48, 0x100
	s_addc_u32 s49, s49, 0
	s_cmp_gt_u32 s50, 13
	s_barrier
	s_cbranch_scc1 .Lgemm_epi0

.Lgemm_epi0:
	v_mul_f32_e32 v152, 0xbfb8aa3b, v126
	v_mul_f32_e32 v153, 0xbfb8aa3b, v127
	v_exp_f32_e32 v152, v152
	v_exp_f32_e32 v153, v153
	v_lshl_or_b32 v156, s47, 7, v148
	v_ashrrev_i32_e32 v157, 31, v156
	v_add_f32_e32 v152, 1.0, v152
	v_add_f32_e32 v153, 1.0, v153
	v_rcp_f32_e32 v154, v152
	v_rcp_f32_e32 v155, v153
	v_mul_f32_e32 v153, 0xbfb8aa3b, v128
	v_exp_f32_e32 v153, v153
	v_lshl_add_u32 v152, s22, 8, v146
	v_pk_mul_f32 v[126:127], v[126:127], v[154:155]
	v_mul_f32_e32 v154, 0xbfb8aa3b, v129
	v_exp_f32_e32 v154, v154
	v_pk_mul_f32 v[118:119], v[126:127], v[118:119]
	v_add_f32_e32 v126, 1.0, v153
	v_mul_f32_e32 v153, 0xbfb8aa3b, v122
	v_add_f32_e32 v127, 1.0, v154
	v_rcp_f32_e32 v126, v126
	v_rcp_f32_e32 v127, v127
	v_exp_f32_e32 v153, v153
	v_mul_f32_e32 v154, 0xbfb8aa3b, v123
	v_exp_f32_e32 v154, v154
	v_pk_mul_f32 v[126:127], v[128:129], v[126:127]
	v_add_f32_e32 v128, 1.0, v153
	v_mul_f32_e32 v153, 0xbfb8aa3b, v124
	v_add_f32_e32 v129, 1.0, v154
	v_exp_f32_e32 v153, v153
	v_mul_f32_e32 v154, 0xbfb8aa3b, v125
	v_exp_f32_e32 v155, v154
	v_rcp_f32_e32 v128, v128
	v_add_f32_e32 v153, 1.0, v153
	v_rcp_f32_e32 v129, v129
	v_rcp_f32_e32 v154, v153
	v_add_f32_e32 v153, 1.0, v155
	v_rcp_f32_e32 v155, v153
	v_pk_mul_f32 v[122:123], v[122:123], v[128:129]
	v_pk_mul_f32 v[120:121], v[126:127], v[120:121]
	v_pk_mul_f32 v[114:115], v[122:123], v[114:115]
	v_pk_mul_f32 v[122:123], v[124:125], v[154:155]
	v_cvt_pk_bf16_f32 v118, v118, v119
	v_pk_mul_f32 v[116:117], v[122:123], v[116:117]
	v_cvt_pk_bf16_f32 v119, v120, v121
	v_cvt_pk_bf16_f32 v121, v116, v117
	v_mul_f32_e32 v116, 0xbfb8aa3b, v110
	v_exp_f32_e32 v116, v116
	v_mul_f32_e32 v117, 0xbfb8aa3b, v111
	v_exp_f32_e32 v117, v117
	v_cvt_pk_bf16_f32 v120, v114, v115
	v_add_f32_e32 v116, 1.0, v116
	v_mov_b64_e32 v[114:115], s[4:5]
	v_rcp_f32_e32 v124, v116
	v_add_f32_e32 v116, 1.0, v117
	v_mad_i64_i32 v[122:123], s[0:1], v152, s46, v[114:115]
	v_rcp_f32_e32 v125, v116
	v_lshlrev_b64 v[116:117], 1, v[156:157]
	v_lshl_add_u64 v[122:123], v[122:123], 0, v[116:117]
	global_store_dwordx4 v[122:123], v[118:121], off
	v_pk_mul_f32 v[110:111], v[110:111], v[124:125]
	s_and_b64 vcc, exec, s[2:3]
	v_mul_f32_e32 v118, 0xbfb8aa3b, v112
	v_mul_f32_e32 v119, 0xbfb8aa3b, v113
	v_exp_f32_e32 v118, v118
	v_exp_f32_e32 v119, v119
	v_pk_mul_f32 v[102:103], v[110:111], v[102:103]
	s_mov_b32 s47, s8
	v_add_f32_e32 v110, 1.0, v118
	v_add_f32_e32 v111, 1.0, v119
	v_mul_f32_e32 v118, 0xbfb8aa3b, v106
	v_mul_f32_e32 v119, 0xbfb8aa3b, v107
	v_rcp_f32_e32 v110, v110
	v_rcp_f32_e32 v111, v111
	v_exp_f32_e32 v118, v118
	v_exp_f32_e32 v119, v119
	s_mov_b32 s22, s12
	v_pk_mul_f32 v[110:111], v[112:113], v[110:111]
	v_add_f32_e32 v112, 1.0, v118
	v_add_f32_e32 v113, 1.0, v119
	v_mul_f32_e32 v118, 0xbfb8aa3b, v108
	v_mul_f32_e32 v119, 0xbfb8aa3b, v109
	v_exp_f32_e32 v118, v118
	v_exp_f32_e32 v119, v119
	v_rcp_f32_e32 v112, v112
	v_rcp_f32_e32 v113, v113
	v_add_f32_e32 v118, 1.0, v118
	v_add_f32_e32 v119, 1.0, v119
	v_rcp_f32_e32 v118, v118
	v_rcp_f32_e32 v119, v119
	v_pk_mul_f32 v[106:107], v[106:107], v[112:113]
	v_pk_mul_f32 v[104:105], v[110:111], v[104:105]
	v_pk_mul_f32 v[106:107], v[106:107], v[98:99]
	v_pk_mul_f32 v[98:99], v[108:109], v[118:119]
	v_or_b32_e32 v110, 16, v152
	v_pk_mul_f32 v[108:109], v[98:99], v[100:101]
	v_mul_f32_e32 v101, 0xbfb8aa3b, v94
	v_cvt_pk_bf16_f32 v98, v102, v103
	v_exp_f32_e32 v102, v101
	v_mul_f32_e32 v101, 0xbfb8aa3b, v95
	v_exp_f32_e32 v103, v101
	v_cvt_pk_bf16_f32 v99, v104, v105
	v_mad_i64_i32 v[104:105], s[0:1], v110, s46, v[114:115]
	v_cvt_pk_bf16_f32 v100, v106, v107
	v_cvt_pk_bf16_f32 v101, v108, v109
	v_add_f32_e32 v102, 1.0, v102
	v_add_f32_e32 v103, 1.0, v103
	v_lshl_add_u64 v[104:105], v[104:105], 0, v[116:117]
	v_rcp_f32_e32 v102, v102
	v_rcp_f32_e32 v103, v103
	global_store_dwordx4 v[104:105], v[98:101], off
	s_mov_b64 s[26:27], s[20:21]
	s_mov_b64 s[24:25], s[14:15]
	v_mul_f32_e32 v98, 0xbfb8aa3b, v96
	v_mul_f32_e32 v99, 0xbfb8aa3b, v97
	v_exp_f32_e32 v98, v98
	v_exp_f32_e32 v99, v99
	v_pk_mul_f32 v[94:95], v[94:95], v[102:103]
	s_nop 0
	v_pk_mul_f32 v[86:87], v[94:95], v[86:87]
	v_add_f32_e32 v94, 1.0, v98
	v_add_f32_e32 v95, 1.0, v99
	v_mul_f32_e32 v98, 0xbfb8aa3b, v90
	v_mul_f32_e32 v99, 0xbfb8aa3b, v91
	v_rcp_f32_e32 v94, v94
	v_rcp_f32_e32 v95, v95
	v_exp_f32_e32 v98, v98
	v_exp_f32_e32 v99, v99
	v_pk_mul_f32 v[94:95], v[96:97], v[94:95]
	v_add_f32_e32 v96, 1.0, v98
	v_add_f32_e32 v97, 1.0, v99
	v_mul_f32_e32 v98, 0xbfb8aa3b, v92
	v_mul_f32_e32 v99, 0xbfb8aa3b, v93
	v_exp_f32_e32 v98, v98
	v_exp_f32_e32 v99, v99
	v_rcp_f32_e32 v96, v96
	v_rcp_f32_e32 v97, v97
	v_add_f32_e32 v98, 1.0, v98
	v_add_f32_e32 v99, 1.0, v99
	v_rcp_f32_e32 v98, v98
	v_rcp_f32_e32 v99, v99
	v_pk_mul_f32 v[90:91], v[90:91], v[96:97]
	v_pk_mul_f32 v[88:89], v[94:95], v[88:89]
	v_pk_mul_f32 v[90:91], v[90:91], v[82:83]
	v_pk_mul_f32 v[82:83], v[92:93], v[98:99]
	v_or_b32_e32 v94, 32, v152
	v_pk_mul_f32 v[92:93], v[82:83], v[84:85]
	v_mul_f32_e32 v85, 0xbfb8aa3b, v78
	v_cvt_pk_bf16_f32 v82, v86, v87
	v_exp_f32_e32 v86, v85
	v_mul_f32_e32 v85, 0xbfb8aa3b, v79
	v_exp_f32_e32 v87, v85
	v_cvt_pk_bf16_f32 v83, v88, v89
	v_mad_i64_i32 v[88:89], s[0:1], v94, s46, v[114:115]
	v_cvt_pk_bf16_f32 v84, v90, v91
	v_cvt_pk_bf16_f32 v85, v92, v93
	v_add_f32_e32 v86, 1.0, v86
	v_add_f32_e32 v87, 1.0, v87
	v_lshl_add_u64 v[88:89], v[88:89], 0, v[116:117]
	v_rcp_f32_e32 v86, v86
	v_rcp_f32_e32 v87, v87
	global_store_dwordx4 v[88:89], v[82:85], off
	v_pk_mul_f32 v[78:79], v[78:79], v[86:87]
	s_nop 0
	v_mul_f32_e32 v82, 0xbfb8aa3b, v80
	v_mul_f32_e32 v83, 0xbfb8aa3b, v81
	v_exp_f32_e32 v82, v82
	v_exp_f32_e32 v83, v83
	v_pk_mul_f32 v[70:71], v[78:79], v[70:71]
	v_add_f32_e32 v78, 1.0, v82
	v_add_f32_e32 v79, 1.0, v83
	v_mul_f32_e32 v82, 0xbfb8aa3b, v74
	v_mul_f32_e32 v83, 0xbfb8aa3b, v75
	v_rcp_f32_e32 v78, v78
	v_rcp_f32_e32 v79, v79
	v_exp_f32_e32 v82, v82
	v_exp_f32_e32 v83, v83
	v_pk_mul_f32 v[78:79], v[80:81], v[78:79]
	v_add_f32_e32 v80, 1.0, v82
	v_add_f32_e32 v81, 1.0, v83
	v_mul_f32_e32 v82, 0xbfb8aa3b, v76
	v_mul_f32_e32 v83, 0xbfb8aa3b, v77
	v_exp_f32_e32 v82, v82
	v_exp_f32_e32 v83, v83
	v_rcp_f32_e32 v80, v80
	v_rcp_f32_e32 v81, v81
	v_add_f32_e32 v82, 1.0, v82
	v_add_f32_e32 v83, 1.0, v83
	v_rcp_f32_e32 v82, v82
	v_rcp_f32_e32 v83, v83
	v_pk_mul_f32 v[74:75], v[74:75], v[80:81]
	v_pk_mul_f32 v[72:73], v[78:79], v[72:73]
	v_pk_mul_f32 v[74:75], v[74:75], v[66:67]
	v_pk_mul_f32 v[66:67], v[76:77], v[82:83]
	v_or_b32_e32 v78, 48, v152
	v_pk_mul_f32 v[76:77], v[66:67], v[68:69]
	v_cvt_pk_bf16_f32 v66, v70, v71
	v_mul_f32_e32 v70, 0xbfb8aa3b, v62
	v_cvt_pk_bf16_f32 v67, v72, v73
	v_exp_f32_e32 v72, v70
	v_mul_f32_e32 v70, 0xbfb8aa3b, v63
	v_exp_f32_e32 v73, v70
	v_mad_i64_i32 v[70:71], s[0:1], v78, s46, v[114:115]
	v_cvt_pk_bf16_f32 v68, v74, v75
	v_cvt_pk_bf16_f32 v69, v76, v77
	v_add_f32_e32 v72, 1.0, v72
	v_add_f32_e32 v73, 1.0, v73
	v_lshl_add_u64 v[70:71], v[70:71], 0, v[116:117]
	v_rcp_f32_e32 v72, v72
	v_rcp_f32_e32 v73, v73
	global_store_dwordx4 v[70:71], v[66:69], off
	v_pk_mul_f32 v[62:63], v[62:63], v[72:73]
	s_nop 0
	v_mul_f32_e32 v66, 0xbfb8aa3b, v64
	v_mul_f32_e32 v67, 0xbfb8aa3b, v65
	v_exp_f32_e32 v66, v66
	v_exp_f32_e32 v67, v67
	v_pk_mul_f32 v[54:55], v[62:63], v[54:55]
	v_add_u32_e32 v68, 0x80, v152
	v_add_f32_e32 v62, 1.0, v66
	v_add_f32_e32 v63, 1.0, v67
	v_mul_f32_e32 v66, 0xbfb8aa3b, v58
	v_mul_f32_e32 v67, 0xbfb8aa3b, v59
	v_rcp_f32_e32 v62, v62
	v_rcp_f32_e32 v63, v63
	v_exp_f32_e32 v66, v66
	v_exp_f32_e32 v67, v67
	v_pk_mul_f32 v[62:63], v[64:65], v[62:63]
	v_add_f32_e32 v64, 1.0, v66
	v_add_f32_e32 v65, 1.0, v67
	v_mul_f32_e32 v66, 0xbfb8aa3b, v60
	v_mul_f32_e32 v67, 0xbfb8aa3b, v61
	v_exp_f32_e32 v66, v66
	v_exp_f32_e32 v67, v67
	v_rcp_f32_e32 v64, v64
	v_rcp_f32_e32 v65, v65
	v_add_f32_e32 v66, 1.0, v66
	v_add_f32_e32 v67, 1.0, v67
	v_rcp_f32_e32 v66, v66
	v_rcp_f32_e32 v67, v67
	v_pk_mul_f32 v[58:59], v[58:59], v[64:65]
	v_pk_mul_f32 v[56:57], v[62:63], v[56:57]
	v_pk_mul_f32 v[58:59], v[58:59], v[50:51]
	v_pk_mul_f32 v[50:51], v[60:61], v[66:67]
	s_nop 0
	v_pk_mul_f32 v[60:61], v[50:51], v[52:53]
	v_mul_f32_e32 v53, 0xbfb8aa3b, v46
	v_cvt_pk_bf16_f32 v50, v54, v55
	v_exp_f32_e32 v54, v53
	v_mul_f32_e32 v53, 0xbfb8aa3b, v47
	v_exp_f32_e32 v55, v53
	v_cvt_pk_bf16_f32 v51, v56, v57
	v_mad_i64_i32 v[56:57], s[0:1], v68, s46, v[114:115]
	v_cvt_pk_bf16_f32 v52, v58, v59
	v_cvt_pk_bf16_f32 v53, v60, v61
	v_add_f32_e32 v54, 1.0, v54
	v_add_f32_e32 v55, 1.0, v55
	v_lshl_add_u64 v[56:57], v[56:57], 0, v[116:117]
	v_rcp_f32_e32 v54, v54
	v_rcp_f32_e32 v55, v55
	global_store_dwordx4 v[56:57], v[50:53], off
	v_pk_mul_f32 v[46:47], v[46:47], v[54:55]
	s_nop 0
	v_mul_f32_e32 v50, 0xbfb8aa3b, v48
	v_mul_f32_e32 v51, 0xbfb8aa3b, v49
	v_exp_f32_e32 v50, v50
	v_exp_f32_e32 v51, v51
	v_pk_mul_f32 v[38:39], v[46:47], v[38:39]
	v_add_f32_e32 v46, 1.0, v50
	v_add_f32_e32 v47, 1.0, v51
	v_mul_f32_e32 v50, 0xbfb8aa3b, v42
	v_mul_f32_e32 v51, 0xbfb8aa3b, v43
	v_rcp_f32_e32 v46, v46
	v_rcp_f32_e32 v47, v47
	v_exp_f32_e32 v50, v50
	v_exp_f32_e32 v51, v51
	v_pk_mul_f32 v[46:47], v[48:49], v[46:47]
	v_add_f32_e32 v48, 1.0, v50
	v_add_f32_e32 v49, 1.0, v51
	v_mul_f32_e32 v50, 0xbfb8aa3b, v44
	v_mul_f32_e32 v51, 0xbfb8aa3b, v45
	v_exp_f32_e32 v50, v50
	v_exp_f32_e32 v51, v51
	v_rcp_f32_e32 v48, v48
	v_rcp_f32_e32 v49, v49
	v_add_f32_e32 v50, 1.0, v50
	v_add_f32_e32 v51, 1.0, v51
	v_rcp_f32_e32 v50, v50
	v_rcp_f32_e32 v51, v51
	v_pk_mul_f32 v[42:43], v[42:43], v[48:49]
	v_pk_mul_f32 v[40:41], v[46:47], v[40:41]
	v_pk_mul_f32 v[42:43], v[42:43], v[34:35]
	v_pk_mul_f32 v[34:35], v[44:45], v[50:51]
	v_add_u32_e32 v46, 0x90, v152
	v_pk_mul_f32 v[44:45], v[34:35], v[36:37]
	v_mul_f32_e32 v37, 0xbfb8aa3b, v30
	v_cvt_pk_bf16_f32 v34, v38, v39
	v_exp_f32_e32 v38, v37
	v_mul_f32_e32 v37, 0xbfb8aa3b, v31
	v_exp_f32_e32 v39, v37
	v_cvt_pk_bf16_f32 v35, v40, v41
	v_mad_i64_i32 v[40:41], s[0:1], v46, s46, v[114:115]
	v_cvt_pk_bf16_f32 v36, v42, v43
	v_cvt_pk_bf16_f32 v37, v44, v45
	v_add_f32_e32 v38, 1.0, v38
	v_add_f32_e32 v39, 1.0, v39
	v_lshl_add_u64 v[40:41], v[40:41], 0, v[116:117]
	v_rcp_f32_e32 v38, v38
	v_rcp_f32_e32 v39, v39
	global_store_dwordx4 v[40:41], v[34:37], off
	v_pk_mul_f32 v[30:31], v[30:31], v[38:39]
	s_nop 0
	v_mul_f32_e32 v34, 0xbfb8aa3b, v32
	v_mul_f32_e32 v35, 0xbfb8aa3b, v33
	v_exp_f32_e32 v34, v34
	v_exp_f32_e32 v35, v35
	v_pk_mul_f32 v[22:23], v[30:31], v[22:23]
	v_add_f32_e32 v30, 1.0, v34
	v_add_f32_e32 v31, 1.0, v35
	v_mul_f32_e32 v34, 0xbfb8aa3b, v26
	v_mul_f32_e32 v35, 0xbfb8aa3b, v27
	v_rcp_f32_e32 v30, v30
	v_rcp_f32_e32 v31, v31
	v_exp_f32_e32 v34, v34
	v_exp_f32_e32 v35, v35
	v_pk_mul_f32 v[30:31], v[32:33], v[30:31]
	v_add_f32_e32 v32, 1.0, v34
	v_add_f32_e32 v33, 1.0, v35
	v_mul_f32_e32 v34, 0xbfb8aa3b, v28
	v_mul_f32_e32 v35, 0xbfb8aa3b, v29
	v_exp_f32_e32 v34, v34
	v_exp_f32_e32 v35, v35
	v_rcp_f32_e32 v32, v32
	v_rcp_f32_e32 v33, v33
	v_add_f32_e32 v34, 1.0, v34
	v_add_f32_e32 v35, 1.0, v35
	v_rcp_f32_e32 v34, v34
	v_rcp_f32_e32 v35, v35
	v_pk_mul_f32 v[26:27], v[26:27], v[32:33]
	v_pk_mul_f32 v[24:25], v[30:31], v[24:25]
	v_pk_mul_f32 v[26:27], v[26:27], v[18:19]
	v_pk_mul_f32 v[18:19], v[28:29], v[34:35]
	v_add_u32_e32 v30, 0xa0, v152
	v_pk_mul_f32 v[28:29], v[18:19], v[20:21]
	v_mul_f32_e32 v21, 0xbfb8aa3b, v14
	v_cvt_pk_bf16_f32 v18, v22, v23
	v_exp_f32_e32 v22, v21
	v_mul_f32_e32 v21, 0xbfb8aa3b, v15
	v_exp_f32_e32 v23, v21
	v_cvt_pk_bf16_f32 v19, v24, v25
	v_mad_i64_i32 v[24:25], s[0:1], v30, s46, v[114:115]
	v_cvt_pk_bf16_f32 v20, v26, v27
	v_cvt_pk_bf16_f32 v21, v28, v29
	v_add_f32_e32 v22, 1.0, v22
	v_add_f32_e32 v23, 1.0, v23
	v_lshl_add_u64 v[24:25], v[24:25], 0, v[116:117]
	v_rcp_f32_e32 v22, v22
	v_rcp_f32_e32 v23, v23
	global_store_dwordx4 v[24:25], v[18:21], off
	v_pk_mul_f32 v[14:15], v[14:15], v[22:23]
	s_nop 0
	v_mul_f32_e32 v18, 0xbfb8aa3b, v16
	v_mul_f32_e32 v19, 0xbfb8aa3b, v17
	v_exp_f32_e32 v18, v18
	v_exp_f32_e32 v19, v19
	v_pk_mul_f32 v[6:7], v[14:15], v[6:7]
	v_add_f32_e32 v14, 1.0, v18
	v_add_f32_e32 v15, 1.0, v19
	v_mul_f32_e32 v18, 0xbfb8aa3b, v10
	v_mul_f32_e32 v19, 0xbfb8aa3b, v11
	v_rcp_f32_e32 v14, v14
	v_rcp_f32_e32 v15, v15
	v_exp_f32_e32 v18, v18
	v_exp_f32_e32 v19, v19
	v_pk_mul_f32 v[14:15], v[16:17], v[14:15]
	v_add_f32_e32 v16, 1.0, v18
	v_add_f32_e32 v17, 1.0, v19
	v_mul_f32_e32 v18, 0xbfb8aa3b, v12
	v_mul_f32_e32 v19, 0xbfb8aa3b, v13
	v_exp_f32_e32 v18, v18
	v_exp_f32_e32 v19, v19
	v_rcp_f32_e32 v16, v16
	v_rcp_f32_e32 v17, v17
	v_add_f32_e32 v18, 1.0, v18
	v_add_f32_e32 v19, 1.0, v19
	v_rcp_f32_e32 v18, v18
	v_rcp_f32_e32 v19, v19
	v_pk_mul_f32 v[10:11], v[10:11], v[16:17]
	v_pk_mul_f32 v[8:9], v[14:15], v[8:9]
	v_pk_mul_f32 v[10:11], v[10:11], v[2:3]
	v_pk_mul_f32 v[2:3], v[12:13], v[18:19]
	v_add_u32_e32 v14, 0xb0, v152
	v_pk_mul_f32 v[12:13], v[2:3], v[4:5]
	v_cvt_pk_bf16_f32 v2, v6, v7
	v_mad_i64_i32 v[6:7], s[0:1], v14, s46, v[114:115]
	v_cvt_pk_bf16_f32 v3, v8, v9
	v_cvt_pk_bf16_f32 v4, v10, v11
	v_cvt_pk_bf16_f32 v5, v12, v13
	v_lshl_add_u64 v[6:7], v[6:7], 0, v[116:117]
	global_store_dwordx4 v[6:7], v[2:5], off
	s_cbranch_vccz .LBB0_72
	s_waitcnt vmcnt(0)
	s_cmpk_gt_u32 s30, 0xff
	s_cbranch_scc1 .LBB0_79
	s_barrier

.LBB0_118:
	s_add_u32 s22, s22, 0xb0080
	s_addc_u32 s23, s23, 0
	s_add_u32 s0, s24, 0x100
	s_addc_u32 s1, s25, 0
	s_mov_b32 s50, -2
	s_waitcnt lgkmcnt(0)
	ds_read_b128 v[130:133], v209
	ds_read_b128 v[134:137], v209 offset:1024
	ds_read_b128 v[138:141], v209 offset:2048
	ds_read_b128 v[142:145], v209 offset:3072
	s_add_u32 s24, s22, 0xfff50080
	s_addc_u32 s25, s23, -1
	s_cmp_eq_u32 s50, 40
	s_cselect_b32 s27, s7, s25
	s_cselect_b32 s26, s6, s24
	s_cselect_b32 s25, s9, s1
	s_cselect_b32 s24, s8, s0
	v_lshl_add_u64 v[194:195], s[22:23], 0, v[186:187]
	s_add_i32 m0, s35, 0xc000
	ds_read_b128 v[146:149], v210
	ds_read_b128 v[150:153], v210 offset:1024
	ds_read_b128 v[154:157], v210 offset:2048
	ds_read_b128 v[158:161], v210 offset:3072
	ds_read_b128 v[162:165], v210 offset:4096
	ds_read_b128 v[166:169], v210 offset:5120
	ds_read_b128 v[170:173], v210 offset:6144
	ds_read_b128 v[174:177], v210 offset:7168
	global_load_lds_dwordx4 v[194:195], off
	v_lshl_add_u64 v[194:195], s[22:23], 0, v[188:189]
	s_add_i32 m0, s35, 0xe000
	s_nop 0
	global_load_lds_dwordx4 v[194:195], off
	s_waitcnt lgkmcnt(8)
	s_barrier
	s_waitcnt lgkmcnt(0)
	s_setprio 1
	s_waitcnt lgkmcnt(0)
	v_mfma_f32_16x16x32_bf16 v[126:129], v[130:133], v[146:149], 0
	v_mfma_f32_16x16x32_bf16 v[122:125], v[138:141], v[146:149], 0
	v_mfma_f32_16x16x32_bf16 v[110:113], v[130:133], v[154:157], 0
	v_mfma_f32_16x16x32_bf16 v[106:109], v[138:141], v[154:157], 0
	v_mfma_f32_16x16x32_bf16 v[94:97], v[130:133], v[162:165], 0
	v_mfma_f32_16x16x32_bf16 v[90:93], v[138:141], v[162:165], 0
	v_mfma_f32_16x16x32_bf16 v[78:81], v[130:133], v[170:173], 0
	v_mfma_f32_16x16x32_bf16 v[74:77], v[138:141], v[170:173], 0
	v_mfma_f32_16x16x32_bf16 v[126:129], v[134:137], v[150:153], v[126:129]
	v_mfma_f32_16x16x32_bf16 v[122:125], v[142:145], v[150:153], v[122:125]
	v_mfma_f32_16x16x32_bf16 v[110:113], v[134:137], v[158:161], v[110:113]
	v_mfma_f32_16x16x32_bf16 v[106:109], v[142:145], v[158:161], v[106:109]
	v_mfma_f32_16x16x32_bf16 v[94:97], v[134:137], v[166:169], v[94:97]
	v_mfma_f32_16x16x32_bf16 v[90:93], v[142:145], v[166:169], v[90:93]
	v_mfma_f32_16x16x32_bf16 v[78:81], v[134:137], v[174:177], v[78:81]
	v_mfma_f32_16x16x32_bf16 v[74:77], v[142:145], v[174:177], v[74:77]
	s_setprio 0
	s_barrier
	s_add_i32 s51, s44, s34
	v_lshl_add_u64 v[218:219], s[24:25], 0, v[180:181]
	s_mov_b32 m0, s51
	ds_read_b128 v[194:197], v211
	ds_read_b128 v[198:201], v211 offset:1024
	ds_read_b128 v[202:205], v211 offset:2048
	ds_read_b128 v[214:217], v211 offset:3072
	global_load_lds_dwordx4 v[218:219], off
	v_lshl_add_u64 v[220:221], s[24:25], 0, v[184:185]
	s_add_i32 m0, s51, 0x2000
	s_nop 0
	global_load_lds_dwordx4 v[220:221], off
	s_barrier
	s_waitcnt lgkmcnt(0)
	s_setprio 1
	s_waitcnt lgkmcnt(0)
	v_mfma_f32_16x16x32_bf16 v[118:121], v[194:197], v[146:149], 0
	v_mfma_f32_16x16x32_bf16 v[114:117], v[202:205], v[146:149], 0
	v_mfma_f32_16x16x32_bf16 v[102:105], v[194:197], v[154:157], 0
	v_mfma_f32_16x16x32_bf16 v[98:101], v[202:205], v[154:157], 0
	v_mfma_f32_16x16x32_bf16 v[86:89], v[194:197], v[162:165], 0
	v_mfma_f32_16x16x32_bf16 v[82:85], v[202:205], v[162:165], 0
	v_mfma_f32_16x16x32_bf16 v[70:73], v[194:197], v[170:173], 0
	v_mfma_f32_16x16x32_bf16 v[66:69], v[202:205], v[170:173], 0
	v_mfma_f32_16x16x32_bf16 v[118:121], v[198:201], v[150:153], v[118:121]
	v_mfma_f32_16x16x32_bf16 v[114:117], v[214:217], v[150:153], v[114:117]
	v_mfma_f32_16x16x32_bf16 v[102:105], v[198:201], v[158:161], v[102:105]
	v_mfma_f32_16x16x32_bf16 v[98:101], v[214:217], v[158:161], v[98:101]
	v_mfma_f32_16x16x32_bf16 v[86:89], v[198:201], v[166:169], v[86:89]
	v_mfma_f32_16x16x32_bf16 v[82:85], v[214:217], v[166:169], v[82:85]
	v_mfma_f32_16x16x32_bf16 v[70:73], v[198:201], v[174:177], v[70:73]
	v_mfma_f32_16x16x32_bf16 v[66:69], v[214:217], v[174:177], v[66:69]
	s_setprio 0
	s_mov_b32 m0, s35
	v_lshl_add_u64 v[222:223], s[26:27], 0, v[178:179]
	s_barrier
	ds_read_b128 v[146:149], v210 offset:16384
	ds_read_b128 v[150:153], v210 offset:17408
	ds_read_b128 v[154:157], v210 offset:18432
	ds_read_b128 v[158:161], v210 offset:19456
	ds_read_b128 v[162:165], v210 offset:20480
	ds_read_b128 v[166:169], v210 offset:21504
	ds_read_b128 v[170:173], v210 offset:22528
	ds_read_b128 v[174:177], v210 offset:23552
	global_load_lds_dwordx4 v[222:223], off
	v_lshl_add_u64 v[224:225], s[26:27], 0, v[182:183]
	s_mov_b32 m0, s36
	s_nop 0
	global_load_lds_dwordx4 v[224:225], off
	s_barrier
	s_waitcnt lgkmcnt(0)
	s_setprio 1
	s_waitcnt lgkmcnt(0)
	v_mfma_f32_16x16x32_bf16 v[62:65], v[130:133], v[146:149], 0
	v_mfma_f32_16x16x32_bf16 v[58:61], v[138:141], v[146:149], 0
	v_mfma_f32_16x16x32_bf16 v[46:49], v[130:133], v[154:157], 0
	v_mfma_f32_16x16x32_bf16 v[42:45], v[138:141], v[154:157], 0
	v_mfma_f32_16x16x32_bf16 v[30:33], v[130:133], v[162:165], 0
	v_mfma_f32_16x16x32_bf16 v[26:29], v[138:141], v[162:165], 0
	v_mfma_f32_16x16x32_bf16 v[14:17], v[130:133], v[170:173], 0
	v_mfma_f32_16x16x32_bf16 v[10:13], v[138:141], v[170:173], 0
	v_mfma_f32_16x16x32_bf16 v[62:65], v[134:137], v[150:153], v[62:65]
	v_mfma_f32_16x16x32_bf16 v[58:61], v[142:145], v[150:153], v[58:61]
	v_mfma_f32_16x16x32_bf16 v[46:49], v[134:137], v[158:161], v[46:49]
	v_mfma_f32_16x16x32_bf16 v[42:45], v[142:145], v[158:161], v[42:45]
	v_mfma_f32_16x16x32_bf16 v[30:33], v[134:137], v[166:169], v[30:33]
	v_mfma_f32_16x16x32_bf16 v[26:29], v[142:145], v[166:169], v[26:29]
	v_mfma_f32_16x16x32_bf16 v[14:17], v[134:137], v[174:177], v[14:17]
	v_mfma_f32_16x16x32_bf16 v[10:13], v[142:145], v[174:177], v[10:13]
	s_setprio 0
	s_barrier
	s_add_u32 s52, s24, 0xb0000
	s_addc_u32 s53, s25, 0
	s_add_i32 s51, s45, s34
	v_lshl_add_u64 v[130:131], s[52:53], 0, v[180:181]
	s_mov_b32 m0, s51
	s_nop 0
	global_load_lds_dwordx4 v[130:131], off
	v_lshl_add_u64 v[130:131], s[52:53], 0, v[184:185]
	s_add_i32 m0, s51, 0x2000
	s_nop 0
	global_load_lds_dwordx4 v[130:131], off
	s_waitcnt vmcnt(6)
	s_barrier
	s_setprio 1
	v_mfma_f32_16x16x32_bf16 v[54:57], v[194:197], v[146:149], 0
	v_mfma_f32_16x16x32_bf16 v[50:53], v[202:205], v[146:149], 0
	v_mfma_f32_16x16x32_bf16 v[38:41], v[194:197], v[154:157], 0
	v_mfma_f32_16x16x32_bf16 v[34:37], v[202:205], v[154:157], 0
	v_mfma_f32_16x16x32_bf16 v[22:25], v[194:197], v[162:165], 0
	v_mfma_f32_16x16x32_bf16 v[18:21], v[202:205], v[162:165], 0
	v_mfma_f32_16x16x32_bf16 v[6:9], v[194:197], v[170:173], 0
	v_mfma_f32_16x16x32_bf16 v[2:5], v[202:205], v[170:173], 0
	v_mfma_f32_16x16x32_bf16 v[54:57], v[198:201], v[150:153], v[54:57]
	v_mfma_f32_16x16x32_bf16 v[50:53], v[214:217], v[150:153], v[50:53]
	v_mfma_f32_16x16x32_bf16 v[38:41], v[198:201], v[158:161], v[38:41]
	v_mfma_f32_16x16x32_bf16 v[34:37], v[214:217], v[158:161], v[34:37]
	v_mfma_f32_16x16x32_bf16 v[22:25], v[198:201], v[166:169], v[22:25]
	v_mfma_f32_16x16x32_bf16 v[18:21], v[214:217], v[166:169], v[18:21]
	v_mfma_f32_16x16x32_bf16 v[6:9], v[198:201], v[174:177], v[6:9]
	v_mfma_f32_16x16x32_bf16 v[2:5], v[214:217], v[174:177], v[2:5]
	s_setprio 0
	s_add_i32 s51, 0, 0x18000
	v_add_u32_e32 v142, s51, v207
	s_barrier
	ds_read_b128 v[130:133], v142
	ds_read_b128 v[134:137], v142 offset:1024
	ds_read_b128 v[138:141], v142 offset:2048
	ds_read_b128 v[142:145], v142 offset:3072
	s_add_u32 s26, s26, 0xb0000
	s_addc_u32 s27, s27, 0
	s_mov_b32 m0, s37
	v_lshl_add_u64 v[194:195], s[26:27], 0, v[178:179]
	ds_read_b128 v[146:149], v210 offset:32768
	ds_read_b128 v[150:153], v210 offset:33792
	ds_read_b128 v[154:157], v210 offset:34816
	ds_read_b128 v[158:161], v210 offset:35840
	ds_read_b128 v[162:165], v210 offset:36864
	ds_read_b128 v[166:169], v210 offset:37888
	ds_read_b128 v[170:173], v210 offset:38912
	ds_read_b128 v[174:177], v210 offset:39936
	global_load_lds_dwordx4 v[194:195], off
	v_lshl_add_u64 v[194:195], s[26:27], 0, v[182:183]
	s_mov_b32 m0, s38
	s_nop 0
	global_load_lds_dwordx4 v[194:195], off
	s_waitcnt lgkmcnt(8)
	s_barrier
	s_waitcnt lgkmcnt(0)
	s_setprio 1
	s_waitcnt lgkmcnt(0)
	v_mfma_f32_16x16x32_bf16 v[126:129], v[130:133], v[146:149], v[126:129]
	v_mfma_f32_16x16x32_bf16 v[122:125], v[138:141], v[146:149], v[122:125]
	v_mfma_f32_16x16x32_bf16 v[110:113], v[130:133], v[154:157], v[110:113]
	v_mfma_f32_16x16x32_bf16 v[106:109], v[138:141], v[154:157], v[106:109]
	v_mfma_f32_16x16x32_bf16 v[94:97], v[130:133], v[162:165], v[94:97]
	v_mfma_f32_16x16x32_bf16 v[90:93], v[138:141], v[162:165], v[90:93]
	v_mfma_f32_16x16x32_bf16 v[78:81], v[130:133], v[170:173], v[78:81]
	v_mfma_f32_16x16x32_bf16 v[74:77], v[138:141], v[170:173], v[74:77]
	v_mfma_f32_16x16x32_bf16 v[126:129], v[134:137], v[150:153], v[126:129]
	v_mfma_f32_16x16x32_bf16 v[122:125], v[142:145], v[150:153], v[122:125]
	v_mfma_f32_16x16x32_bf16 v[110:113], v[134:137], v[158:161], v[110:113]
	v_mfma_f32_16x16x32_bf16 v[106:109], v[142:145], v[158:161], v[106:109]
	v_mfma_f32_16x16x32_bf16 v[94:97], v[134:137], v[166:169], v[94:97]
	v_mfma_f32_16x16x32_bf16 v[90:93], v[142:145], v[166:169], v[90:93]
	v_mfma_f32_16x16x32_bf16 v[78:81], v[134:137], v[174:177], v[78:81]
	v_mfma_f32_16x16x32_bf16 v[74:77], v[142:145], v[174:177], v[74:77]
	s_setprio 0
	s_barrier
	s_add_i32 s26, 0, 0x1c000
	s_add_i32 s27, s51, s34
	v_add_u32_e32 v213, s26, v207
	v_lshl_add_u64 v[218:219], v[218:219], 0, s[20:21]
	s_mov_b32 m0, s27
	ds_read_b128 v[194:197], v213
	ds_read_b128 v[198:201], v213 offset:1024
	ds_read_b128 v[202:205], v213 offset:2048
	ds_read_b128 v[214:217], v213 offset:3072
	global_load_lds_dwordx4 v[218:219], off
	v_lshl_add_u64 v[218:219], v[220:221], 0, s[20:21]
	s_add_i32 m0, s27, 0x2000
	s_nop 0
	global_load_lds_dwordx4 v[218:219], off
	s_barrier
	s_waitcnt lgkmcnt(0)
	s_setprio 1
	s_waitcnt lgkmcnt(0)
	v_mfma_f32_16x16x32_bf16 v[118:121], v[194:197], v[146:149], v[118:121]
	v_mfma_f32_16x16x32_bf16 v[114:117], v[202:205], v[146:149], v[114:117]
	v_mfma_f32_16x16x32_bf16 v[102:105], v[194:197], v[154:157], v[102:105]
	v_mfma_f32_16x16x32_bf16 v[98:101], v[202:205], v[154:157], v[98:101]
	v_mfma_f32_16x16x32_bf16 v[86:89], v[194:197], v[162:165], v[86:89]
	v_mfma_f32_16x16x32_bf16 v[82:85], v[202:205], v[162:165], v[82:85]
	v_mfma_f32_16x16x32_bf16 v[70:73], v[194:197], v[170:173], v[70:73]
	v_mfma_f32_16x16x32_bf16 v[66:69], v[202:205], v[170:173], v[66:69]
	v_mfma_f32_16x16x32_bf16 v[118:121], v[198:201], v[150:153], v[118:121]
	v_mfma_f32_16x16x32_bf16 v[114:117], v[214:217], v[150:153], v[114:117]
	v_mfma_f32_16x16x32_bf16 v[102:105], v[198:201], v[158:161], v[102:105]
	v_mfma_f32_16x16x32_bf16 v[98:101], v[214:217], v[158:161], v[98:101]
	v_mfma_f32_16x16x32_bf16 v[86:89], v[198:201], v[166:169], v[86:89]
	v_mfma_f32_16x16x32_bf16 v[82:85], v[214:217], v[166:169], v[82:85]
	v_mfma_f32_16x16x32_bf16 v[70:73], v[198:201], v[174:177], v[70:73]
	v_mfma_f32_16x16x32_bf16 v[66:69], v[214:217], v[174:177], v[66:69]
	s_setprio 0
	s_mov_b32 m0, s40
	v_lshl_add_u64 v[218:219], v[222:223], 0, s[20:21]
	s_barrier
	ds_read_b128 v[146:149], v210 offset:49152
	ds_read_b128 v[150:153], v210 offset:50176
	ds_read_b128 v[154:157], v210 offset:51200
	ds_read_b128 v[158:161], v210 offset:52224
	ds_read_b128 v[162:165], v210 offset:53248
	ds_read_b128 v[166:169], v210 offset:54272
	ds_read_b128 v[170:173], v210 offset:55296
	ds_read_b128 v[174:177], v210 offset:56320
	global_load_lds_dwordx4 v[218:219], off
	v_lshl_add_u64 v[218:219], v[224:225], 0, s[20:21]
	s_mov_b32 m0, s41
	s_nop 0
	global_load_lds_dwordx4 v[218:219], off
	s_barrier
	s_waitcnt lgkmcnt(0)
	s_setprio 1
	s_waitcnt lgkmcnt(0)
	v_mfma_f32_16x16x32_bf16 v[62:65], v[130:133], v[146:149], v[62:65]
	v_mfma_f32_16x16x32_bf16 v[58:61], v[138:141], v[146:149], v[58:61]
	v_mfma_f32_16x16x32_bf16 v[46:49], v[130:133], v[154:157], v[46:49]
	v_mfma_f32_16x16x32_bf16 v[42:45], v[138:141], v[154:157], v[42:45]
	v_mfma_f32_16x16x32_bf16 v[30:33], v[130:133], v[162:165], v[30:33]
	v_mfma_f32_16x16x32_bf16 v[26:29], v[138:141], v[162:165], v[26:29]
	v_mfma_f32_16x16x32_bf16 v[14:17], v[130:133], v[170:173], v[14:17]
	v_mfma_f32_16x16x32_bf16 v[10:13], v[138:141], v[170:173], v[10:13]
	v_mfma_f32_16x16x32_bf16 v[62:65], v[134:137], v[150:153], v[62:65]
	v_mfma_f32_16x16x32_bf16 v[58:61], v[142:145], v[150:153], v[58:61]
	v_mfma_f32_16x16x32_bf16 v[46:49], v[134:137], v[158:161], v[46:49]
	v_mfma_f32_16x16x32_bf16 v[42:45], v[142:145], v[158:161], v[42:45]
	v_mfma_f32_16x16x32_bf16 v[30:33], v[134:137], v[166:169], v[30:33]
	v_mfma_f32_16x16x32_bf16 v[26:29], v[142:145], v[166:169], v[26:29]
	v_mfma_f32_16x16x32_bf16 v[14:17], v[134:137], v[174:177], v[14:17]
	v_mfma_f32_16x16x32_bf16 v[10:13], v[142:145], v[174:177], v[10:13]
	s_setprio 0
	s_barrier
	s_add_u32 s24, s24, 0xb0080
	s_addc_u32 s25, s25, 0
	s_add_i32 s26, s26, s34
	v_lshl_add_u64 v[130:131], s[24:25], 0, v[180:181]
	s_mov_b32 m0, s26
	s_nop 0
	global_load_lds_dwordx4 v[130:131], off
	v_lshl_add_u64 v[130:131], s[24:25], 0, v[184:185]
	s_add_i32 m0, s26, 0x2000
	s_nop 0
	global_load_lds_dwordx4 v[130:131], off
	s_waitcnt vmcnt(6)
	s_barrier
	s_setprio 1
	v_mfma_f32_16x16x32_bf16 v[54:57], v[194:197], v[146:149], v[54:57]
	v_mfma_f32_16x16x32_bf16 v[50:53], v[202:205], v[146:149], v[50:53]
	v_mfma_f32_16x16x32_bf16 v[38:41], v[194:197], v[154:157], v[38:41]
	v_mfma_f32_16x16x32_bf16 v[34:37], v[202:205], v[154:157], v[34:37]
	v_mfma_f32_16x16x32_bf16 v[22:25], v[194:197], v[162:165], v[22:25]
	v_mfma_f32_16x16x32_bf16 v[18:21], v[202:205], v[162:165], v[18:21]
	v_mfma_f32_16x16x32_bf16 v[6:9], v[194:197], v[170:173], v[6:9]
	v_mfma_f32_16x16x32_bf16 v[2:5], v[202:205], v[170:173], v[2:5]
	v_mfma_f32_16x16x32_bf16 v[54:57], v[198:201], v[150:153], v[54:57]
	v_mfma_f32_16x16x32_bf16 v[50:53], v[214:217], v[150:153], v[50:53]
	v_mfma_f32_16x16x32_bf16 v[38:41], v[198:201], v[158:161], v[38:41]
	v_mfma_f32_16x16x32_bf16 v[34:37], v[214:217], v[158:161], v[34:37]
	v_mfma_f32_16x16x32_bf16 v[22:25], v[198:201], v[166:169], v[22:25]
	v_mfma_f32_16x16x32_bf16 v[18:21], v[214:217], v[166:169], v[18:21]
	v_mfma_f32_16x16x32_bf16 v[6:9], v[198:201], v[174:177], v[6:9]
	v_mfma_f32_16x16x32_bf16 v[2:5], v[214:217], v[174:177], v[2:5]
	s_setprio 0
	s_add_i32 s50, s50, 2
	s_add_u32 s22, s22, 0x100
	s_addc_u32 s23, s23, 0
	s_add_u32 s0, s0, 0x100
	s_addc_u32 s1, s1, 0
	s_cmp_gt_u32 s50, 41
	s_barrier
	s_cbranch_scc1 .Lgemm_epi1

.Lgemm_epi1:
	v_lshl_add_u32 v198, s49, 8, v206
	v_lshl_or_b32 v194, s48, 8, v208
	v_ashrrev_i32_e32 v195, 31, v194
	v_ashrrev_i32_e32 v199, 31, v198
	v_lshl_add_u64 v[196:197], v[194:195], 2, s[12:13]
	v_lshlrev_b64 v[130:131], 12, v[198:199]
	v_lshl_add_u64 v[130:131], v[196:197], 0, v[130:131]
	global_load_dwordx4 v[214:217], v[130:131], off
	global_load_dwordx4 v[218:221], v[130:131], off offset:16
	global_load_dwordx4 v[222:225], v[130:131], off offset:512
	global_load_dwordx4 v[226:229], v[130:131], off offset:528
	v_or_b32_e32 v204, 16, v198
	v_or_b32_e32 v202, 32, v198
	v_or_b32_e32 v200, 48, v198
	v_ashrrev_i32_e32 v205, 31, v204
	v_ashrrev_i32_e32 v203, 31, v202
	v_ashrrev_i32_e32 v201, 31, v200
	v_lshlrev_b64 v[130:131], 12, v[204:205]
	v_lshlrev_b64 v[132:133], 12, v[202:203]
	v_lshlrev_b64 v[134:135], 12, v[200:201]
	v_lshl_add_u64 v[130:131], v[196:197], 0, v[130:131]
	v_lshl_add_u64 v[132:133], v[196:197], 0, v[132:133]
	v_lshl_add_u64 v[134:135], v[196:197], 0, v[134:135]
	global_load_dwordx4 v[170:173], v[130:131], off offset:16
	global_load_dwordx4 v[174:177], v[130:131], off
	global_load_dwordx4 v[162:165], v[130:131], off offset:528
	global_load_dwordx4 v[166:169], v[130:131], off offset:512
	global_load_dwordx4 v[154:157], v[132:133], off offset:16
	global_load_dwordx4 v[158:161], v[132:133], off
	global_load_dwordx4 v[146:149], v[132:133], off offset:528
	global_load_dwordx4 v[150:153], v[132:133], off offset:512
	global_load_dwordx4 v[138:141], v[134:135], off offset:16
	global_load_dwordx4 v[142:145], v[134:135], off
	s_nop 0
	global_load_dwordx4 v[130:133], v[134:135], off offset:528
	s_nop 0
	global_load_dwordx4 v[134:137], v[134:135], off offset:512
	v_and_b32_e32 v230, 64, v212
	v_xor_b32_e32 v213, 16, v212
	v_add_u32_e32 v233, 64, v230
	v_cmp_lt_i32_e32 vcc, v213, v233
	v_xor_b32_e32 v232, 32, v212
	v_lshlrev_b64 v[230:231], 11, v[198:199]
	v_cndmask_b32_e32 v213, v212, v213, vcc
	v_lshlrev_b32_e32 v213, 2, v213
	v_cmp_lt_i32_e32 vcc, v232, v233
	v_lshl_add_u64 v[230:231], s[68:69], 0, v[230:231]
	v_lshl_add_u64 v[230:231], v[194:195], 1, v[230:231]
	v_cndmask_b32_e32 v232, v212, v232, vcc
	s_waitcnt vmcnt(0)
	v_pk_fma_f32 v[126:127], v[126:127], 0.5, v[214:215] op_sel_hi:[1,0,1]
	v_pk_fma_f32 v[128:129], v[128:129], 0.5, v[216:217] op_sel_hi:[1,0,1]
	v_pk_fma_f32 v[118:119], v[118:119], 0.5, v[222:223] op_sel_hi:[1,0,1]
	v_pk_fma_f32 v[214:215], v[116:117], 0.5, v[228:229] op_sel_hi:[1,0,1]
	v_mul_f32_e32 v116, v127, v127
	v_mul_f32_e32 v117, v119, v119
	v_pk_fma_f32 v[120:121], v[120:121], 0.5, v[224:225] op_sel_hi:[1,0,1]
	v_fmac_f32_e32 v116, v126, v126
	v_fmac_f32_e32 v117, v118, v118
	v_fmac_f32_e32 v116, v128, v128
	v_fmac_f32_e32 v117, v120, v120
	v_pk_fma_f32 v[122:123], v[122:123], 0.5, v[218:219] op_sel_hi:[1,0,1]
	v_pk_fma_f32 v[216:217], v[114:115], 0.5, v[226:227] op_sel_hi:[1,0,1]
	v_fmac_f32_e32 v116, v129, v129
	v_fmac_f32_e32 v117, v121, v121
	v_fmac_f32_e32 v116, v122, v122
	v_fmac_f32_e32 v117, v216, v216
	v_pk_fma_f32 v[124:125], v[124:125], 0.5, v[220:221] op_sel_hi:[1,0,1]
	v_fmac_f32_e32 v116, v123, v123
	v_fmac_f32_e32 v117, v217, v217
	v_fmac_f32_e32 v116, v124, v124
	v_fmac_f32_e32 v117, v214, v214
	v_fmac_f32_e32 v116, v125, v125
	v_fmac_f32_e32 v117, v215, v215
	v_cvt_pk_bf16_f32 v114, v126, v127
	v_add_f32_e32 v126, v116, v117
	ds_bpermute_b32 v127, v213, v126
	v_cvt_pk_bf16_f32 v115, v128, v129
	v_cvt_pk_bf16_f32 v116, v122, v123
	v_cvt_pk_bf16_f32 v117, v124, v125
	global_store_dwordx4 v[230:231], v[114:117], off
	v_lshlrev_b32_e32 v122, 2, v232
	v_cvt_pk_bf16_f32 v118, v118, v119
	s_waitcnt lgkmcnt(0)
	v_add_f32_e32 v114, v126, v127
	ds_bpermute_b32 v115, v122, v114
	v_cvt_pk_bf16_f32 v119, v120, v121
	v_cvt_pk_bf16_f32 v120, v216, v217
	v_cvt_pk_bf16_f32 v121, v214, v215
	global_store_dwordx4 v[230:231], v[118:121], off offset:256
	s_and_saveexec_b64 s[22:23], s[2:3]
	s_cbranch_execz .LBB0_122
	s_waitcnt lgkmcnt(0)
	v_add_f32_e32 v116, v114, v115
	v_lshl_add_u64 v[114:115], v[198:199], 2, s[14:15]
	global_atomic_add_f32 v[114:115], v116, off

.LBB0_205:
	s_ashr_i32 s27, s26, 31
	s_lshl_b64 s[0:1], s[26:27], 19
	v_cmp_lt_i64_e32 vcc, s[28:29], v[144:145]
	s_add_u32 s28, s68, s0
	s_addc_u32 s29, s69, s1
	s_and_b64 s[0:1], vcc, exec
	s_cselect_b32 s0, s29, s37
	s_cselect_b32 s1, s28, s36
	s_ashr_i32 s25, s24, 31
	s_lshl_b64 s[30:31], s[24:25], 19
	s_add_u32 s30, s44, s30
	s_addc_u32 s31, s45, s31
	s_and_b64 s[40:41], vcc, exec
	s_cselect_b32 s25, s31, s39
	s_cselect_b32 s27, s30, s38
	s_add_u32 s36, s36, 0x40080
	s_addc_u32 s37, s37, 0
	s_add_u32 s35, s38, 0x100
	s_addc_u32 s59, s39, 0
	s_mov_b32 s60, -2
	ds_read_b128 v[148:151], v164
	ds_read_b128 v[152:155], v164 offset:1024
	ds_read_b128 v[156:159], v164 offset:2048
	ds_read_b128 v[168:171], v164 offset:3072
	s_add_u32 s38, s36, 0xfffc0080
	s_addc_u32 s39, s37, -1
	s_cmp_eq_u32 s60, 12
	s_cselect_b32 s41, s0, s39
	s_cselect_b32 s40, s1, s38
	s_cselect_b32 s39, s25, s59
	s_cselect_b32 s38, s27, s35
	v_lshl_add_u64 v[204:205], s[36:37], 0, v[140:141]
	s_add_i32 m0, s46, 0xc000
	ds_read_b128 v[172:175], v165
	ds_read_b128 v[176:179], v165 offset:1024
	ds_read_b128 v[180:183], v165 offset:2048
	ds_read_b128 v[184:187], v165 offset:3072
	ds_read_b128 v[188:191], v165 offset:4096
	ds_read_b128 v[192:195], v165 offset:5120
	ds_read_b128 v[196:199], v165 offset:6144
	ds_read_b128 v[200:203], v165 offset:7168
	global_load_lds_dwordx4 v[204:205], off
	v_lshl_add_u64 v[204:205], s[36:37], 0, v[142:143]
	s_add_i32 m0, s46, 0xe000
	s_nop 0
	global_load_lds_dwordx4 v[204:205], off
	s_waitcnt lgkmcnt(8)
	s_barrier
	s_waitcnt lgkmcnt(0)
	s_setprio 1
	s_waitcnt lgkmcnt(0)
	v_mfma_f32_16x16x32_bf16 v[126:129], v[148:151], v[172:175], 0
	v_mfma_f32_16x16x32_bf16 v[122:125], v[156:159], v[172:175], 0
	v_mfma_f32_16x16x32_bf16 v[110:113], v[148:151], v[180:183], 0
	v_mfma_f32_16x16x32_bf16 v[106:109], v[156:159], v[180:183], 0
	v_mfma_f32_16x16x32_bf16 v[94:97], v[148:151], v[188:191], 0
	v_mfma_f32_16x16x32_bf16 v[90:93], v[156:159], v[188:191], 0
	v_mfma_f32_16x16x32_bf16 v[78:81], v[148:151], v[196:199], 0
	v_mfma_f32_16x16x32_bf16 v[74:77], v[156:159], v[196:199], 0
	v_mfma_f32_16x16x32_bf16 v[126:129], v[152:155], v[176:179], v[126:129]
	v_mfma_f32_16x16x32_bf16 v[122:125], v[168:171], v[176:179], v[122:125]
	v_mfma_f32_16x16x32_bf16 v[110:113], v[152:155], v[184:187], v[110:113]
	v_mfma_f32_16x16x32_bf16 v[106:109], v[168:171], v[184:187], v[106:109]
	v_mfma_f32_16x16x32_bf16 v[94:97], v[152:155], v[192:195], v[94:97]
	v_mfma_f32_16x16x32_bf16 v[90:93], v[168:171], v[192:195], v[90:93]
	v_mfma_f32_16x16x32_bf16 v[78:81], v[152:155], v[200:203], v[78:81]
	v_mfma_f32_16x16x32_bf16 v[74:77], v[168:171], v[200:203], v[74:77]
	s_setprio 0
	s_barrier
	s_add_i32 s61, s55, s43
	v_lshl_add_u64 v[220:221], s[38:39], 0, v[132:133]
	s_mov_b32 m0, s61
	ds_read_b128 v[204:207], v166
	ds_read_b128 v[208:211], v166 offset:1024
	ds_read_b128 v[212:215], v166 offset:2048
	ds_read_b128 v[216:219], v166 offset:3072
	global_load_lds_dwordx4 v[220:221], off
	v_lshl_add_u64 v[222:223], s[38:39], 0, v[136:137]
	s_add_i32 m0, s61, 0x2000
	s_nop 0
	global_load_lds_dwordx4 v[222:223], off
	s_barrier
	s_waitcnt lgkmcnt(0)
	s_setprio 1
	s_waitcnt lgkmcnt(0)
	v_mfma_f32_16x16x32_bf16 v[118:121], v[204:207], v[172:175], 0
	v_mfma_f32_16x16x32_bf16 v[114:117], v[212:215], v[172:175], 0
	v_mfma_f32_16x16x32_bf16 v[102:105], v[204:207], v[180:183], 0
	v_mfma_f32_16x16x32_bf16 v[98:101], v[212:215], v[180:183], 0
	v_mfma_f32_16x16x32_bf16 v[86:89], v[204:207], v[188:191], 0
	v_mfma_f32_16x16x32_bf16 v[82:85], v[212:215], v[188:191], 0
	v_mfma_f32_16x16x32_bf16 v[70:73], v[204:207], v[196:199], 0
	v_mfma_f32_16x16x32_bf16 v[66:69], v[212:215], v[196:199], 0
	v_mfma_f32_16x16x32_bf16 v[118:121], v[208:211], v[176:179], v[118:121]
	v_mfma_f32_16x16x32_bf16 v[114:117], v[216:219], v[176:179], v[114:117]
	v_mfma_f32_16x16x32_bf16 v[102:105], v[208:211], v[184:187], v[102:105]
	v_mfma_f32_16x16x32_bf16 v[98:101], v[216:219], v[184:187], v[98:101]
	v_mfma_f32_16x16x32_bf16 v[86:89], v[208:211], v[192:195], v[86:89]
	v_mfma_f32_16x16x32_bf16 v[82:85], v[216:219], v[192:195], v[82:85]
	v_mfma_f32_16x16x32_bf16 v[70:73], v[208:211], v[200:203], v[70:73]
	v_mfma_f32_16x16x32_bf16 v[66:69], v[216:219], v[200:203], v[66:69]
	s_setprio 0
	s_mov_b32 m0, s46
	v_lshl_add_u64 v[224:225], s[40:41], 0, v[130:131]
	s_barrier
	ds_read_b128 v[172:175], v165 offset:16384
	ds_read_b128 v[176:179], v165 offset:17408
	ds_read_b128 v[180:183], v165 offset:18432
	ds_read_b128 v[184:187], v165 offset:19456
	ds_read_b128 v[188:191], v165 offset:20480
	ds_read_b128 v[192:195], v165 offset:21504
	ds_read_b128 v[196:199], v165 offset:22528
	ds_read_b128 v[200:203], v165 offset:23552
	global_load_lds_dwordx4 v[224:225], off
	v_lshl_add_u64 v[226:227], s[40:41], 0, v[134:135]
	s_mov_b32 m0, s47
	s_nop 0
	global_load_lds_dwordx4 v[226:227], off
	s_barrier
	s_waitcnt lgkmcnt(0)
	s_setprio 1
	s_waitcnt lgkmcnt(0)
	v_mfma_f32_16x16x32_bf16 v[62:65], v[148:151], v[172:175], 0
	v_mfma_f32_16x16x32_bf16 v[58:61], v[156:159], v[172:175], 0
	v_mfma_f32_16x16x32_bf16 v[46:49], v[148:151], v[180:183], 0
	v_mfma_f32_16x16x32_bf16 v[42:45], v[156:159], v[180:183], 0
	v_mfma_f32_16x16x32_bf16 v[30:33], v[148:151], v[188:191], 0
	v_mfma_f32_16x16x32_bf16 v[26:29], v[156:159], v[188:191], 0
	v_mfma_f32_16x16x32_bf16 v[14:17], v[148:151], v[196:199], 0
	v_mfma_f32_16x16x32_bf16 v[10:13], v[156:159], v[196:199], 0
	v_mfma_f32_16x16x32_bf16 v[62:65], v[152:155], v[176:179], v[62:65]
	v_mfma_f32_16x16x32_bf16 v[58:61], v[168:171], v[176:179], v[58:61]
	v_mfma_f32_16x16x32_bf16 v[46:49], v[152:155], v[184:187], v[46:49]
	v_mfma_f32_16x16x32_bf16 v[42:45], v[168:171], v[184:187], v[42:45]
	v_mfma_f32_16x16x32_bf16 v[30:33], v[152:155], v[192:195], v[30:33]
	v_mfma_f32_16x16x32_bf16 v[26:29], v[168:171], v[192:195], v[26:29]
	v_mfma_f32_16x16x32_bf16 v[14:17], v[152:155], v[200:203], v[14:17]
	v_mfma_f32_16x16x32_bf16 v[10:13], v[168:171], v[200:203], v[10:13]
	s_setprio 0
	s_barrier
	s_add_u32 s62, s38, 0x40000
	s_addc_u32 s63, s39, 0
	s_add_i32 s61, s56, s43
	v_lshl_add_u64 v[148:149], s[62:63], 0, v[132:133]
	s_mov_b32 m0, s61
	s_nop 0
	global_load_lds_dwordx4 v[148:149], off
	v_lshl_add_u64 v[148:149], s[62:63], 0, v[136:137]
	s_add_i32 m0, s61, 0x2000
	s_nop 0
	global_load_lds_dwordx4 v[148:149], off
	s_waitcnt vmcnt(6)
	s_barrier
	s_setprio 1
	v_mfma_f32_16x16x32_bf16 v[54:57], v[204:207], v[172:175], 0
	v_mfma_f32_16x16x32_bf16 v[50:53], v[212:215], v[172:175], 0
	v_mfma_f32_16x16x32_bf16 v[38:41], v[204:207], v[180:183], 0
	v_mfma_f32_16x16x32_bf16 v[34:37], v[212:215], v[180:183], 0
	v_mfma_f32_16x16x32_bf16 v[22:25], v[204:207], v[188:191], 0
	v_mfma_f32_16x16x32_bf16 v[18:21], v[212:215], v[188:191], 0
	v_mfma_f32_16x16x32_bf16 v[6:9], v[204:207], v[196:199], 0
	v_mfma_f32_16x16x32_bf16 v[2:5], v[212:215], v[196:199], 0
	v_mfma_f32_16x16x32_bf16 v[54:57], v[208:211], v[176:179], v[54:57]
	v_mfma_f32_16x16x32_bf16 v[50:53], v[216:219], v[176:179], v[50:53]
	v_mfma_f32_16x16x32_bf16 v[38:41], v[208:211], v[184:187], v[38:41]
	v_mfma_f32_16x16x32_bf16 v[34:37], v[216:219], v[184:187], v[34:37]
	v_mfma_f32_16x16x32_bf16 v[22:25], v[208:211], v[192:195], v[22:25]
	v_mfma_f32_16x16x32_bf16 v[18:21], v[216:219], v[192:195], v[18:21]
	v_mfma_f32_16x16x32_bf16 v[6:9], v[208:211], v[200:203], v[6:9]
	v_mfma_f32_16x16x32_bf16 v[2:5], v[216:219], v[200:203], v[2:5]
	s_setprio 0
	s_add_i32 s61, 0, 0x18000
	v_add_u32_e32 v138, s61, v161
	s_barrier
	ds_read_b128 v[148:151], v138
	ds_read_b128 v[152:155], v138 offset:1024
	ds_read_b128 v[156:159], v138 offset:2048
	ds_read_b128 v[168:171], v138 offset:3072
	s_add_u32 s40, s40, 0x40000
	s_addc_u32 s41, s41, 0
	s_mov_b32 m0, s48
	v_lshl_add_u64 v[204:205], s[40:41], 0, v[130:131]
	ds_read_b128 v[172:175], v165 offset:32768
	ds_read_b128 v[176:179], v165 offset:33792
	ds_read_b128 v[180:183], v165 offset:34816
	ds_read_b128 v[184:187], v165 offset:35840
	ds_read_b128 v[188:191], v165 offset:36864
	ds_read_b128 v[192:195], v165 offset:37888
	ds_read_b128 v[196:199], v165 offset:38912
	ds_read_b128 v[200:203], v165 offset:39936
	global_load_lds_dwordx4 v[204:205], off
	v_lshl_add_u64 v[204:205], s[40:41], 0, v[134:135]
	s_mov_b32 m0, s49
	s_nop 0
	global_load_lds_dwordx4 v[204:205], off
	s_waitcnt lgkmcnt(8)
	s_barrier
	s_waitcnt lgkmcnt(0)
	s_setprio 1
	s_waitcnt lgkmcnt(0)
	v_mfma_f32_16x16x32_bf16 v[126:129], v[148:151], v[172:175], v[126:129]
	v_mfma_f32_16x16x32_bf16 v[122:125], v[156:159], v[172:175], v[122:125]
	v_mfma_f32_16x16x32_bf16 v[110:113], v[148:151], v[180:183], v[110:113]
	v_mfma_f32_16x16x32_bf16 v[106:109], v[156:159], v[180:183], v[106:109]
	v_mfma_f32_16x16x32_bf16 v[94:97], v[148:151], v[188:191], v[94:97]
	v_mfma_f32_16x16x32_bf16 v[90:93], v[156:159], v[188:191], v[90:93]
	v_mfma_f32_16x16x32_bf16 v[78:81], v[148:151], v[196:199], v[78:81]
	v_mfma_f32_16x16x32_bf16 v[74:77], v[156:159], v[196:199], v[74:77]
	v_mfma_f32_16x16x32_bf16 v[126:129], v[152:155], v[176:179], v[126:129]
	v_mfma_f32_16x16x32_bf16 v[122:125], v[168:171], v[176:179], v[122:125]
	v_mfma_f32_16x16x32_bf16 v[110:113], v[152:155], v[184:187], v[110:113]
	v_mfma_f32_16x16x32_bf16 v[106:109], v[168:171], v[184:187], v[106:109]
	v_mfma_f32_16x16x32_bf16 v[94:97], v[152:155], v[192:195], v[94:97]
	v_mfma_f32_16x16x32_bf16 v[90:93], v[168:171], v[192:195], v[90:93]
	v_mfma_f32_16x16x32_bf16 v[78:81], v[152:155], v[200:203], v[78:81]
	v_mfma_f32_16x16x32_bf16 v[74:77], v[168:171], v[200:203], v[74:77]
	s_setprio 0
	s_barrier
	s_add_i32 s40, 0, 0x1c000
	s_add_i32 s41, s61, s43
	v_add_u32_e32 v138, s40, v161
	v_lshl_add_u64 v[220:221], v[220:221], 0, s[12:13]
	s_mov_b32 m0, s41
	ds_read_b128 v[204:207], v138
	ds_read_b128 v[208:211], v138 offset:1024
	ds_read_b128 v[212:215], v138 offset:2048
	ds_read_b128 v[216:219], v138 offset:3072
	global_load_lds_dwordx4 v[220:221], off
	v_lshl_add_u64 v[220:221], v[222:223], 0, s[12:13]
	s_add_i32 m0, s41, 0x2000
	s_nop 0
	global_load_lds_dwordx4 v[220:221], off
	s_barrier
	s_waitcnt lgkmcnt(0)
	s_setprio 1
	s_waitcnt lgkmcnt(0)
	v_mfma_f32_16x16x32_bf16 v[118:121], v[204:207], v[172:175], v[118:121]
	v_mfma_f32_16x16x32_bf16 v[114:117], v[212:215], v[172:175], v[114:117]
	v_mfma_f32_16x16x32_bf16 v[102:105], v[204:207], v[180:183], v[102:105]
	v_mfma_f32_16x16x32_bf16 v[98:101], v[212:215], v[180:183], v[98:101]
	v_mfma_f32_16x16x32_bf16 v[86:89], v[204:207], v[188:191], v[86:89]
	v_mfma_f32_16x16x32_bf16 v[82:85], v[212:215], v[188:191], v[82:85]
	v_mfma_f32_16x16x32_bf16 v[70:73], v[204:207], v[196:199], v[70:73]
	v_mfma_f32_16x16x32_bf16 v[66:69], v[212:215], v[196:199], v[66:69]
	v_mfma_f32_16x16x32_bf16 v[118:121], v[208:211], v[176:179], v[118:121]
	v_mfma_f32_16x16x32_bf16 v[114:117], v[216:219], v[176:179], v[114:117]
	v_mfma_f32_16x16x32_bf16 v[102:105], v[208:211], v[184:187], v[102:105]
	v_mfma_f32_16x16x32_bf16 v[98:101], v[216:219], v[184:187], v[98:101]
	v_mfma_f32_16x16x32_bf16 v[86:89], v[208:211], v[192:195], v[86:89]
	v_mfma_f32_16x16x32_bf16 v[82:85], v[216:219], v[192:195], v[82:85]
	v_mfma_f32_16x16x32_bf16 v[70:73], v[208:211], v[200:203], v[70:73]
	v_mfma_f32_16x16x32_bf16 v[66:69], v[216:219], v[200:203], v[66:69]
	s_setprio 0
	s_mov_b32 m0, s50
	v_lshl_add_u64 v[220:221], v[224:225], 0, s[12:13]
	s_barrier
	ds_read_b128 v[172:175], v165 offset:49152
	ds_read_b128 v[176:179], v165 offset:50176
	ds_read_b128 v[180:183], v165 offset:51200
	ds_read_b128 v[184:187], v165 offset:52224
	ds_read_b128 v[188:191], v165 offset:53248
	ds_read_b128 v[192:195], v165 offset:54272
	ds_read_b128 v[196:199], v165 offset:55296
	ds_read_b128 v[200:203], v165 offset:56320
	global_load_lds_dwordx4 v[220:221], off
	v_lshl_add_u64 v[220:221], v[226:227], 0, s[12:13]
	s_mov_b32 m0, s51
	s_nop 0
	global_load_lds_dwordx4 v[220:221], off
	s_barrier
	s_waitcnt lgkmcnt(0)
	s_setprio 1
	s_waitcnt lgkmcnt(0)
	v_mfma_f32_16x16x32_bf16 v[62:65], v[148:151], v[172:175], v[62:65]
	v_mfma_f32_16x16x32_bf16 v[58:61], v[156:159], v[172:175], v[58:61]
	v_mfma_f32_16x16x32_bf16 v[46:49], v[148:151], v[180:183], v[46:49]
	v_mfma_f32_16x16x32_bf16 v[42:45], v[156:159], v[180:183], v[42:45]
	v_mfma_f32_16x16x32_bf16 v[30:33], v[148:151], v[188:191], v[30:33]
	v_mfma_f32_16x16x32_bf16 v[26:29], v[156:159], v[188:191], v[26:29]
	v_mfma_f32_16x16x32_bf16 v[14:17], v[148:151], v[196:199], v[14:17]
	v_mfma_f32_16x16x32_bf16 v[10:13], v[156:159], v[196:199], v[10:13]
	v_mfma_f32_16x16x32_bf16 v[62:65], v[152:155], v[176:179], v[62:65]
	v_mfma_f32_16x16x32_bf16 v[58:61], v[168:171], v[176:179], v[58:61]
	v_mfma_f32_16x16x32_bf16 v[46:49], v[152:155], v[184:187], v[46:49]
	v_mfma_f32_16x16x32_bf16 v[42:45], v[168:171], v[184:187], v[42:45]
	v_mfma_f32_16x16x32_bf16 v[30:33], v[152:155], v[192:195], v[30:33]
	v_mfma_f32_16x16x32_bf16 v[26:29], v[168:171], v[192:195], v[26:29]
	v_mfma_f32_16x16x32_bf16 v[14:17], v[152:155], v[200:203], v[14:17]
	v_mfma_f32_16x16x32_bf16 v[10:13], v[168:171], v[200:203], v[10:13]
	s_setprio 0
	s_barrier
	s_add_u32 s38, s38, 0x40080
	s_addc_u32 s39, s39, 0
	s_add_i32 s40, s40, s43
	v_lshl_add_u64 v[148:149], s[38:39], 0, v[132:133]
	s_mov_b32 m0, s40
	s_nop 0
	global_load_lds_dwordx4 v[148:149], off
	v_lshl_add_u64 v[148:149], s[38:39], 0, v[136:137]
	s_add_i32 m0, s40, 0x2000
	s_nop 0
	global_load_lds_dwordx4 v[148:149], off
	s_waitcnt vmcnt(6)
	s_barrier
	s_setprio 1
	v_mfma_f32_16x16x32_bf16 v[54:57], v[204:207], v[172:175], v[54:57]
	v_mfma_f32_16x16x32_bf16 v[50:53], v[212:215], v[172:175], v[50:53]
	v_mfma_f32_16x16x32_bf16 v[38:41], v[204:207], v[180:183], v[38:41]
	v_mfma_f32_16x16x32_bf16 v[34:37], v[212:215], v[180:183], v[34:37]
	v_mfma_f32_16x16x32_bf16 v[22:25], v[204:207], v[188:191], v[22:25]
	v_mfma_f32_16x16x32_bf16 v[18:21], v[212:215], v[188:191], v[18:21]
	v_mfma_f32_16x16x32_bf16 v[6:9], v[204:207], v[196:199], v[6:9]
	v_mfma_f32_16x16x32_bf16 v[2:5], v[212:215], v[196:199], v[2:5]
	v_mfma_f32_16x16x32_bf16 v[54:57], v[208:211], v[176:179], v[54:57]
	v_mfma_f32_16x16x32_bf16 v[50:53], v[216:219], v[176:179], v[50:53]
	v_mfma_f32_16x16x32_bf16 v[38:41], v[208:211], v[184:187], v[38:41]
	v_mfma_f32_16x16x32_bf16 v[34:37], v[216:219], v[184:187], v[34:37]
	v_mfma_f32_16x16x32_bf16 v[22:25], v[208:211], v[192:195], v[22:25]
	v_mfma_f32_16x16x32_bf16 v[18:21], v[216:219], v[192:195], v[18:21]
	v_mfma_f32_16x16x32_bf16 v[6:9], v[208:211], v[200:203], v[6:9]
	v_mfma_f32_16x16x32_bf16 v[2:5], v[216:219], v[200:203], v[2:5]
	s_setprio 0
	s_add_i32 s60, s60, 2
	s_add_u32 s36, s36, 0x100
	s_addc_u32 s37, s37, 0
	s_add_u32 s35, s35, 0x100
	s_addc_u32 s59, s59, 0
	s_cmp_gt_u32 s60, 13
	s_barrier
	s_cbranch_scc1 .Lgemm_epi2

.Lgemm_epi2:
	s_add_u32 s8, s68, 0xf000000
	s_addc_u32 s9, s69, 0
	s_cmp_gt_i32 s4, 11
	s_cselect_b32 s8, s8, s98
	s_cselect_b32 s9, s9, s99
	s_cmp_gt_i32 s4, 9
	v_lshl_add_u32 v150, s34, 8, v160
	s_cselect_b64 s[34:35], -1, 0
	s_lshl_b32 s0, s5, 10
	v_add_u32_e32 v167, s0, v162
	ds_read_b32 v152, v167
	v_ashrrev_i32_e32 v151, 31, v150
	v_lshlrev_b64 v[154:155], 11, v[150:151]
	v_lshl_or_b32 v148, s4, 8, v163
	s_mov_b64 s[4:5], -1
	s_and_b64 vcc, exec, s[34:35]
	v_lshl_add_u64 v[154:155], s[8:9], 0, v[154:155]
	s_cbranch_vccz .LBB0_209
	v_mov_b32_e32 v149, v139
	v_lshl_add_u64 v[156:157], v[148:149], 1, v[154:155]
	v_lshl_add_u64 v[158:159], v[156:157], 0, s[20:21]
	s_mov_b64 s[4:5], 0

.LBB0_585:
	s_ashr_i32 s15, s14, 31
	s_lshl_b64 s[0:1], s[14:15], 19
	v_cmp_lt_i64_e32 vcc, s[16:17], v[166:167]
	s_add_u32 s16, s31, s0
	s_addc_u32 s17, s33, s1
	s_and_b64 s[0:1], vcc, exec
	s_cselect_b32 s0, s17, s25
	s_cselect_b32 s1, s16, s24
	s_ashr_i32 s13, s12, 31
	s_lshl_b64 s[18:19], s[12:13], 19
	s_add_u32 s18, s34, s18
	s_addc_u32 s19, s35, s19
	s_and_b64 s[28:29], vcc, exec
	s_cselect_b32 s13, s19, s27
	s_cselect_b32 s15, s18, s26
	s_add_u32 s24, s24, 0x40080
	s_addc_u32 s25, s25, 0
	s_add_u32 s21, s26, 0x100
	s_addc_u32 s47, s27, 0
	s_mov_b32 s48, -2
	s_waitcnt lgkmcnt(0)
	ds_read_b128 v[130:133], v191
	ds_read_b128 v[134:137], v191 offset:1024
	ds_read_b128 v[138:141], v191 offset:2048
	ds_read_b128 v[142:145], v191 offset:3072
	s_add_u32 s26, s24, 0xfffc0080
	s_addc_u32 s27, s25, -1
	s_cmp_eq_u32 s48, 12
	s_cselect_b32 s29, s0, s27
	s_cselect_b32 s28, s1, s26
	s_cselect_b32 s27, s13, s47
	s_cselect_b32 s26, s15, s21
	v_lshl_add_u64 v[186:187], s[24:25], 0, v[162:163]
	s_add_i32 m0, s23, 0xc000
	ds_read_b128 v[146:149], v192
	ds_read_b128 v[150:153], v192 offset:1024
	ds_read_b128 v[170:173], v192 offset:2048
	ds_read_b128 v[174:177], v192 offset:3072
	ds_read_b128 v[178:181], v192 offset:4096
	ds_read_b128 v[182:185], v192 offset:5120
	ds_read_b128 v[196:199], v192 offset:6144
	ds_read_b128 v[200:203], v192 offset:7168
	global_load_lds_dwordx4 v[186:187], off
	v_lshl_add_u64 v[186:187], s[24:25], 0, v[164:165]
	s_add_i32 m0, s23, 0xe000
	s_nop 0
	global_load_lds_dwordx4 v[186:187], off
	s_waitcnt lgkmcnt(8)
	s_barrier
	s_waitcnt lgkmcnt(0)
	s_setprio 1
	s_waitcnt lgkmcnt(0)
	v_mfma_f32_16x16x32_bf16 v[126:129], v[130:133], v[146:149], 0
	v_mfma_f32_16x16x32_bf16 v[122:125], v[138:141], v[146:149], 0
	v_mfma_f32_16x16x32_bf16 v[110:113], v[130:133], v[170:173], 0
	v_mfma_f32_16x16x32_bf16 v[106:109], v[138:141], v[170:173], 0
	v_mfma_f32_16x16x32_bf16 v[94:97], v[130:133], v[178:181], 0
	v_mfma_f32_16x16x32_bf16 v[90:93], v[138:141], v[178:181], 0
	v_mfma_f32_16x16x32_bf16 v[78:81], v[130:133], v[196:199], 0
	v_mfma_f32_16x16x32_bf16 v[74:77], v[138:141], v[196:199], 0
	v_mfma_f32_16x16x32_bf16 v[126:129], v[134:137], v[150:153], v[126:129]
	v_mfma_f32_16x16x32_bf16 v[122:125], v[142:145], v[150:153], v[122:125]
	v_mfma_f32_16x16x32_bf16 v[110:113], v[134:137], v[174:177], v[110:113]
	v_mfma_f32_16x16x32_bf16 v[106:109], v[142:145], v[174:177], v[106:109]
	v_mfma_f32_16x16x32_bf16 v[94:97], v[134:137], v[182:185], v[94:97]
	v_mfma_f32_16x16x32_bf16 v[90:93], v[142:145], v[182:185], v[90:93]
	v_mfma_f32_16x16x32_bf16 v[78:81], v[134:137], v[200:203], v[78:81]
	v_mfma_f32_16x16x32_bf16 v[74:77], v[142:145], v[200:203], v[74:77]
	s_setprio 0
	s_barrier
	s_add_i32 s49, s45, s36
	v_lshl_add_u64 v[186:187], s[26:27], 0, v[156:157]
	s_mov_b32 m0, s49
	ds_read_b128 v[204:207], v193
	ds_read_b128 v[208:211], v193 offset:1024
	ds_read_b128 v[212:215], v193 offset:2048
	ds_read_b128 v[216:219], v193 offset:3072
	global_load_lds_dwordx4 v[186:187], off
	v_lshl_add_u64 v[220:221], s[26:27], 0, v[160:161]
	s_add_i32 m0, s49, 0x2000
	s_nop 0
	global_load_lds_dwordx4 v[220:221], off
	s_barrier
	s_waitcnt lgkmcnt(0)
	s_setprio 1
	s_waitcnt lgkmcnt(0)
	v_mfma_f32_16x16x32_bf16 v[118:121], v[204:207], v[146:149], 0
	v_mfma_f32_16x16x32_bf16 v[114:117], v[212:215], v[146:149], 0
	v_mfma_f32_16x16x32_bf16 v[102:105], v[204:207], v[170:173], 0
	v_mfma_f32_16x16x32_bf16 v[98:101], v[212:215], v[170:173], 0
	v_mfma_f32_16x16x32_bf16 v[86:89], v[204:207], v[178:181], 0
	v_mfma_f32_16x16x32_bf16 v[82:85], v[212:215], v[178:181], 0
	v_mfma_f32_16x16x32_bf16 v[70:73], v[204:207], v[196:199], 0
	v_mfma_f32_16x16x32_bf16 v[66:69], v[212:215], v[196:199], 0
	v_mfma_f32_16x16x32_bf16 v[118:121], v[208:211], v[150:153], v[118:121]
	v_mfma_f32_16x16x32_bf16 v[114:117], v[216:219], v[150:153], v[114:117]
	v_mfma_f32_16x16x32_bf16 v[102:105], v[208:211], v[174:177], v[102:105]
	v_mfma_f32_16x16x32_bf16 v[98:101], v[216:219], v[174:177], v[98:101]
	v_mfma_f32_16x16x32_bf16 v[86:89], v[208:211], v[182:185], v[86:89]
	v_mfma_f32_16x16x32_bf16 v[82:85], v[216:219], v[182:185], v[82:85]
	v_mfma_f32_16x16x32_bf16 v[70:73], v[208:211], v[200:203], v[70:73]
	v_mfma_f32_16x16x32_bf16 v[66:69], v[216:219], v[200:203], v[66:69]
	s_setprio 0
	s_mov_b32 m0, s23
	v_lshl_add_u64 v[222:223], s[28:29], 0, v[154:155]
	s_barrier
	ds_read_b128 v[146:149], v192 offset:16384
	ds_read_b128 v[150:153], v192 offset:17408
	ds_read_b128 v[170:173], v192 offset:18432
	ds_read_b128 v[174:177], v192 offset:19456
	ds_read_b128 v[178:181], v192 offset:20480
	ds_read_b128 v[182:185], v192 offset:21504
	ds_read_b128 v[196:199], v192 offset:22528
	ds_read_b128 v[200:203], v192 offset:23552
	global_load_lds_dwordx4 v[222:223], off
	v_lshl_add_u64 v[224:225], s[28:29], 0, v[158:159]
	s_mov_b32 m0, s37
	s_nop 0
	global_load_lds_dwordx4 v[224:225], off
	s_barrier
	s_waitcnt lgkmcnt(0)
	s_setprio 1
	s_waitcnt lgkmcnt(0)
	v_mfma_f32_16x16x32_bf16 v[62:65], v[130:133], v[146:149], 0
	v_mfma_f32_16x16x32_bf16 v[58:61], v[138:141], v[146:149], 0
	v_mfma_f32_16x16x32_bf16 v[46:49], v[130:133], v[170:173], 0
	v_mfma_f32_16x16x32_bf16 v[42:45], v[138:141], v[170:173], 0
	v_mfma_f32_16x16x32_bf16 v[30:33], v[130:133], v[178:181], 0
	v_mfma_f32_16x16x32_bf16 v[26:29], v[138:141], v[178:181], 0
	v_mfma_f32_16x16x32_bf16 v[14:17], v[130:133], v[196:199], 0
	v_mfma_f32_16x16x32_bf16 v[10:13], v[138:141], v[196:199], 0
	v_mfma_f32_16x16x32_bf16 v[62:65], v[134:137], v[150:153], v[62:65]
	v_mfma_f32_16x16x32_bf16 v[58:61], v[142:145], v[150:153], v[58:61]
	v_mfma_f32_16x16x32_bf16 v[46:49], v[134:137], v[174:177], v[46:49]
	v_mfma_f32_16x16x32_bf16 v[42:45], v[142:145], v[174:177], v[42:45]
	v_mfma_f32_16x16x32_bf16 v[30:33], v[134:137], v[182:185], v[30:33]
	v_mfma_f32_16x16x32_bf16 v[26:29], v[142:145], v[182:185], v[26:29]
	v_mfma_f32_16x16x32_bf16 v[14:17], v[134:137], v[200:203], v[14:17]
	v_mfma_f32_16x16x32_bf16 v[10:13], v[142:145], v[200:203], v[10:13]
	s_setprio 0
	s_barrier
	s_add_u32 s50, s26, 0x40000
	s_addc_u32 s51, s27, 0
	s_add_i32 s49, s46, s36
	v_lshl_add_u64 v[130:131], s[50:51], 0, v[156:157]
	s_mov_b32 m0, s49
	s_nop 0
	global_load_lds_dwordx4 v[130:131], off
	v_lshl_add_u64 v[130:131], s[50:51], 0, v[160:161]
	s_add_i32 m0, s49, 0x2000
	s_nop 0
	global_load_lds_dwordx4 v[130:131], off
	s_waitcnt vmcnt(6)
	s_barrier
	s_setprio 1
	v_mfma_f32_16x16x32_bf16 v[54:57], v[204:207], v[146:149], 0
	v_mfma_f32_16x16x32_bf16 v[50:53], v[212:215], v[146:149], 0
	v_mfma_f32_16x16x32_bf16 v[38:41], v[204:207], v[170:173], 0
	v_mfma_f32_16x16x32_bf16 v[34:37], v[212:215], v[170:173], 0
	v_mfma_f32_16x16x32_bf16 v[22:25], v[204:207], v[178:181], 0
	v_mfma_f32_16x16x32_bf16 v[18:21], v[212:215], v[178:181], 0
	v_mfma_f32_16x16x32_bf16 v[6:9], v[204:207], v[196:199], 0
	v_mfma_f32_16x16x32_bf16 v[2:5], v[212:215], v[196:199], 0
	v_mfma_f32_16x16x32_bf16 v[54:57], v[208:211], v[150:153], v[54:57]
	v_mfma_f32_16x16x32_bf16 v[50:53], v[216:219], v[150:153], v[50:53]
	v_mfma_f32_16x16x32_bf16 v[38:41], v[208:211], v[174:177], v[38:41]
	v_mfma_f32_16x16x32_bf16 v[34:37], v[216:219], v[174:177], v[34:37]
	v_mfma_f32_16x16x32_bf16 v[22:25], v[208:211], v[182:185], v[22:25]
	v_mfma_f32_16x16x32_bf16 v[18:21], v[216:219], v[182:185], v[18:21]
	v_mfma_f32_16x16x32_bf16 v[6:9], v[208:211], v[200:203], v[6:9]
	v_mfma_f32_16x16x32_bf16 v[2:5], v[216:219], v[200:203], v[2:5]
	s_setprio 0
	s_add_i32 s49, 0, 0x18000
	v_add_u32_e32 v142, s49, v189
	s_barrier
	ds_read_b128 v[130:133], v142
	ds_read_b128 v[134:137], v142 offset:1024
	ds_read_b128 v[138:141], v142 offset:2048
	ds_read_b128 v[142:145], v142 offset:3072
	s_add_u32 s28, s28, 0x40000
	s_addc_u32 s29, s29, 0
	s_mov_b32 m0, s38
	v_lshl_add_u64 v[204:205], s[28:29], 0, v[154:155]
	ds_read_b128 v[146:149], v192 offset:32768
	ds_read_b128 v[150:153], v192 offset:33792
	ds_read_b128 v[170:173], v192 offset:34816
	ds_read_b128 v[174:177], v192 offset:35840
	ds_read_b128 v[178:181], v192 offset:36864
	ds_read_b128 v[182:185], v192 offset:37888
	ds_read_b128 v[196:199], v192 offset:38912
	ds_read_b128 v[200:203], v192 offset:39936
	global_load_lds_dwordx4 v[204:205], off
	v_lshl_add_u64 v[204:205], s[28:29], 0, v[158:159]
	s_mov_b32 m0, s39
	s_nop 0
	global_load_lds_dwordx4 v[204:205], off
	s_waitcnt lgkmcnt(8)
	s_barrier
	s_waitcnt lgkmcnt(0)
	s_setprio 1
	s_waitcnt lgkmcnt(0)
	v_mfma_f32_16x16x32_bf16 v[126:129], v[130:133], v[146:149], v[126:129]
	v_mfma_f32_16x16x32_bf16 v[122:125], v[138:141], v[146:149], v[122:125]
	v_mfma_f32_16x16x32_bf16 v[110:113], v[130:133], v[170:173], v[110:113]
	v_mfma_f32_16x16x32_bf16 v[106:109], v[138:141], v[170:173], v[106:109]
	v_mfma_f32_16x16x32_bf16 v[94:97], v[130:133], v[178:181], v[94:97]
	v_mfma_f32_16x16x32_bf16 v[90:93], v[138:141], v[178:181], v[90:93]
	v_mfma_f32_16x16x32_bf16 v[78:81], v[130:133], v[196:199], v[78:81]
	v_mfma_f32_16x16x32_bf16 v[74:77], v[138:141], v[196:199], v[74:77]
	v_mfma_f32_16x16x32_bf16 v[126:129], v[134:137], v[150:153], v[126:129]
	v_mfma_f32_16x16x32_bf16 v[122:125], v[142:145], v[150:153], v[122:125]
	v_mfma_f32_16x16x32_bf16 v[110:113], v[134:137], v[174:177], v[110:113]
	v_mfma_f32_16x16x32_bf16 v[106:109], v[142:145], v[174:177], v[106:109]
	v_mfma_f32_16x16x32_bf16 v[94:97], v[134:137], v[182:185], v[94:97]
	v_mfma_f32_16x16x32_bf16 v[90:93], v[142:145], v[182:185], v[90:93]
	v_mfma_f32_16x16x32_bf16 v[78:81], v[134:137], v[200:203], v[78:81]
	v_mfma_f32_16x16x32_bf16 v[74:77], v[142:145], v[200:203], v[74:77]
	s_setprio 0
	s_barrier
	s_add_i32 s28, 0, 0x1c000
	s_add_i32 s29, s49, s36
	v_add_u32_e32 v195, s28, v189
	v_lshl_add_u64 v[186:187], v[186:187], 0, s[8:9]
	s_mov_b32 m0, s29
	ds_read_b128 v[204:207], v195
	ds_read_b128 v[208:211], v195 offset:1024
	ds_read_b128 v[212:215], v195 offset:2048
	ds_read_b128 v[216:219], v195 offset:3072
	global_load_lds_dwordx4 v[186:187], off
	v_lshl_add_u64 v[186:187], v[220:221], 0, s[8:9]
	s_add_i32 m0, s29, 0x2000
	s_nop 0
	global_load_lds_dwordx4 v[186:187], off
	s_barrier
	s_waitcnt lgkmcnt(0)
	s_setprio 1
	s_waitcnt lgkmcnt(0)
	v_mfma_f32_16x16x32_bf16 v[118:121], v[204:207], v[146:149], v[118:121]
	v_mfma_f32_16x16x32_bf16 v[114:117], v[212:215], v[146:149], v[114:117]
	v_mfma_f32_16x16x32_bf16 v[102:105], v[204:207], v[170:173], v[102:105]
	v_mfma_f32_16x16x32_bf16 v[98:101], v[212:215], v[170:173], v[98:101]
	v_mfma_f32_16x16x32_bf16 v[86:89], v[204:207], v[178:181], v[86:89]
	v_mfma_f32_16x16x32_bf16 v[82:85], v[212:215], v[178:181], v[82:85]
	v_mfma_f32_16x16x32_bf16 v[70:73], v[204:207], v[196:199], v[70:73]
	v_mfma_f32_16x16x32_bf16 v[66:69], v[212:215], v[196:199], v[66:69]
	v_mfma_f32_16x16x32_bf16 v[118:121], v[208:211], v[150:153], v[118:121]
	v_mfma_f32_16x16x32_bf16 v[114:117], v[216:219], v[150:153], v[114:117]
	v_mfma_f32_16x16x32_bf16 v[102:105], v[208:211], v[174:177], v[102:105]
	v_mfma_f32_16x16x32_bf16 v[98:101], v[216:219], v[174:177], v[98:101]
	v_mfma_f32_16x16x32_bf16 v[86:89], v[208:211], v[182:185], v[86:89]
	v_mfma_f32_16x16x32_bf16 v[82:85], v[216:219], v[182:185], v[82:85]
	v_mfma_f32_16x16x32_bf16 v[70:73], v[208:211], v[200:203], v[70:73]
	v_mfma_f32_16x16x32_bf16 v[66:69], v[216:219], v[200:203], v[66:69]
	s_setprio 0
	s_mov_b32 m0, s41
	v_lshl_add_u64 v[186:187], v[222:223], 0, s[8:9]
	s_barrier
	ds_read_b128 v[146:149], v192 offset:49152
	ds_read_b128 v[150:153], v192 offset:50176
	ds_read_b128 v[170:173], v192 offset:51200
	ds_read_b128 v[174:177], v192 offset:52224
	ds_read_b128 v[178:181], v192 offset:53248
	ds_read_b128 v[182:185], v192 offset:54272
	ds_read_b128 v[196:199], v192 offset:55296
	ds_read_b128 v[200:203], v192 offset:56320
	global_load_lds_dwordx4 v[186:187], off
	v_lshl_add_u64 v[186:187], v[224:225], 0, s[8:9]
	s_mov_b32 m0, s42
	s_nop 0
	global_load_lds_dwordx4 v[186:187], off
	s_barrier
	s_waitcnt lgkmcnt(0)
	s_setprio 1
	s_waitcnt lgkmcnt(0)
	v_mfma_f32_16x16x32_bf16 v[62:65], v[130:133], v[146:149], v[62:65]
	v_mfma_f32_16x16x32_bf16 v[58:61], v[138:141], v[146:149], v[58:61]
	v_mfma_f32_16x16x32_bf16 v[46:49], v[130:133], v[170:173], v[46:49]
	v_mfma_f32_16x16x32_bf16 v[42:45], v[138:141], v[170:173], v[42:45]
	v_mfma_f32_16x16x32_bf16 v[30:33], v[130:133], v[178:181], v[30:33]
	v_mfma_f32_16x16x32_bf16 v[26:29], v[138:141], v[178:181], v[26:29]
	v_mfma_f32_16x16x32_bf16 v[14:17], v[130:133], v[196:199], v[14:17]
	v_mfma_f32_16x16x32_bf16 v[10:13], v[138:141], v[196:199], v[10:13]
	v_mfma_f32_16x16x32_bf16 v[62:65], v[134:137], v[150:153], v[62:65]
	v_mfma_f32_16x16x32_bf16 v[58:61], v[142:145], v[150:153], v[58:61]
	v_mfma_f32_16x16x32_bf16 v[46:49], v[134:137], v[174:177], v[46:49]
	v_mfma_f32_16x16x32_bf16 v[42:45], v[142:145], v[174:177], v[42:45]
	v_mfma_f32_16x16x32_bf16 v[30:33], v[134:137], v[182:185], v[30:33]
	v_mfma_f32_16x16x32_bf16 v[26:29], v[142:145], v[182:185], v[26:29]
	v_mfma_f32_16x16x32_bf16 v[14:17], v[134:137], v[200:203], v[14:17]
	v_mfma_f32_16x16x32_bf16 v[10:13], v[142:145], v[200:203], v[10:13]
	s_setprio 0
	s_barrier
	s_add_u32 s26, s26, 0x40080
	s_addc_u32 s27, s27, 0
	s_add_i32 s28, s28, s36
	v_lshl_add_u64 v[130:131], s[26:27], 0, v[156:157]
	s_mov_b32 m0, s28
	s_nop 0
	global_load_lds_dwordx4 v[130:131], off
	v_lshl_add_u64 v[130:131], s[26:27], 0, v[160:161]
	s_add_i32 m0, s28, 0x2000
	s_nop 0
	global_load_lds_dwordx4 v[130:131], off
	s_waitcnt vmcnt(6)
	s_barrier
	s_setprio 1
	v_mfma_f32_16x16x32_bf16 v[54:57], v[204:207], v[146:149], v[54:57]
	v_mfma_f32_16x16x32_bf16 v[50:53], v[212:215], v[146:149], v[50:53]
	v_mfma_f32_16x16x32_bf16 v[38:41], v[204:207], v[170:173], v[38:41]
	v_mfma_f32_16x16x32_bf16 v[34:37], v[212:215], v[170:173], v[34:37]
	v_mfma_f32_16x16x32_bf16 v[22:25], v[204:207], v[178:181], v[22:25]
	v_mfma_f32_16x16x32_bf16 v[18:21], v[212:215], v[178:181], v[18:21]
	v_mfma_f32_16x16x32_bf16 v[6:9], v[204:207], v[196:199], v[6:9]
	v_mfma_f32_16x16x32_bf16 v[2:5], v[212:215], v[196:199], v[2:5]
	v_mfma_f32_16x16x32_bf16 v[54:57], v[208:211], v[150:153], v[54:57]
	v_mfma_f32_16x16x32_bf16 v[50:53], v[216:219], v[150:153], v[50:53]
	v_mfma_f32_16x16x32_bf16 v[38:41], v[208:211], v[174:177], v[38:41]
	v_mfma_f32_16x16x32_bf16 v[34:37], v[216:219], v[174:177], v[34:37]
	v_mfma_f32_16x16x32_bf16 v[22:25], v[208:211], v[182:185], v[22:25]
	v_mfma_f32_16x16x32_bf16 v[18:21], v[216:219], v[182:185], v[18:21]
	v_mfma_f32_16x16x32_bf16 v[6:9], v[208:211], v[200:203], v[6:9]
	v_mfma_f32_16x16x32_bf16 v[2:5], v[216:219], v[200:203], v[2:5]
	s_setprio 0
	s_add_i32 s48, s48, 2
	s_add_u32 s24, s24, 0x100
	s_addc_u32 s25, s25, 0
	s_add_u32 s21, s21, 0x100
	s_addc_u32 s47, s47, 0
	s_cmp_gt_u32 s48, 13
	s_barrier
	s_cbranch_scc1 .Lgemm_epi3

.Lgemm_epi3:
	v_lshl_or_b32 v170, s22, 8, v190
	v_lshl_add_u32 v174, s20, 8, v188
	v_ashrrev_i32_e32 v171, 31, v170
	v_lshlrev_b64 v[204:205], 1, v[170:171]
	v_ashrrev_i32_e32 v175, 31, v174
	v_lshl_add_u64 v[172:173], s[68:69], 0, v[204:205]
	v_lshlrev_b64 v[206:207], 11, v[174:175]
	v_lshl_add_u64 v[130:131], v[172:173], 0, v[206:207]
	global_load_dwordx4 v[196:199], v[130:131], off
	global_load_dwordx4 v[200:203], v[130:131], off offset:256
	v_or_b32_e32 v184, 16, v174
	v_or_b32_e32 v180, 32, v174
	v_or_b32_e32 v176, 48, v174
	v_ashrrev_i32_e32 v185, 31, v184
	v_ashrrev_i32_e32 v181, 31, v180
	v_ashrrev_i32_e32 v177, 31, v176
	v_lshlrev_b64 v[186:187], 11, v[184:185]
	v_lshlrev_b64 v[182:183], 11, v[180:181]
	v_lshlrev_b64 v[178:179], 11, v[176:177]
	v_lshl_add_u64 v[130:131], v[172:173], 0, v[186:187]
	v_lshl_add_u64 v[132:133], v[172:173], 0, v[182:183]
	v_lshl_add_u64 v[208:209], v[172:173], 0, v[178:179]
	global_load_dwordx4 v[150:153], v[130:131], off
	global_load_dwordx4 v[146:149], v[130:131], off offset:256
	global_load_dwordx4 v[142:145], v[132:133], off
	global_load_dwordx4 v[138:141], v[132:133], off offset:256
	global_load_dwordx4 v[134:137], v[208:209], off
	s_nop 0
	global_load_dwordx4 v[130:133], v[208:209], off offset:256
	v_lshl_add_u64 v[206:207], s[68:69], 0, v[206:207]
	v_and_b32_e32 v208, 64, v194
	v_lshl_add_u64 v[204:205], v[206:207], 0, v[204:205]
	v_xor_b32_e32 v195, 16, v194
	v_add_u32_e32 v208, 64, v208
	v_xor_b32_e32 v209, 32, v194
	v_cmp_lt_i32_e32 vcc, v195, v208
	s_waitcnt vmcnt(0)
	v_lshlrev_b32_e32 v206, 16, v196
	v_and_b32_e32 v207, 0xffff0000, v196
	v_lshlrev_b32_e32 v210, 16, v200
	v_and_b32_e32 v211, 0xffff0000, v200
	v_lshlrev_b32_e32 v196, 16, v197
	v_and_b32_e32 v197, 0xffff0000, v197
	v_lshlrev_b32_e32 v212, 16, v202
	v_and_b32_e32 v213, 0xffff0000, v202
	v_lshlrev_b32_e32 v202, 16, v203
	v_and_b32_e32 v203, 0xffff0000, v203
	v_pk_add_f32 v[126:127], v[126:127], v[206:207]
	v_pk_add_f32 v[118:119], v[118:119], v[210:211]
	v_lshlrev_b32_e32 v200, 16, v201
	v_and_b32_e32 v201, 0xffff0000, v201
	v_pk_add_f32 v[128:129], v[128:129], v[196:197]
	v_pk_add_f32 v[196:197], v[116:117], v[202:203]
	v_mul_f32_e32 v116, v127, v127
	v_mul_f32_e32 v117, v119, v119
	v_cndmask_b32_e32 v195, v194, v195, vcc
	v_cmp_lt_i32_e32 vcc, v209, v208
	v_pk_add_f32 v[120:121], v[120:121], v[200:201]
	v_fmac_f32_e32 v116, v126, v126
	v_fmac_f32_e32 v117, v118, v118
	v_cndmask_b32_e32 v214, v194, v209, vcc
	v_lshlrev_b32_e32 v208, 16, v198
	v_and_b32_e32 v209, 0xffff0000, v198
	v_lshlrev_b32_e32 v198, 16, v199
	v_and_b32_e32 v199, 0xffff0000, v199
	v_fmac_f32_e32 v116, v128, v128
	v_fmac_f32_e32 v117, v120, v120
	v_pk_add_f32 v[124:125], v[124:125], v[198:199]
	v_pk_add_f32 v[122:123], v[122:123], v[208:209]
	v_pk_add_f32 v[198:199], v[114:115], v[212:213]
	v_fmac_f32_e32 v116, v129, v129
	v_fmac_f32_e32 v117, v121, v121
	v_fmac_f32_e32 v116, v122, v122
	v_fmac_f32_e32 v117, v198, v198
	v_fmac_f32_e32 v116, v123, v123
	v_fmac_f32_e32 v117, v199, v199
	v_fmac_f32_e32 v116, v124, v124
	v_fmac_f32_e32 v117, v196, v196
	v_fmac_f32_e32 v116, v125, v125
	v_fmac_f32_e32 v117, v197, v197
	v_lshlrev_b32_e32 v195, 2, v195
	v_cvt_pk_bf16_f32 v114, v126, v127
	v_add_f32_e32 v126, v116, v117
	ds_bpermute_b32 v127, v195, v126
	v_cvt_pk_bf16_f32 v115, v128, v129
	v_cvt_pk_bf16_f32 v116, v122, v123
	v_cvt_pk_bf16_f32 v117, v124, v125
	global_store_dwordx4 v[204:205], v[114:117], off
	v_cvt_pk_bf16_f32 v118, v118, v119
	v_cvt_pk_bf16_f32 v119, v120, v121
	s_waitcnt lgkmcnt(0)
	v_add_f32_e32 v115, v126, v127
	v_lshlrev_b32_e32 v114, 2, v214
	ds_bpermute_b32 v116, v114, v115
	v_cvt_pk_bf16_f32 v120, v198, v199
	v_cvt_pk_bf16_f32 v121, v196, v197
	global_store_dwordx4 v[204:205], v[118:121], off offset:256
	s_and_saveexec_b64 s[20:21], s[2:3]
	s_cbranch_execz .LBB0_589
	s_waitcnt lgkmcnt(0)
	v_add_f32_e32 v115, v115, v116
	v_lshl_add_u64 v[116:117], v[174:175], 2, s[6:7]
	global_atomic_add_f32 v[116:117], v115, off

.LBB0_661:
	s_ashr_i32 s13, s12, 31
	s_lshl_b64 s[0:1], s[12:13], 19
	v_cmp_lt_i64_e32 vcc, s[14:15], v[142:143]
	s_add_u32 s14, s68, s0
	s_addc_u32 s15, s69, s1
	s_and_b64 s[0:1], vcc, exec
	s_cselect_b32 s0, s15, s21
	s_cselect_b32 s1, s14, s20
	s_ashr_i32 s9, s8, 31
	s_lshl_b64 s[16:17], s[8:9], 19
	s_add_u32 s16, s28, s16
	s_addc_u32 s17, s29, s17
	s_and_b64 s[24:25], vcc, exec
	s_cselect_b32 s9, s17, s23
	s_cselect_b32 s13, s16, s22
	s_add_u32 s20, s20, 0x40080
	s_addc_u32 s21, s21, 0
	s_add_u32 s45, s22, 0x100
	s_addc_u32 s46, s23, 0
	s_mov_b32 s47, -2
	ds_read_b128 v[146:149], v156
	ds_read_b128 v[160:163], v156 offset:1024
	ds_read_b128 v[164:167], v156 offset:2048
	ds_read_b128 v[168:171], v156 offset:3072
	s_add_u32 s22, s20, 0xfffc0080
	s_addc_u32 s23, s21, -1
	s_cmp_eq_u32 s47, 12
	s_cselect_b32 s25, s0, s23
	s_cselect_b32 s24, s1, s22
	s_cselect_b32 s23, s9, s46
	s_cselect_b32 s22, s13, s45
	v_lshl_add_u64 v[150:151], s[20:21], 0, v[138:139]
	s_add_i32 m0, s19, 0xc000
	ds_read_b128 v[172:175], v157
	ds_read_b128 v[176:179], v157 offset:1024
	ds_read_b128 v[180:183], v157 offset:2048
	ds_read_b128 v[184:187], v157 offset:3072
	ds_read_b128 v[188:191], v157 offset:4096
	ds_read_b128 v[192:195], v157 offset:5120
	ds_read_b128 v[196:199], v157 offset:6144
	ds_read_b128 v[200:203], v157 offset:7168
	global_load_lds_dwordx4 v[150:151], off
	v_lshl_add_u64 v[150:151], s[20:21], 0, v[140:141]
	s_add_i32 m0, s19, 0xe000
	s_nop 0
	global_load_lds_dwordx4 v[150:151], off
	s_waitcnt lgkmcnt(8)
	s_barrier
	s_waitcnt lgkmcnt(0)
	s_setprio 1
	s_waitcnt lgkmcnt(0)
	v_mfma_f32_16x16x32_bf16 v[126:129], v[146:149], v[172:175], 0
	v_mfma_f32_16x16x32_bf16 v[122:125], v[164:167], v[172:175], 0
	v_mfma_f32_16x16x32_bf16 v[110:113], v[146:149], v[180:183], 0
	v_mfma_f32_16x16x32_bf16 v[106:109], v[164:167], v[180:183], 0
	v_mfma_f32_16x16x32_bf16 v[94:97], v[146:149], v[188:191], 0
	v_mfma_f32_16x16x32_bf16 v[90:93], v[164:167], v[188:191], 0
	v_mfma_f32_16x16x32_bf16 v[78:81], v[146:149], v[196:199], 0
	v_mfma_f32_16x16x32_bf16 v[74:77], v[164:167], v[196:199], 0
	v_mfma_f32_16x16x32_bf16 v[126:129], v[160:163], v[176:179], v[126:129]
	v_mfma_f32_16x16x32_bf16 v[122:125], v[168:171], v[176:179], v[122:125]
	v_mfma_f32_16x16x32_bf16 v[110:113], v[160:163], v[184:187], v[110:113]
	v_mfma_f32_16x16x32_bf16 v[106:109], v[168:171], v[184:187], v[106:109]
	v_mfma_f32_16x16x32_bf16 v[94:97], v[160:163], v[192:195], v[94:97]
	v_mfma_f32_16x16x32_bf16 v[90:93], v[168:171], v[192:195], v[90:93]
	v_mfma_f32_16x16x32_bf16 v[78:81], v[160:163], v[200:203], v[78:81]
	v_mfma_f32_16x16x32_bf16 v[74:77], v[168:171], v[200:203], v[74:77]
	s_setprio 0
	s_barrier
	s_add_i32 s48, s39, s27
	v_lshl_add_u64 v[150:151], s[22:23], 0, v[134:135]
	s_mov_b32 m0, s48
	ds_read_b128 v[204:207], v158
	ds_read_b128 v[208:211], v158 offset:1024
	ds_read_b128 v[212:215], v158 offset:2048
	ds_read_b128 v[216:219], v158 offset:3072
	global_load_lds_dwordx4 v[150:151], off
	v_lshl_add_u64 v[220:221], s[22:23], 0, v[130:131]
	s_add_i32 m0, s48, 0x2000
	s_nop 0
	global_load_lds_dwordx4 v[220:221], off
	s_barrier
	s_waitcnt lgkmcnt(0)
	s_setprio 1
	s_waitcnt lgkmcnt(0)
	v_mfma_f32_16x16x32_bf16 v[118:121], v[204:207], v[172:175], 0
	v_mfma_f32_16x16x32_bf16 v[114:117], v[212:215], v[172:175], 0
	v_mfma_f32_16x16x32_bf16 v[102:105], v[204:207], v[180:183], 0
	v_mfma_f32_16x16x32_bf16 v[98:101], v[212:215], v[180:183], 0
	v_mfma_f32_16x16x32_bf16 v[86:89], v[204:207], v[188:191], 0
	v_mfma_f32_16x16x32_bf16 v[82:85], v[212:215], v[188:191], 0
	v_mfma_f32_16x16x32_bf16 v[70:73], v[204:207], v[196:199], 0
	v_mfma_f32_16x16x32_bf16 v[66:69], v[212:215], v[196:199], 0
	v_mfma_f32_16x16x32_bf16 v[118:121], v[208:211], v[176:179], v[118:121]
	v_mfma_f32_16x16x32_bf16 v[114:117], v[216:219], v[176:179], v[114:117]
	v_mfma_f32_16x16x32_bf16 v[102:105], v[208:211], v[184:187], v[102:105]
	v_mfma_f32_16x16x32_bf16 v[98:101], v[216:219], v[184:187], v[98:101]
	v_mfma_f32_16x16x32_bf16 v[86:89], v[208:211], v[192:195], v[86:89]
	v_mfma_f32_16x16x32_bf16 v[82:85], v[216:219], v[192:195], v[82:85]
	v_mfma_f32_16x16x32_bf16 v[70:73], v[208:211], v[200:203], v[70:73]
	v_mfma_f32_16x16x32_bf16 v[66:69], v[216:219], v[200:203], v[66:69]
	s_setprio 0
	s_mov_b32 m0, s19
	v_lshl_add_u64 v[222:223], s[24:25], 0, v[136:137]
	s_barrier
	ds_read_b128 v[172:175], v157 offset:16384
	ds_read_b128 v[176:179], v157 offset:17408
	ds_read_b128 v[180:183], v157 offset:18432
	ds_read_b128 v[184:187], v157 offset:19456
	ds_read_b128 v[188:191], v157 offset:20480
	ds_read_b128 v[192:195], v157 offset:21504
	ds_read_b128 v[196:199], v157 offset:22528
	ds_read_b128 v[200:203], v157 offset:23552
	global_load_lds_dwordx4 v[222:223], off
	v_lshl_add_u64 v[224:225], s[24:25], 0, v[132:133]
	s_mov_b32 m0, s33
	s_nop 0
	global_load_lds_dwordx4 v[224:225], off
	s_barrier
	s_waitcnt lgkmcnt(0)
	s_setprio 1
	s_waitcnt lgkmcnt(0)
	v_mfma_f32_16x16x32_bf16 v[62:65], v[146:149], v[172:175], 0
	v_mfma_f32_16x16x32_bf16 v[58:61], v[164:167], v[172:175], 0
	v_mfma_f32_16x16x32_bf16 v[46:49], v[146:149], v[180:183], 0
	v_mfma_f32_16x16x32_bf16 v[42:45], v[164:167], v[180:183], 0
	v_mfma_f32_16x16x32_bf16 v[30:33], v[146:149], v[188:191], 0
	v_mfma_f32_16x16x32_bf16 v[26:29], v[164:167], v[188:191], 0
	v_mfma_f32_16x16x32_bf16 v[14:17], v[146:149], v[196:199], 0
	v_mfma_f32_16x16x32_bf16 v[10:13], v[164:167], v[196:199], 0
	v_mfma_f32_16x16x32_bf16 v[62:65], v[160:163], v[176:179], v[62:65]
	v_mfma_f32_16x16x32_bf16 v[58:61], v[168:171], v[176:179], v[58:61]
	v_mfma_f32_16x16x32_bf16 v[46:49], v[160:163], v[184:187], v[46:49]
	v_mfma_f32_16x16x32_bf16 v[42:45], v[168:171], v[184:187], v[42:45]
	v_mfma_f32_16x16x32_bf16 v[30:33], v[160:163], v[192:195], v[30:33]
	v_mfma_f32_16x16x32_bf16 v[26:29], v[168:171], v[192:195], v[26:29]
	v_mfma_f32_16x16x32_bf16 v[14:17], v[160:163], v[200:203], v[14:17]
	v_mfma_f32_16x16x32_bf16 v[10:13], v[168:171], v[200:203], v[10:13]
	s_setprio 0
	s_barrier
	s_add_u32 s48, s22, 0x40000
	s_addc_u32 s49, s23, 0
	s_add_i32 s50, s40, s27
	v_lshl_add_u64 v[146:147], s[48:49], 0, v[134:135]
	s_mov_b32 m0, s50
	s_nop 0
	global_load_lds_dwordx4 v[146:147], off
	v_lshl_add_u64 v[146:147], s[48:49], 0, v[130:131]
	s_add_i32 m0, s50, 0x2000
	s_nop 0
	global_load_lds_dwordx4 v[146:147], off
	s_waitcnt vmcnt(6)
	s_barrier
	s_setprio 1
	v_mfma_f32_16x16x32_bf16 v[54:57], v[204:207], v[172:175], 0
	v_mfma_f32_16x16x32_bf16 v[50:53], v[212:215], v[172:175], 0
	v_mfma_f32_16x16x32_bf16 v[38:41], v[204:207], v[180:183], 0
	v_mfma_f32_16x16x32_bf16 v[34:37], v[212:215], v[180:183], 0
	v_mfma_f32_16x16x32_bf16 v[22:25], v[204:207], v[188:191], 0
	v_mfma_f32_16x16x32_bf16 v[18:21], v[212:215], v[188:191], 0
	v_mfma_f32_16x16x32_bf16 v[6:9], v[204:207], v[196:199], 0
	v_mfma_f32_16x16x32_bf16 v[2:5], v[212:215], v[196:199], 0
	v_mfma_f32_16x16x32_bf16 v[54:57], v[208:211], v[176:179], v[54:57]
	v_mfma_f32_16x16x32_bf16 v[50:53], v[216:219], v[176:179], v[50:53]
	v_mfma_f32_16x16x32_bf16 v[38:41], v[208:211], v[184:187], v[38:41]
	v_mfma_f32_16x16x32_bf16 v[34:37], v[216:219], v[184:187], v[34:37]
	v_mfma_f32_16x16x32_bf16 v[22:25], v[208:211], v[192:195], v[22:25]
	v_mfma_f32_16x16x32_bf16 v[18:21], v[216:219], v[192:195], v[18:21]
	v_mfma_f32_16x16x32_bf16 v[6:9], v[208:211], v[200:203], v[6:9]
	v_mfma_f32_16x16x32_bf16 v[2:5], v[216:219], v[200:203], v[2:5]
	s_setprio 0
	s_add_i32 s48, 0, 0x18000
	v_add_u32_e32 v159, s48, v153
	s_barrier
	ds_read_b128 v[146:149], v159
	ds_read_b128 v[160:163], v159 offset:1024
	ds_read_b128 v[164:167], v159 offset:2048
	ds_read_b128 v[168:171], v159 offset:3072
	s_add_u32 s24, s24, 0x40000
	s_addc_u32 s25, s25, 0
	s_mov_b32 m0, s34
	v_lshl_add_u64 v[204:205], s[24:25], 0, v[136:137]
	ds_read_b128 v[172:175], v157 offset:32768
	ds_read_b128 v[176:179], v157 offset:33792
	ds_read_b128 v[180:183], v157 offset:34816
	ds_read_b128 v[184:187], v157 offset:35840
	ds_read_b128 v[188:191], v157 offset:36864
	ds_read_b128 v[192:195], v157 offset:37888
	ds_read_b128 v[196:199], v157 offset:38912
	ds_read_b128 v[200:203], v157 offset:39936
	global_load_lds_dwordx4 v[204:205], off
	v_lshl_add_u64 v[204:205], s[24:25], 0, v[132:133]
	s_mov_b32 m0, s35
	s_nop 0
	global_load_lds_dwordx4 v[204:205], off
	s_waitcnt lgkmcnt(8)
	s_barrier
	s_waitcnt lgkmcnt(0)
	s_setprio 1
	s_waitcnt lgkmcnt(0)
	v_mfma_f32_16x16x32_bf16 v[126:129], v[146:149], v[172:175], v[126:129]
	v_mfma_f32_16x16x32_bf16 v[122:125], v[164:167], v[172:175], v[122:125]
	v_mfma_f32_16x16x32_bf16 v[110:113], v[146:149], v[180:183], v[110:113]
	v_mfma_f32_16x16x32_bf16 v[106:109], v[164:167], v[180:183], v[106:109]
	v_mfma_f32_16x16x32_bf16 v[94:97], v[146:149], v[188:191], v[94:97]
	v_mfma_f32_16x16x32_bf16 v[90:93], v[164:167], v[188:191], v[90:93]
	v_mfma_f32_16x16x32_bf16 v[78:81], v[146:149], v[196:199], v[78:81]
	v_mfma_f32_16x16x32_bf16 v[74:77], v[164:167], v[196:199], v[74:77]
	v_mfma_f32_16x16x32_bf16 v[126:129], v[160:163], v[176:179], v[126:129]
	v_mfma_f32_16x16x32_bf16 v[122:125], v[168:171], v[176:179], v[122:125]
	v_mfma_f32_16x16x32_bf16 v[110:113], v[160:163], v[184:187], v[110:113]
	v_mfma_f32_16x16x32_bf16 v[106:109], v[168:171], v[184:187], v[106:109]
	v_mfma_f32_16x16x32_bf16 v[94:97], v[160:163], v[192:195], v[94:97]
	v_mfma_f32_16x16x32_bf16 v[90:93], v[168:171], v[192:195], v[90:93]
	v_mfma_f32_16x16x32_bf16 v[78:81], v[160:163], v[200:203], v[78:81]
	v_mfma_f32_16x16x32_bf16 v[74:77], v[168:171], v[200:203], v[74:77]
	s_setprio 0
	s_barrier
	s_add_i32 s24, 0, 0x1c000
	s_add_i32 s25, s48, s27
	v_add_u32_e32 v159, s24, v153
	v_lshl_add_u64 v[150:151], v[150:151], 0, s[6:7]
	s_mov_b32 m0, s25
	ds_read_b128 v[204:207], v159
	ds_read_b128 v[208:211], v159 offset:1024
	ds_read_b128 v[212:215], v159 offset:2048
	ds_read_b128 v[216:219], v159 offset:3072
	global_load_lds_dwordx4 v[150:151], off
	v_lshl_add_u64 v[150:151], v[220:221], 0, s[6:7]
	s_add_i32 m0, s25, 0x2000
	s_nop 0
	global_load_lds_dwordx4 v[150:151], off
	s_barrier
	s_waitcnt lgkmcnt(0)
	s_setprio 1
	s_waitcnt lgkmcnt(0)
	v_mfma_f32_16x16x32_bf16 v[118:121], v[204:207], v[172:175], v[118:121]
	v_mfma_f32_16x16x32_bf16 v[114:117], v[212:215], v[172:175], v[114:117]
	v_mfma_f32_16x16x32_bf16 v[102:105], v[204:207], v[180:183], v[102:105]
	v_mfma_f32_16x16x32_bf16 v[98:101], v[212:215], v[180:183], v[98:101]
	v_mfma_f32_16x16x32_bf16 v[86:89], v[204:207], v[188:191], v[86:89]
	v_mfma_f32_16x16x32_bf16 v[82:85], v[212:215], v[188:191], v[82:85]
	v_mfma_f32_16x16x32_bf16 v[70:73], v[204:207], v[196:199], v[70:73]
	v_mfma_f32_16x16x32_bf16 v[66:69], v[212:215], v[196:199], v[66:69]
	v_mfma_f32_16x16x32_bf16 v[118:121], v[208:211], v[176:179], v[118:121]
	v_mfma_f32_16x16x32_bf16 v[114:117], v[216:219], v[176:179], v[114:117]
	v_mfma_f32_16x16x32_bf16 v[102:105], v[208:211], v[184:187], v[102:105]
	v_mfma_f32_16x16x32_bf16 v[98:101], v[216:219], v[184:187], v[98:101]
	v_mfma_f32_16x16x32_bf16 v[86:89], v[208:211], v[192:195], v[86:89]
	v_mfma_f32_16x16x32_bf16 v[82:85], v[216:219], v[192:195], v[82:85]
	v_mfma_f32_16x16x32_bf16 v[70:73], v[208:211], v[200:203], v[70:73]
	v_mfma_f32_16x16x32_bf16 v[66:69], v[216:219], v[200:203], v[66:69]
	s_setprio 0
	s_mov_b32 m0, s36
	v_lshl_add_u64 v[150:151], v[222:223], 0, s[6:7]
	s_barrier
	ds_read_b128 v[172:175], v157 offset:49152
	ds_read_b128 v[176:179], v157 offset:50176
	ds_read_b128 v[180:183], v157 offset:51200
	ds_read_b128 v[184:187], v157 offset:52224
	ds_read_b128 v[188:191], v157 offset:53248
	ds_read_b128 v[192:195], v157 offset:54272
	ds_read_b128 v[196:199], v157 offset:55296
	ds_read_b128 v[200:203], v157 offset:56320
	global_load_lds_dwordx4 v[150:151], off
	v_lshl_add_u64 v[150:151], v[224:225], 0, s[6:7]
	s_mov_b32 m0, s37
	s_nop 0
	global_load_lds_dwordx4 v[150:151], off
	s_barrier
	s_waitcnt lgkmcnt(0)
	s_setprio 1
	s_waitcnt lgkmcnt(0)
	v_mfma_f32_16x16x32_bf16 v[62:65], v[146:149], v[172:175], v[62:65]
	v_mfma_f32_16x16x32_bf16 v[58:61], v[164:167], v[172:175], v[58:61]
	v_mfma_f32_16x16x32_bf16 v[46:49], v[146:149], v[180:183], v[46:49]
	v_mfma_f32_16x16x32_bf16 v[42:45], v[164:167], v[180:183], v[42:45]
	v_mfma_f32_16x16x32_bf16 v[30:33], v[146:149], v[188:191], v[30:33]
	v_mfma_f32_16x16x32_bf16 v[26:29], v[164:167], v[188:191], v[26:29]
	v_mfma_f32_16x16x32_bf16 v[14:17], v[146:149], v[196:199], v[14:17]
	v_mfma_f32_16x16x32_bf16 v[10:13], v[164:167], v[196:199], v[10:13]
	v_mfma_f32_16x16x32_bf16 v[62:65], v[160:163], v[176:179], v[62:65]
	v_mfma_f32_16x16x32_bf16 v[58:61], v[168:171], v[176:179], v[58:61]
	v_mfma_f32_16x16x32_bf16 v[46:49], v[160:163], v[184:187], v[46:49]
	v_mfma_f32_16x16x32_bf16 v[42:45], v[168:171], v[184:187], v[42:45]
	v_mfma_f32_16x16x32_bf16 v[30:33], v[160:163], v[192:195], v[30:33]
	v_mfma_f32_16x16x32_bf16 v[26:29], v[168:171], v[192:195], v[26:29]
	v_mfma_f32_16x16x32_bf16 v[14:17], v[160:163], v[200:203], v[14:17]
	v_mfma_f32_16x16x32_bf16 v[10:13], v[168:171], v[200:203], v[10:13]
	s_setprio 0
	s_barrier
	s_add_u32 s22, s22, 0x40080
	s_addc_u32 s23, s23, 0
	s_add_i32 s24, s24, s27
	v_lshl_add_u64 v[146:147], s[22:23], 0, v[134:135]
	s_mov_b32 m0, s24
	s_nop 0
	global_load_lds_dwordx4 v[146:147], off
	v_lshl_add_u64 v[146:147], s[22:23], 0, v[130:131]
	s_add_i32 m0, s24, 0x2000
	s_nop 0
	global_load_lds_dwordx4 v[146:147], off
	s_waitcnt vmcnt(6)
	s_barrier
	s_setprio 1
	v_mfma_f32_16x16x32_bf16 v[54:57], v[204:207], v[172:175], v[54:57]
	v_mfma_f32_16x16x32_bf16 v[50:53], v[212:215], v[172:175], v[50:53]
	v_mfma_f32_16x16x32_bf16 v[38:41], v[204:207], v[180:183], v[38:41]
	v_mfma_f32_16x16x32_bf16 v[34:37], v[212:215], v[180:183], v[34:37]
	v_mfma_f32_16x16x32_bf16 v[22:25], v[204:207], v[188:191], v[22:25]
	v_mfma_f32_16x16x32_bf16 v[18:21], v[212:215], v[188:191], v[18:21]
	v_mfma_f32_16x16x32_bf16 v[6:9], v[204:207], v[196:199], v[6:9]
	v_mfma_f32_16x16x32_bf16 v[2:5], v[212:215], v[196:199], v[2:5]
	v_mfma_f32_16x16x32_bf16 v[54:57], v[208:211], v[176:179], v[54:57]
	v_mfma_f32_16x16x32_bf16 v[50:53], v[216:219], v[176:179], v[50:53]
	v_mfma_f32_16x16x32_bf16 v[38:41], v[208:211], v[184:187], v[38:41]
	v_mfma_f32_16x16x32_bf16 v[34:37], v[216:219], v[184:187], v[34:37]
	v_mfma_f32_16x16x32_bf16 v[22:25], v[208:211], v[192:195], v[22:25]
	v_mfma_f32_16x16x32_bf16 v[18:21], v[216:219], v[192:195], v[18:21]
	v_mfma_f32_16x16x32_bf16 v[6:9], v[208:211], v[200:203], v[6:9]
	v_mfma_f32_16x16x32_bf16 v[2:5], v[216:219], v[200:203], v[2:5]
	s_setprio 0
	s_add_i32 s47, s47, 2
	s_add_u32 s20, s20, 0x100
	s_addc_u32 s21, s21, 0
	s_add_u32 s45, s45, 0x100
	s_addc_u32 s46, s46, 0
	s_cmp_gt_u32 s47, 13
	s_barrier
	s_cbranch_scc1 .Lgemm_epi4

.Lgemm_epi4:
	v_lshl_add_u32 v146, s43, 10, v154
	ds_read2_b32 v[160:161], v146 offset1:16
	ds_read2_b32 v[150:151], v146 offset0:32 offset1:48
	ds_read2_b32 v[148:149], v146 offset0:128 offset1:144
	ds_read2_b32 v[146:147], v146 offset0:160 offset1:176
	v_lshl_or_b32 v162, s44, 7, v155
	s_waitcnt lgkmcnt(0)
	v_pk_mul_f32 v[126:127], v[126:127], v[160:161] op_sel_hi:[1,0]
	v_pk_mul_f32 v[128:129], v[128:129], v[160:161] op_sel_hi:[1,0]
	v_mul_f32_e32 v163, 0xbfb8aa3b, v126
	v_mul_f32_e32 v165, 0xbfb8aa3b, v127
	v_exp_f32_e32 v164, v163
	v_exp_f32_e32 v165, v165
	v_mul_f32_e32 v166, 0xbfb8aa3b, v128
	v_mul_f32_e32 v167, 0xbfb8aa3b, v129
	v_exp_f32_e32 v166, v166
	v_exp_f32_e32 v167, v167
	v_add_f32_e32 v164, 1.0, v164
	v_add_f32_e32 v165, 1.0, v165
	v_rcp_f32_e32 v164, v164
	v_rcp_f32_e32 v165, v165
	v_add_f32_e32 v166, 1.0, v166
	v_add_f32_e32 v167, 1.0, v167
	v_rcp_f32_e32 v166, v166
	v_rcp_f32_e32 v167, v167
	v_pk_mul_f32 v[118:119], v[118:119], v[160:161] op_sel_hi:[1,0]
	v_pk_mul_f32 v[126:127], v[126:127], v[164:165]
	v_pk_mul_f32 v[122:123], v[122:123], v[160:161] op_sel_hi:[1,0]
	v_pk_mul_f32 v[118:119], v[118:119], v[126:127]
	v_pk_mul_f32 v[126:127], v[128:129], v[166:167]
	v_mul_f32_e32 v128, 0xbfb8aa3b, v122
	v_exp_f32_e32 v128, v128
	v_pk_mul_f32 v[120:121], v[120:121], v[160:161] op_sel_hi:[1,0]
	v_pk_mul_f32 v[124:125], v[124:125], v[160:161] op_sel_hi:[1,0]
	v_pk_mul_f32 v[120:121], v[120:121], v[126:127]
	v_mul_f32_e32 v126, 0xbfb8aa3b, v123
	v_exp_f32_e32 v127, v126
	v_add_f32_e32 v126, 1.0, v128
	v_mul_f32_e32 v128, 0xbfb8aa3b, v124
	v_mul_f32_e32 v129, 0xbfb8aa3b, v125
	v_exp_f32_e32 v128, v128
	v_exp_f32_e32 v129, v129
	v_add_f32_e32 v127, 1.0, v127
	v_rcp_f32_e32 v126, v126
	v_rcp_f32_e32 v127, v127
	v_add_f32_e32 v128, 1.0, v128
	v_add_f32_e32 v129, 1.0, v129
	v_rcp_f32_e32 v128, v128
	v_rcp_f32_e32 v129, v129
	v_pk_mul_f32 v[114:115], v[114:115], v[160:161] op_sel_hi:[1,0]
	v_pk_mul_f32 v[122:123], v[122:123], v[126:127]
	v_pk_mul_f32 v[116:117], v[116:117], v[160:161] op_sel_hi:[1,0]
	v_pk_mul_f32 v[114:115], v[114:115], v[122:123]
	v_pk_mul_f32 v[122:123], v[124:125], v[128:129]
	v_mov_b32_e32 v124, v161
	v_pk_mul_f32 v[110:111], v[110:111], v[124:125] op_sel_hi:[1,0]
	v_lshl_add_u32 v159, s18, 8, v152
	v_mul_f32_e32 v125, 0xbfb8aa3b, v110
	v_exp_f32_e32 v125, v125
	v_ashrrev_i32_e32 v163, 31, v162
	v_pk_mul_f32 v[116:117], v[116:117], v[122:123]
	v_cvt_pk_bf16_f32 v118, v118, v119
	v_cvt_pk_bf16_f32 v119, v120, v121
	v_cvt_pk_bf16_f32 v120, v114, v115
	v_mov_b64_e32 v[114:115], s[4:5]
	v_cvt_pk_bf16_f32 v121, v116, v117
	v_mad_i64_i32 v[122:123], s[0:1], v159, s41, v[114:115]
	v_lshlrev_b64 v[116:117], 1, v[162:163]
	v_lshl_add_u64 v[122:123], v[122:123], 0, v[116:117]
	global_store_dwordx4 v[122:123], v[118:121], off
	v_pk_mul_f32 v[112:113], v[112:113], v[124:125] op_sel_hi:[1,0]
	v_pk_mul_f32 v[102:103], v[102:103], v[124:125] op_sel_hi:[1,0]
	v_mul_f32_e32 v118, 0xbfb8aa3b, v111
	v_exp_f32_e32 v119, v118
	v_mul_f32_e32 v120, 0xbfb8aa3b, v112
	v_mul_f32_e32 v121, 0xbfb8aa3b, v113
	v_exp_f32_e32 v120, v120
	v_exp_f32_e32 v121, v121
	v_add_f32_e32 v118, 1.0, v125
	v_add_f32_e32 v119, 1.0, v119
	v_rcp_f32_e32 v118, v118
	v_rcp_f32_e32 v119, v119
	v_add_f32_e32 v120, 1.0, v120
	v_add_f32_e32 v121, 1.0, v121
	v_rcp_f32_e32 v120, v120
	v_rcp_f32_e32 v121, v121
	v_pk_mul_f32 v[110:111], v[110:111], v[118:119]
	v_pk_mul_f32 v[106:107], v[106:107], v[124:125] op_sel_hi:[1,0]
	v_pk_mul_f32 v[102:103], v[102:103], v[110:111]
	v_pk_mul_f32 v[110:111], v[112:113], v[120:121]
	v_mul_f32_e32 v112, 0xbfb8aa3b, v106
	v_exp_f32_e32 v112, v112
	v_pk_mul_f32 v[104:105], v[104:105], v[124:125] op_sel_hi:[1,0]
	v_pk_mul_f32 v[108:109], v[108:109], v[124:125] op_sel_hi:[1,0]
	v_pk_mul_f32 v[104:105], v[104:105], v[110:111]
	v_mul_f32_e32 v110, 0xbfb8aa3b, v107
	v_exp_f32_e32 v111, v110
	v_add_f32_e32 v110, 1.0, v112
	v_mul_f32_e32 v112, 0xbfb8aa3b, v108
	v_mul_f32_e32 v113, 0xbfb8aa3b, v109
	v_exp_f32_e32 v112, v112
	v_exp_f32_e32 v113, v113
	v_add_f32_e32 v111, 1.0, v111
	v_rcp_f32_e32 v110, v110
	v_rcp_f32_e32 v111, v111
	v_add_f32_e32 v112, 1.0, v112
	v_add_f32_e32 v113, 1.0, v113
	v_rcp_f32_e32 v112, v112
	v_rcp_f32_e32 v113, v113
	v_pk_mul_f32 v[98:99], v[98:99], v[124:125] op_sel_hi:[1,0]
	v_pk_mul_f32 v[106:107], v[106:107], v[110:111]
	v_or_b32_e32 v110, 16, v159
	v_pk_mul_f32 v[106:107], v[98:99], v[106:107]
	v_pk_mul_f32 v[98:99], v[100:101], v[124:125] op_sel_hi:[1,0]
	v_pk_mul_f32 v[100:101], v[108:109], v[112:113]
	v_pk_mul_f32 v[94:95], v[94:95], v[150:151] op_sel_hi:[1,0]
	v_pk_mul_f32 v[108:109], v[98:99], v[100:101]
	v_cvt_pk_bf16_f32 v98, v102, v103
	v_mad_i64_i32 v[102:103], s[0:1], v110, s41, v[114:115]
	v_cvt_pk_bf16_f32 v99, v104, v105
	v_cvt_pk_bf16_f32 v100, v106, v107
	v_cvt_pk_bf16_f32 v101, v108, v109
	v_lshl_add_u64 v[102:103], v[102:103], 0, v[116:117]
	v_mul_f32_e32 v104, 0xbfb8aa3b, v94
	global_store_dwordx4 v[102:103], v[98:101], off
	v_pk_mul_f32 v[96:97], v[96:97], v[150:151] op_sel_hi:[1,0]
	v_exp_f32_e32 v104, v104
	v_mul_f32_e32 v98, 0xbfb8aa3b, v95
	v_exp_f32_e32 v99, v98
	v_mul_f32_e32 v100, 0xbfb8aa3b, v96
	v_mul_f32_e32 v101, 0xbfb8aa3b, v97
	v_exp_f32_e32 v100, v100
	v_exp_f32_e32 v101, v101
	v_add_f32_e32 v98, 1.0, v104
	v_add_f32_e32 v99, 1.0, v99
	v_rcp_f32_e32 v98, v98
	v_rcp_f32_e32 v99, v99
	v_add_f32_e32 v100, 1.0, v100
	v_add_f32_e32 v101, 1.0, v101
	v_rcp_f32_e32 v100, v100
	v_rcp_f32_e32 v101, v101
	v_pk_mul_f32 v[86:87], v[86:87], v[150:151] op_sel_hi:[1,0]
	v_pk_mul_f32 v[94:95], v[94:95], v[98:99]
	v_pk_mul_f32 v[90:91], v[90:91], v[150:151] op_sel_hi:[1,0]
	v_pk_mul_f32 v[86:87], v[86:87], v[94:95]
	v_pk_mul_f32 v[94:95], v[96:97], v[100:101]
	v_mul_f32_e32 v96, 0xbfb8aa3b, v90
	v_exp_f32_e32 v96, v96
	v_pk_mul_f32 v[88:89], v[88:89], v[150:151] op_sel_hi:[1,0]
	v_pk_mul_f32 v[92:93], v[92:93], v[150:151] op_sel_hi:[1,0]
	v_pk_mul_f32 v[88:89], v[88:89], v[94:95]
	v_mul_f32_e32 v94, 0xbfb8aa3b, v91
	v_exp_f32_e32 v95, v94
	v_add_f32_e32 v94, 1.0, v96
	v_mul_f32_e32 v96, 0xbfb8aa3b, v92
	v_mul_f32_e32 v97, 0xbfb8aa3b, v93
	v_exp_f32_e32 v96, v96
	v_exp_f32_e32 v97, v97
	v_add_f32_e32 v95, 1.0, v95
	v_rcp_f32_e32 v94, v94
	v_rcp_f32_e32 v95, v95
	v_add_f32_e32 v96, 1.0, v96
	v_add_f32_e32 v97, 1.0, v97
	v_rcp_f32_e32 v96, v96
	v_rcp_f32_e32 v97, v97
	v_pk_mul_f32 v[82:83], v[82:83], v[150:151] op_sel_hi:[1,0]
	v_pk_mul_f32 v[90:91], v[90:91], v[94:95]
	v_or_b32_e32 v94, 32, v159
	v_pk_mul_f32 v[90:91], v[82:83], v[90:91]
	v_pk_mul_f32 v[82:83], v[84:85], v[150:151] op_sel_hi:[1,0]
	v_pk_mul_f32 v[84:85], v[92:93], v[96:97]
	v_pk_mul_f32 v[62:63], v[62:63], v[148:149] op_sel_hi:[1,0]
	v_pk_mul_f32 v[92:93], v[82:83], v[84:85]
	v_cvt_pk_bf16_f32 v83, v88, v89
	v_mov_b32_e32 v88, v151
	v_pk_mul_f32 v[78:79], v[78:79], v[88:89] op_sel_hi:[1,0]
	v_cvt_pk_bf16_f32 v82, v86, v87
	v_mul_f32_e32 v89, 0xbfb8aa3b, v78
	v_exp_f32_e32 v89, v89
	v_mad_i64_i32 v[86:87], s[0:1], v94, s41, v[114:115]
	v_cvt_pk_bf16_f32 v84, v90, v91
	v_cvt_pk_bf16_f32 v85, v92, v93
	v_lshl_add_u64 v[86:87], v[86:87], 0, v[116:117]
	global_store_dwordx4 v[86:87], v[82:85], off
	v_pk_mul_f32 v[80:81], v[80:81], v[88:89] op_sel_hi:[1,0]
	v_pk_mul_f32 v[70:71], v[70:71], v[88:89] op_sel_hi:[1,0]
	v_mul_f32_e32 v82, 0xbfb8aa3b, v79
	v_exp_f32_e32 v83, v82
	v_mul_f32_e32 v84, 0xbfb8aa3b, v80
	v_mul_f32_e32 v85, 0xbfb8aa3b, v81
	v_exp_f32_e32 v84, v84
	v_exp_f32_e32 v85, v85
	v_add_f32_e32 v82, 1.0, v89
	v_add_f32_e32 v83, 1.0, v83
	v_rcp_f32_e32 v82, v82
	v_rcp_f32_e32 v83, v83
	v_add_f32_e32 v84, 1.0, v84
	v_add_f32_e32 v85, 1.0, v85
	v_rcp_f32_e32 v84, v84
	v_rcp_f32_e32 v85, v85
	v_pk_mul_f32 v[78:79], v[78:79], v[82:83]
	v_pk_mul_f32 v[74:75], v[74:75], v[88:89] op_sel_hi:[1,0]
	v_pk_mul_f32 v[70:71], v[70:71], v[78:79]
	v_pk_mul_f32 v[78:79], v[80:81], v[84:85]
	v_mul_f32_e32 v80, 0xbfb8aa3b, v74
	v_exp_f32_e32 v80, v80
	v_pk_mul_f32 v[72:73], v[72:73], v[88:89] op_sel_hi:[1,0]
	v_pk_mul_f32 v[76:77], v[76:77], v[88:89] op_sel_hi:[1,0]
	v_pk_mul_f32 v[72:73], v[72:73], v[78:79]
	v_mul_f32_e32 v78, 0xbfb8aa3b, v75
	v_exp_f32_e32 v79, v78
	v_add_f32_e32 v78, 1.0, v80
	v_mul_f32_e32 v80, 0xbfb8aa3b, v76
	v_mul_f32_e32 v81, 0xbfb8aa3b, v77
	v_exp_f32_e32 v80, v80
	v_exp_f32_e32 v81, v81
	v_add_f32_e32 v79, 1.0, v79
	v_rcp_f32_e32 v78, v78
	v_rcp_f32_e32 v79, v79
	v_add_f32_e32 v80, 1.0, v80
	v_add_f32_e32 v81, 1.0, v81
	v_rcp_f32_e32 v80, v80
	v_rcp_f32_e32 v81, v81
	v_pk_mul_f32 v[66:67], v[66:67], v[88:89] op_sel_hi:[1,0]
	v_pk_mul_f32 v[74:75], v[74:75], v[78:79]
	v_or_b32_e32 v78, 48, v159
	v_pk_mul_f32 v[74:75], v[66:67], v[74:75]
	v_pk_mul_f32 v[66:67], v[68:69], v[88:89] op_sel_hi:[1,0]
	v_pk_mul_f32 v[68:69], v[76:77], v[80:81]
	v_pk_mul_f32 v[64:65], v[64:65], v[148:149] op_sel_hi:[1,0]
	v_pk_mul_f32 v[76:77], v[66:67], v[68:69]
	v_cvt_pk_bf16_f32 v66, v70, v71
	v_mad_i64_i32 v[70:71], s[0:1], v78, s41, v[114:115]
	v_cvt_pk_bf16_f32 v67, v72, v73
	v_cvt_pk_bf16_f32 v68, v74, v75
	v_cvt_pk_bf16_f32 v69, v76, v77
	v_lshl_add_u64 v[70:71], v[70:71], 0, v[116:117]
	global_store_dwordx4 v[70:71], v[66:69], off
	v_pk_mul_f32 v[54:55], v[54:55], v[148:149] op_sel_hi:[1,0]
	v_pk_mul_f32 v[58:59], v[58:59], v[148:149] op_sel_hi:[1,0]
	v_mul_f32_e32 v66, 0xbfb8aa3b, v62
	v_mul_f32_e32 v67, 0xbfb8aa3b, v63
	v_exp_f32_e32 v66, v66
	v_exp_f32_e32 v67, v67
	v_mul_f32_e32 v68, 0xbfb8aa3b, v64
	v_mul_f32_e32 v69, 0xbfb8aa3b, v65
	v_exp_f32_e32 v68, v68
	v_exp_f32_e32 v69, v69
	v_add_f32_e32 v66, 1.0, v66
	v_add_f32_e32 v67, 1.0, v67
	v_rcp_f32_e32 v66, v66
	v_rcp_f32_e32 v67, v67
	v_add_f32_e32 v68, 1.0, v68
	v_add_f32_e32 v69, 1.0, v69
	v_rcp_f32_e32 v68, v68
	v_rcp_f32_e32 v69, v69
	v_pk_mul_f32 v[62:63], v[62:63], v[66:67]
	v_pk_mul_f32 v[56:57], v[56:57], v[148:149] op_sel_hi:[1,0]
	v_pk_mul_f32 v[54:55], v[54:55], v[62:63]
	v_pk_mul_f32 v[62:63], v[64:65], v[68:69]
	v_mul_f32_e32 v64, 0xbfb8aa3b, v58
	v_exp_f32_e32 v64, v64
	v_pk_mul_f32 v[56:57], v[56:57], v[62:63]
	v_mul_f32_e32 v62, 0xbfb8aa3b, v59
	v_pk_mul_f32 v[60:61], v[60:61], v[148:149] op_sel_hi:[1,0]
	v_exp_f32_e32 v63, v62
	v_add_f32_e32 v62, 1.0, v64
	v_mul_f32_e32 v64, 0xbfb8aa3b, v60
	v_mul_f32_e32 v65, 0xbfb8aa3b, v61
	v_exp_f32_e32 v64, v64
	v_exp_f32_e32 v65, v65
	v_add_f32_e32 v63, 1.0, v63
	v_rcp_f32_e32 v62, v62
	v_rcp_f32_e32 v63, v63
	v_add_f32_e32 v64, 1.0, v64
	v_add_f32_e32 v65, 1.0, v65
	v_rcp_f32_e32 v64, v64
	v_rcp_f32_e32 v65, v65
	v_pk_mul_f32 v[50:51], v[50:51], v[148:149] op_sel_hi:[1,0]
	v_pk_mul_f32 v[58:59], v[58:59], v[62:63]
	v_add_u32_e32 v70, 0x80, v159
	v_pk_mul_f32 v[58:59], v[50:51], v[58:59]
	v_pk_mul_f32 v[50:51], v[52:53], v[148:149] op_sel_hi:[1,0]
	v_pk_mul_f32 v[52:53], v[60:61], v[64:65]
	v_pk_mul_f32 v[30:31], v[30:31], v[146:147] op_sel_hi:[1,0]
	v_pk_mul_f32 v[60:61], v[50:51], v[52:53]
	v_cvt_pk_bf16_f32 v51, v56, v57
	v_mov_b32_e32 v56, v149
	v_pk_mul_f32 v[46:47], v[46:47], v[56:57] op_sel_hi:[1,0]
	v_cvt_pk_bf16_f32 v50, v54, v55
	v_mul_f32_e32 v57, 0xbfb8aa3b, v46
	v_exp_f32_e32 v57, v57
	v_mad_i64_i32 v[54:55], s[0:1], v70, s41, v[114:115]
	v_cvt_pk_bf16_f32 v52, v58, v59
	v_cvt_pk_bf16_f32 v53, v60, v61
	v_lshl_add_u64 v[54:55], v[54:55], 0, v[116:117]
	global_store_dwordx4 v[54:55], v[50:53], off
	v_pk_mul_f32 v[48:49], v[48:49], v[56:57] op_sel_hi:[1,0]
	v_pk_mul_f32 v[38:39], v[38:39], v[56:57] op_sel_hi:[1,0]
	v_mul_f32_e32 v50, 0xbfb8aa3b, v47
	v_exp_f32_e32 v51, v50
	v_mul_f32_e32 v52, 0xbfb8aa3b, v48
	v_mul_f32_e32 v53, 0xbfb8aa3b, v49
	v_exp_f32_e32 v52, v52
	v_exp_f32_e32 v53, v53
	v_add_f32_e32 v50, 1.0, v57
	v_add_f32_e32 v51, 1.0, v51
	v_rcp_f32_e32 v50, v50
	v_rcp_f32_e32 v51, v51
	v_add_f32_e32 v52, 1.0, v52
	v_add_f32_e32 v53, 1.0, v53
	v_rcp_f32_e32 v52, v52
	v_rcp_f32_e32 v53, v53
	v_pk_mul_f32 v[46:47], v[46:47], v[50:51]
	v_pk_mul_f32 v[42:43], v[42:43], v[56:57] op_sel_hi:[1,0]
	v_pk_mul_f32 v[38:39], v[38:39], v[46:47]
	v_pk_mul_f32 v[46:47], v[48:49], v[52:53]
	v_mul_f32_e32 v48, 0xbfb8aa3b, v42
	v_exp_f32_e32 v48, v48
	v_pk_mul_f32 v[40:41], v[40:41], v[56:57] op_sel_hi:[1,0]
	v_pk_mul_f32 v[44:45], v[44:45], v[56:57] op_sel_hi:[1,0]
	v_pk_mul_f32 v[40:41], v[40:41], v[46:47]
	v_mul_f32_e32 v46, 0xbfb8aa3b, v43
	v_exp_f32_e32 v47, v46
	v_add_f32_e32 v46, 1.0, v48
	v_mul_f32_e32 v48, 0xbfb8aa3b, v44
	v_mul_f32_e32 v49, 0xbfb8aa3b, v45
	v_exp_f32_e32 v48, v48
	v_exp_f32_e32 v49, v49
	v_add_f32_e32 v47, 1.0, v47
	v_rcp_f32_e32 v46, v46
	v_rcp_f32_e32 v47, v47
	v_add_f32_e32 v48, 1.0, v48
	v_add_f32_e32 v49, 1.0, v49
	v_rcp_f32_e32 v48, v48
	v_rcp_f32_e32 v49, v49
	v_pk_mul_f32 v[34:35], v[34:35], v[56:57] op_sel_hi:[1,0]
	v_pk_mul_f32 v[42:43], v[42:43], v[46:47]
	v_add_u32_e32 v46, 0x90, v159
	v_pk_mul_f32 v[42:43], v[34:35], v[42:43]
	v_pk_mul_f32 v[34:35], v[36:37], v[56:57] op_sel_hi:[1,0]
	v_pk_mul_f32 v[36:37], v[44:45], v[48:49]
	v_pk_mul_f32 v[32:33], v[32:33], v[146:147] op_sel_hi:[1,0]
	v_pk_mul_f32 v[44:45], v[34:35], v[36:37]
	v_cvt_pk_bf16_f32 v34, v38, v39
	v_mad_i64_i32 v[38:39], s[0:1], v46, s41, v[114:115]
	v_cvt_pk_bf16_f32 v35, v40, v41
	v_cvt_pk_bf16_f32 v36, v42, v43
	v_cvt_pk_bf16_f32 v37, v44, v45
	v_lshl_add_u64 v[38:39], v[38:39], 0, v[116:117]
	v_mul_f32_e32 v40, 0xbfb8aa3b, v30
	global_store_dwordx4 v[38:39], v[34:37], off
	v_exp_f32_e32 v40, v40
	v_pk_mul_f32 v[22:23], v[22:23], v[146:147] op_sel_hi:[1,0]
	v_mul_f32_e32 v34, 0xbfb8aa3b, v31
	v_exp_f32_e32 v35, v34
	v_mul_f32_e32 v36, 0xbfb8aa3b, v32
	v_mul_f32_e32 v37, 0xbfb8aa3b, v33
	v_exp_f32_e32 v36, v36
	v_exp_f32_e32 v37, v37
	v_add_f32_e32 v34, 1.0, v40
	v_add_f32_e32 v35, 1.0, v35
	v_rcp_f32_e32 v34, v34
	v_rcp_f32_e32 v35, v35
	v_add_f32_e32 v36, 1.0, v36
	v_add_f32_e32 v37, 1.0, v37
	v_rcp_f32_e32 v36, v36
	v_rcp_f32_e32 v37, v37
	v_pk_mul_f32 v[30:31], v[30:31], v[34:35]
	v_pk_mul_f32 v[26:27], v[26:27], v[146:147] op_sel_hi:[1,0]
	v_pk_mul_f32 v[22:23], v[22:23], v[30:31]
	v_pk_mul_f32 v[30:31], v[32:33], v[36:37]
	v_mul_f32_e32 v32, 0xbfb8aa3b, v26
	v_exp_f32_e32 v32, v32
	v_pk_mul_f32 v[24:25], v[24:25], v[146:147] op_sel_hi:[1,0]
	v_pk_mul_f32 v[28:29], v[28:29], v[146:147] op_sel_hi:[1,0]
	v_pk_mul_f32 v[24:25], v[24:25], v[30:31]
	v_mul_f32_e32 v30, 0xbfb8aa3b, v27
	v_exp_f32_e32 v31, v30
	v_add_f32_e32 v30, 1.0, v32
	v_mul_f32_e32 v32, 0xbfb8aa3b, v28
	v_mul_f32_e32 v33, 0xbfb8aa3b, v29
	v_exp_f32_e32 v32, v32
	v_exp_f32_e32 v33, v33
	v_add_f32_e32 v31, 1.0, v31
	v_rcp_f32_e32 v30, v30
	v_rcp_f32_e32 v31, v31
	v_add_f32_e32 v32, 1.0, v32
	v_add_f32_e32 v33, 1.0, v33
	v_rcp_f32_e32 v32, v32
	v_rcp_f32_e32 v33, v33
	v_pk_mul_f32 v[18:19], v[18:19], v[146:147] op_sel_hi:[1,0]
	v_pk_mul_f32 v[26:27], v[26:27], v[30:31]
	v_add_u32_e32 v30, 0xa0, v159
	v_pk_mul_f32 v[26:27], v[18:19], v[26:27]
	v_pk_mul_f32 v[18:19], v[20:21], v[146:147] op_sel_hi:[1,0]
	v_pk_mul_f32 v[20:21], v[28:29], v[32:33]
	s_and_b64 vcc, exec, s[2:3]
	v_pk_mul_f32 v[28:29], v[18:19], v[20:21]
	v_cvt_pk_bf16_f32 v19, v24, v25
	v_mov_b32_e32 v24, v147
	v_pk_mul_f32 v[14:15], v[14:15], v[24:25] op_sel_hi:[1,0]
	v_cvt_pk_bf16_f32 v18, v22, v23
	v_mul_f32_e32 v25, 0xbfb8aa3b, v14
	v_exp_f32_e32 v25, v25
	v_mad_i64_i32 v[22:23], s[0:1], v30, s41, v[114:115]
	v_cvt_pk_bf16_f32 v20, v26, v27
	v_cvt_pk_bf16_f32 v21, v28, v29
	v_lshl_add_u64 v[22:23], v[22:23], 0, v[116:117]
	global_store_dwordx4 v[22:23], v[18:21], off
	v_pk_mul_f32 v[16:17], v[16:17], v[24:25] op_sel_hi:[1,0]
	v_pk_mul_f32 v[6:7], v[6:7], v[24:25] op_sel_hi:[1,0]
	v_mul_f32_e32 v18, 0xbfb8aa3b, v15
	v_exp_f32_e32 v19, v18
	v_mul_f32_e32 v20, 0xbfb8aa3b, v16
	v_mul_f32_e32 v21, 0xbfb8aa3b, v17
	v_exp_f32_e32 v20, v20
	v_exp_f32_e32 v21, v21
	v_add_f32_e32 v18, 1.0, v25
	v_add_f32_e32 v19, 1.0, v19
	v_rcp_f32_e32 v18, v18
	v_rcp_f32_e32 v19, v19
	v_add_f32_e32 v20, 1.0, v20
	v_add_f32_e32 v21, 1.0, v21
	v_rcp_f32_e32 v20, v20
	v_rcp_f32_e32 v21, v21
	v_pk_mul_f32 v[14:15], v[14:15], v[18:19]
	v_pk_mul_f32 v[10:11], v[10:11], v[24:25] op_sel_hi:[1,0]
	v_pk_mul_f32 v[6:7], v[6:7], v[14:15]
	v_pk_mul_f32 v[14:15], v[16:17], v[20:21]
	v_mul_f32_e32 v16, 0xbfb8aa3b, v10
	v_exp_f32_e32 v16, v16
	v_pk_mul_f32 v[8:9], v[8:9], v[24:25] op_sel_hi:[1,0]
	v_pk_mul_f32 v[12:13], v[12:13], v[24:25] op_sel_hi:[1,0]
	v_pk_mul_f32 v[8:9], v[8:9], v[14:15]
	v_mul_f32_e32 v14, 0xbfb8aa3b, v11
	v_exp_f32_e32 v15, v14
	v_add_f32_e32 v14, 1.0, v16
	v_mul_f32_e32 v16, 0xbfb8aa3b, v12
	v_mul_f32_e32 v17, 0xbfb8aa3b, v13
	v_exp_f32_e32 v16, v16
	v_exp_f32_e32 v17, v17
	v_add_f32_e32 v15, 1.0, v15
	v_rcp_f32_e32 v14, v14
	v_rcp_f32_e32 v15, v15
	v_add_f32_e32 v16, 1.0, v16
	v_add_f32_e32 v17, 1.0, v17
	v_rcp_f32_e32 v16, v16
	v_rcp_f32_e32 v17, v17
	v_pk_mul_f32 v[2:3], v[2:3], v[24:25] op_sel_hi:[1,0]
	v_pk_mul_f32 v[10:11], v[10:11], v[14:15]
	v_add_u32_e32 v14, 0xb0, v159
	v_pk_mul_f32 v[10:11], v[2:3], v[10:11]
	v_pk_mul_f32 v[2:3], v[4:5], v[24:25] op_sel_hi:[1,0]
	v_pk_mul_f32 v[4:5], v[12:13], v[16:17]
	s_mov_b32 s44, s8
	v_pk_mul_f32 v[12:13], v[2:3], v[4:5]
	v_cvt_pk_bf16_f32 v2, v6, v7
	v_mad_i64_i32 v[6:7], s[0:1], v14, s41, v[114:115]
	v_cvt_pk_bf16_f32 v3, v8, v9
	v_cvt_pk_bf16_f32 v4, v10, v11
	v_cvt_pk_bf16_f32 v5, v12, v13
	v_lshl_add_u64 v[6:7], v[6:7], 0, v[116:117]
	s_mov_b32 s18, s12
	s_mov_b64 s[22:23], s[16:17]
	s_mov_b64 s[20:21], s[14:15]
	s_mov_b32 s43, s42
	global_store_dwordx4 v[6:7], v[2:5], off
	s_cbranch_vccz .LBB0_659
	s_waitcnt vmcnt(0)
	s_cmpk_gt_u32 s26, 0xff
	s_cbranch_scc1 .LBB0_666
	s_barrier

.LBB0_706:
	s_add_u32 s8, s8, 0xb0080
	s_addc_u32 s9, s9, 0
	s_add_u32 s42, s16, 0x100
	s_addc_u32 s43, s17, 0
	s_mov_b32 s44, -2
	ds_read_b128 v[144:147], v156
	ds_read_b128 v[148:151], v156 offset:1024
	ds_read_b128 v[160:163], v156 offset:2048
	ds_read_b128 v[164:167], v156 offset:3072
	s_add_u32 s16, s8, 0xfff50080
	s_addc_u32 s17, s9, -1
	s_cmp_eq_u32 s44, 40
	s_cselect_b32 s19, s3, s17
	s_cselect_b32 s18, s2, s16
	s_cselect_b32 s17, s5, s43
	s_cselect_b32 s16, s4, s42
	v_lshl_add_u64 v[200:201], s[8:9], 0, v[136:137]
	s_add_i32 m0, s27, 0xc000
	ds_read_b128 v[168:171], v157
	ds_read_b128 v[172:175], v157 offset:1024
	ds_read_b128 v[176:179], v157 offset:2048
	ds_read_b128 v[180:183], v157 offset:3072
	ds_read_b128 v[184:187], v157 offset:4096
	ds_read_b128 v[188:191], v157 offset:5120
	ds_read_b128 v[192:195], v157 offset:6144
	ds_read_b128 v[196:199], v157 offset:7168
	global_load_lds_dwordx4 v[200:201], off
	v_lshl_add_u64 v[200:201], s[8:9], 0, v[138:139]
	s_add_i32 m0, s27, 0xe000
	s_nop 0
	global_load_lds_dwordx4 v[200:201], off
	s_waitcnt lgkmcnt(8)
	s_barrier
	s_waitcnt lgkmcnt(0)
	s_setprio 1
	s_waitcnt lgkmcnt(0)
	v_mfma_f32_16x16x32_bf16 v[124:127], v[144:147], v[168:171], 0
	v_mfma_f32_16x16x32_bf16 v[120:123], v[160:163], v[168:171], 0
	v_mfma_f32_16x16x32_bf16 v[108:111], v[144:147], v[176:179], 0
	v_mfma_f32_16x16x32_bf16 v[104:107], v[160:163], v[176:179], 0
	v_mfma_f32_16x16x32_bf16 v[92:95], v[144:147], v[184:187], 0
	v_mfma_f32_16x16x32_bf16 v[88:91], v[160:163], v[184:187], 0
	v_mfma_f32_16x16x32_bf16 v[80:83], v[144:147], v[192:195], 0
	v_mfma_f32_16x16x32_bf16 v[72:75], v[160:163], v[192:195], 0
	v_mfma_f32_16x16x32_bf16 v[124:127], v[148:151], v[172:175], v[124:127]
	v_mfma_f32_16x16x32_bf16 v[120:123], v[164:167], v[172:175], v[120:123]
	v_mfma_f32_16x16x32_bf16 v[108:111], v[148:151], v[180:183], v[108:111]
	v_mfma_f32_16x16x32_bf16 v[104:107], v[164:167], v[180:183], v[104:107]
	v_mfma_f32_16x16x32_bf16 v[92:95], v[148:151], v[188:191], v[92:95]
	v_mfma_f32_16x16x32_bf16 v[88:91], v[164:167], v[188:191], v[88:91]
	v_mfma_f32_16x16x32_bf16 v[80:83], v[148:151], v[196:199], v[80:83]
	v_mfma_f32_16x16x32_bf16 v[72:75], v[164:167], v[196:199], v[72:75]
	s_setprio 0
	s_barrier
	s_add_i32 s45, s36, s26
	v_lshl_add_u64 v[216:217], s[16:17], 0, v[130:131]
	s_mov_b32 m0, s45
	ds_read_b128 v[200:203], v158
	ds_read_b128 v[204:207], v158 offset:1024
	ds_read_b128 v[208:211], v158 offset:2048
	ds_read_b128 v[212:215], v158 offset:3072
	global_load_lds_dwordx4 v[216:217], off
	v_lshl_add_u64 v[218:219], s[16:17], 0, v[134:135]
	s_add_i32 m0, s45, 0x2000
	s_nop 0
	global_load_lds_dwordx4 v[218:219], off
	s_barrier
	s_waitcnt lgkmcnt(0)
	s_setprio 1
	s_waitcnt lgkmcnt(0)
	v_mfma_f32_16x16x32_bf16 v[116:119], v[200:203], v[168:171], 0
	v_mfma_f32_16x16x32_bf16 v[112:115], v[208:211], v[168:171], 0
	v_mfma_f32_16x16x32_bf16 v[100:103], v[200:203], v[176:179], 0
	v_mfma_f32_16x16x32_bf16 v[96:99], v[208:211], v[176:179], 0
	v_mfma_f32_16x16x32_bf16 v[84:87], v[200:203], v[184:187], 0
	v_mfma_f32_16x16x32_bf16 v[76:79], v[208:211], v[184:187], 0
	v_mfma_f32_16x16x32_bf16 v[68:71], v[200:203], v[192:195], 0
	v_mfma_f32_16x16x32_bf16 v[64:67], v[208:211], v[192:195], 0
	v_mfma_f32_16x16x32_bf16 v[116:119], v[204:207], v[172:175], v[116:119]
	v_mfma_f32_16x16x32_bf16 v[112:115], v[212:215], v[172:175], v[112:115]
	v_mfma_f32_16x16x32_bf16 v[100:103], v[204:207], v[180:183], v[100:103]
	v_mfma_f32_16x16x32_bf16 v[96:99], v[212:215], v[180:183], v[96:99]
	v_mfma_f32_16x16x32_bf16 v[84:87], v[204:207], v[188:191], v[84:87]
	v_mfma_f32_16x16x32_bf16 v[76:79], v[212:215], v[188:191], v[76:79]
	v_mfma_f32_16x16x32_bf16 v[68:71], v[204:207], v[196:199], v[68:71]
	v_mfma_f32_16x16x32_bf16 v[64:67], v[212:215], v[196:199], v[64:67]
	s_setprio 0
	s_mov_b32 m0, s27
	v_lshl_add_u64 v[220:221], s[18:19], 0, v[128:129]
	s_barrier
	ds_read_b128 v[168:171], v157 offset:16384
	ds_read_b128 v[172:175], v157 offset:17408
	ds_read_b128 v[176:179], v157 offset:18432
	ds_read_b128 v[180:183], v157 offset:19456
	ds_read_b128 v[184:187], v157 offset:20480
	ds_read_b128 v[188:191], v157 offset:21504
	ds_read_b128 v[192:195], v157 offset:22528
	ds_read_b128 v[196:199], v157 offset:23552
	global_load_lds_dwordx4 v[220:221], off
	v_lshl_add_u64 v[222:223], s[18:19], 0, v[132:133]
	s_mov_b32 m0, s28
	s_nop 0
	global_load_lds_dwordx4 v[222:223], off
	s_barrier
	s_waitcnt lgkmcnt(0)
	s_setprio 1
	s_waitcnt lgkmcnt(0)
	v_mfma_f32_16x16x32_bf16 v[60:63], v[144:147], v[168:171], 0
	v_mfma_f32_16x16x32_bf16 v[56:59], v[160:163], v[168:171], 0
	v_mfma_f32_16x16x32_bf16 v[48:51], v[144:147], v[176:179], 0
	v_mfma_f32_16x16x32_bf16 v[40:43], v[160:163], v[176:179], 0
	v_mfma_f32_16x16x32_bf16 v[32:35], v[144:147], v[184:187], 0
	v_mfma_f32_16x16x32_bf16 v[24:27], v[160:163], v[184:187], 0
	v_mfma_f32_16x16x32_bf16 v[16:19], v[144:147], v[192:195], 0
	v_mfma_f32_16x16x32_bf16 v[8:11], v[160:163], v[192:195], 0
	v_mfma_f32_16x16x32_bf16 v[60:63], v[148:151], v[172:175], v[60:63]
	v_mfma_f32_16x16x32_bf16 v[56:59], v[164:167], v[172:175], v[56:59]
	v_mfma_f32_16x16x32_bf16 v[48:51], v[148:151], v[180:183], v[48:51]
	v_mfma_f32_16x16x32_bf16 v[40:43], v[164:167], v[180:183], v[40:43]
	v_mfma_f32_16x16x32_bf16 v[32:35], v[148:151], v[188:191], v[32:35]
	v_mfma_f32_16x16x32_bf16 v[24:27], v[164:167], v[188:191], v[24:27]
	v_mfma_f32_16x16x32_bf16 v[16:19], v[148:151], v[196:199], v[16:19]
	v_mfma_f32_16x16x32_bf16 v[8:11], v[164:167], v[196:199], v[8:11]
	s_setprio 0
	s_barrier
	s_add_u32 s46, s16, 0xb0000
	s_addc_u32 s47, s17, 0
	s_add_i32 s45, s37, s26
	v_lshl_add_u64 v[144:145], s[46:47], 0, v[130:131]
	s_mov_b32 m0, s45
	s_nop 0
	global_load_lds_dwordx4 v[144:145], off
	v_lshl_add_u64 v[144:145], s[46:47], 0, v[134:135]
	s_add_i32 m0, s45, 0x2000
	s_nop 0
	global_load_lds_dwordx4 v[144:145], off
	s_waitcnt vmcnt(6)
	s_barrier
	s_setprio 1
	v_mfma_f32_16x16x32_bf16 v[52:55], v[200:203], v[168:171], 0
	v_mfma_f32_16x16x32_bf16 v[44:47], v[208:211], v[168:171], 0
	v_mfma_f32_16x16x32_bf16 v[36:39], v[200:203], v[176:179], 0
	v_mfma_f32_16x16x32_bf16 v[28:31], v[208:211], v[176:179], 0
	v_mfma_f32_16x16x32_bf16 v[20:23], v[200:203], v[184:187], 0
	v_mfma_f32_16x16x32_bf16 v[12:15], v[208:211], v[184:187], 0
	v_mfma_f32_16x16x32_bf16 v[4:7], v[200:203], v[192:195], 0
	v_mfma_f32_16x16x32_bf16 v[0:3], v[208:211], v[192:195], 0
	v_mfma_f32_16x16x32_bf16 v[52:55], v[204:207], v[172:175], v[52:55]
	v_mfma_f32_16x16x32_bf16 v[44:47], v[212:215], v[172:175], v[44:47]
	v_mfma_f32_16x16x32_bf16 v[36:39], v[204:207], v[180:183], v[36:39]
	v_mfma_f32_16x16x32_bf16 v[28:31], v[212:215], v[180:183], v[28:31]
	v_mfma_f32_16x16x32_bf16 v[20:23], v[204:207], v[188:191], v[20:23]
	v_mfma_f32_16x16x32_bf16 v[12:15], v[212:215], v[188:191], v[12:15]
	v_mfma_f32_16x16x32_bf16 v[4:7], v[204:207], v[196:199], v[4:7]
	v_mfma_f32_16x16x32_bf16 v[0:3], v[212:215], v[196:199], v[0:3]
	s_setprio 0
	s_add_i32 s45, 0, 0x18000
	v_add_u32_e32 v159, s45, v154
	s_barrier
	ds_read_b128 v[144:147], v159
	ds_read_b128 v[148:151], v159 offset:1024
	ds_read_b128 v[160:163], v159 offset:2048
	ds_read_b128 v[164:167], v159 offset:3072
	s_add_u32 s18, s18, 0xb0000
	s_addc_u32 s19, s19, 0
	s_mov_b32 m0, s29
	v_lshl_add_u64 v[200:201], s[18:19], 0, v[128:129]
	ds_read_b128 v[168:171], v157 offset:32768
	ds_read_b128 v[172:175], v157 offset:33792
	ds_read_b128 v[176:179], v157 offset:34816
	ds_read_b128 v[180:183], v157 offset:35840
	ds_read_b128 v[184:187], v157 offset:36864
	ds_read_b128 v[188:191], v157 offset:37888
	ds_read_b128 v[192:195], v157 offset:38912
	ds_read_b128 v[196:199], v157 offset:39936
	global_load_lds_dwordx4 v[200:201], off
	v_lshl_add_u64 v[200:201], s[18:19], 0, v[132:133]
	s_mov_b32 m0, s30
	s_nop 0
	global_load_lds_dwordx4 v[200:201], off
	s_waitcnt lgkmcnt(8)
	s_barrier
	s_waitcnt lgkmcnt(0)
	s_setprio 1
	s_waitcnt lgkmcnt(0)
	v_mfma_f32_16x16x32_bf16 v[124:127], v[144:147], v[168:171], v[124:127]
	v_mfma_f32_16x16x32_bf16 v[120:123], v[160:163], v[168:171], v[120:123]
	v_mfma_f32_16x16x32_bf16 v[108:111], v[144:147], v[176:179], v[108:111]
	v_mfma_f32_16x16x32_bf16 v[104:107], v[160:163], v[176:179], v[104:107]
	v_mfma_f32_16x16x32_bf16 v[92:95], v[144:147], v[184:187], v[92:95]
	v_mfma_f32_16x16x32_bf16 v[88:91], v[160:163], v[184:187], v[88:91]
	v_mfma_f32_16x16x32_bf16 v[80:83], v[144:147], v[192:195], v[80:83]
	v_mfma_f32_16x16x32_bf16 v[72:75], v[160:163], v[192:195], v[72:75]
	v_mfma_f32_16x16x32_bf16 v[124:127], v[148:151], v[172:175], v[124:127]
	v_mfma_f32_16x16x32_bf16 v[120:123], v[164:167], v[172:175], v[120:123]
	v_mfma_f32_16x16x32_bf16 v[108:111], v[148:151], v[180:183], v[108:111]
	v_mfma_f32_16x16x32_bf16 v[104:107], v[164:167], v[180:183], v[104:107]
	v_mfma_f32_16x16x32_bf16 v[92:95], v[148:151], v[188:191], v[92:95]
	v_mfma_f32_16x16x32_bf16 v[88:91], v[164:167], v[188:191], v[88:91]
	v_mfma_f32_16x16x32_bf16 v[80:83], v[148:151], v[196:199], v[80:83]
	v_mfma_f32_16x16x32_bf16 v[72:75], v[164:167], v[196:199], v[72:75]
	s_setprio 0
	s_barrier
	s_add_i32 s18, 0, 0x1c000
	s_add_i32 s19, s45, s26
	v_add_u32_e32 v159, s18, v154
	v_lshl_add_u64 v[216:217], v[216:217], 0, s[6:7]
	s_mov_b32 m0, s19
	ds_read_b128 v[200:203], v159
	ds_read_b128 v[204:207], v159 offset:1024
	ds_read_b128 v[208:211], v159 offset:2048
	ds_read_b128 v[212:215], v159 offset:3072
	global_load_lds_dwordx4 v[216:217], off
	v_lshl_add_u64 v[216:217], v[218:219], 0, s[6:7]
	s_add_i32 m0, s19, 0x2000
	s_nop 0
	global_load_lds_dwordx4 v[216:217], off
	s_barrier
	s_waitcnt lgkmcnt(0)
	s_setprio 1
	s_waitcnt lgkmcnt(0)
	v_mfma_f32_16x16x32_bf16 v[116:119], v[200:203], v[168:171], v[116:119]
	v_mfma_f32_16x16x32_bf16 v[112:115], v[208:211], v[168:171], v[112:115]
	v_mfma_f32_16x16x32_bf16 v[100:103], v[200:203], v[176:179], v[100:103]
	v_mfma_f32_16x16x32_bf16 v[96:99], v[208:211], v[176:179], v[96:99]
	v_mfma_f32_16x16x32_bf16 v[84:87], v[200:203], v[184:187], v[84:87]
	v_mfma_f32_16x16x32_bf16 v[76:79], v[208:211], v[184:187], v[76:79]
	v_mfma_f32_16x16x32_bf16 v[68:71], v[200:203], v[192:195], v[68:71]
	v_mfma_f32_16x16x32_bf16 v[64:67], v[208:211], v[192:195], v[64:67]
	v_mfma_f32_16x16x32_bf16 v[116:119], v[204:207], v[172:175], v[116:119]
	v_mfma_f32_16x16x32_bf16 v[112:115], v[212:215], v[172:175], v[112:115]
	v_mfma_f32_16x16x32_bf16 v[100:103], v[204:207], v[180:183], v[100:103]
	v_mfma_f32_16x16x32_bf16 v[96:99], v[212:215], v[180:183], v[96:99]
	v_mfma_f32_16x16x32_bf16 v[84:87], v[204:207], v[188:191], v[84:87]
	v_mfma_f32_16x16x32_bf16 v[76:79], v[212:215], v[188:191], v[76:79]
	v_mfma_f32_16x16x32_bf16 v[68:71], v[204:207], v[196:199], v[68:71]
	v_mfma_f32_16x16x32_bf16 v[64:67], v[212:215], v[196:199], v[64:67]
	s_setprio 0
	s_mov_b32 m0, s33
	v_lshl_add_u64 v[216:217], v[220:221], 0, s[6:7]
	s_barrier
	ds_read_b128 v[168:171], v157 offset:49152
	ds_read_b128 v[172:175], v157 offset:50176
	ds_read_b128 v[176:179], v157 offset:51200
	ds_read_b128 v[180:183], v157 offset:52224
	ds_read_b128 v[184:187], v157 offset:53248
	ds_read_b128 v[188:191], v157 offset:54272
	ds_read_b128 v[192:195], v157 offset:55296
	ds_read_b128 v[196:199], v157 offset:56320
	global_load_lds_dwordx4 v[216:217], off
	v_lshl_add_u64 v[216:217], v[222:223], 0, s[6:7]
	s_mov_b32 m0, s34
	s_nop 0
	global_load_lds_dwordx4 v[216:217], off
	s_barrier
	s_waitcnt lgkmcnt(0)
	s_setprio 1
	s_waitcnt lgkmcnt(0)
	v_mfma_f32_16x16x32_bf16 v[60:63], v[144:147], v[168:171], v[60:63]
	v_mfma_f32_16x16x32_bf16 v[56:59], v[160:163], v[168:171], v[56:59]
	v_mfma_f32_16x16x32_bf16 v[48:51], v[144:147], v[176:179], v[48:51]
	v_mfma_f32_16x16x32_bf16 v[40:43], v[160:163], v[176:179], v[40:43]
	v_mfma_f32_16x16x32_bf16 v[32:35], v[144:147], v[184:187], v[32:35]
	v_mfma_f32_16x16x32_bf16 v[24:27], v[160:163], v[184:187], v[24:27]
	v_mfma_f32_16x16x32_bf16 v[16:19], v[144:147], v[192:195], v[16:19]
	v_mfma_f32_16x16x32_bf16 v[8:11], v[160:163], v[192:195], v[8:11]
	v_mfma_f32_16x16x32_bf16 v[60:63], v[148:151], v[172:175], v[60:63]
	v_mfma_f32_16x16x32_bf16 v[56:59], v[164:167], v[172:175], v[56:59]
	v_mfma_f32_16x16x32_bf16 v[48:51], v[148:151], v[180:183], v[48:51]
	v_mfma_f32_16x16x32_bf16 v[40:43], v[164:167], v[180:183], v[40:43]
	v_mfma_f32_16x16x32_bf16 v[32:35], v[148:151], v[188:191], v[32:35]
	v_mfma_f32_16x16x32_bf16 v[24:27], v[164:167], v[188:191], v[24:27]
	v_mfma_f32_16x16x32_bf16 v[16:19], v[148:151], v[196:199], v[16:19]
	v_mfma_f32_16x16x32_bf16 v[8:11], v[164:167], v[196:199], v[8:11]
	s_setprio 0
	s_barrier
	s_add_u32 s16, s16, 0xb0080
	s_addc_u32 s17, s17, 0
	s_add_i32 s18, s18, s26
	v_lshl_add_u64 v[144:145], s[16:17], 0, v[130:131]
	s_mov_b32 m0, s18
	s_nop 0
	global_load_lds_dwordx4 v[144:145], off
	v_lshl_add_u64 v[144:145], s[16:17], 0, v[134:135]
	s_add_i32 m0, s18, 0x2000
	s_nop 0
	global_load_lds_dwordx4 v[144:145], off
	s_waitcnt vmcnt(6)
	s_barrier
	s_setprio 1
	v_mfma_f32_16x16x32_bf16 v[52:55], v[200:203], v[168:171], v[52:55]
	v_mfma_f32_16x16x32_bf16 v[44:47], v[208:211], v[168:171], v[44:47]
	v_mfma_f32_16x16x32_bf16 v[36:39], v[200:203], v[176:179], v[36:39]
	v_mfma_f32_16x16x32_bf16 v[28:31], v[208:211], v[176:179], v[28:31]
	v_mfma_f32_16x16x32_bf16 v[20:23], v[200:203], v[184:187], v[20:23]
	v_mfma_f32_16x16x32_bf16 v[12:15], v[208:211], v[184:187], v[12:15]
	v_mfma_f32_16x16x32_bf16 v[4:7], v[200:203], v[192:195], v[4:7]
	v_mfma_f32_16x16x32_bf16 v[0:3], v[208:211], v[192:195], v[0:3]
	v_mfma_f32_16x16x32_bf16 v[52:55], v[204:207], v[172:175], v[52:55]
	v_mfma_f32_16x16x32_bf16 v[44:47], v[212:215], v[172:175], v[44:47]
	v_mfma_f32_16x16x32_bf16 v[36:39], v[204:207], v[180:183], v[36:39]
	v_mfma_f32_16x16x32_bf16 v[28:31], v[212:215], v[180:183], v[28:31]
	v_mfma_f32_16x16x32_bf16 v[20:23], v[204:207], v[188:191], v[20:23]
	v_mfma_f32_16x16x32_bf16 v[12:15], v[212:215], v[188:191], v[12:15]
	v_mfma_f32_16x16x32_bf16 v[4:7], v[204:207], v[196:199], v[4:7]
	v_mfma_f32_16x16x32_bf16 v[0:3], v[212:215], v[196:199], v[0:3]
	s_setprio 0
	s_add_i32 s44, s44, 2
	s_add_u32 s8, s8, 0x100
	s_addc_u32 s9, s9, 0
	s_add_u32 s42, s42, 0x100
	s_addc_u32 s43, s43, 0
	s_cmp_gt_u32 s44, 41
	s_barrier
	s_cbranch_scc1 .Lgemm_epi5

.Lgemm_epi5:
	v_lshl_add_u32 v148, s40, 8, v153
	v_lshl_or_b32 v144, s41, 8, v155
	v_ashrrev_i32_e32 v145, 31, v144
	v_ashrrev_i32_e32 v149, 31, v148
	v_lshl_add_u64 v[146:147], v[144:145], 1, s[14:15]
	v_lshlrev_b64 v[150:151], 11, v[148:149]
	v_or_b32_e32 v180, 16, v148
	v_lshl_add_u64 v[150:151], v[146:147], 0, v[150:151]
	v_ashrrev_i32_e32 v181, 31, v180
	global_load_dwordx4 v[160:163], v[150:151], off
	global_load_dwordx4 v[164:167], v[150:151], off offset:256
	v_lshlrev_b64 v[150:151], 11, v[180:181]
	v_or_b32_e32 v192, 32, v148
	v_lshl_add_u64 v[150:151], v[146:147], 0, v[150:151]
	v_ashrrev_i32_e32 v193, 31, v192
	global_load_dwordx4 v[168:171], v[150:151], off
	global_load_dwordx4 v[172:175], v[150:151], off offset:256
	v_lshlrev_b64 v[150:151], 11, v[192:193]
	v_lshl_add_u64 v[182:183], v[146:147], 0, v[150:151]
	global_load_dwordx4 v[176:179], v[182:183], off
	v_or_b32_e32 v150, 48, v148
	v_ashrrev_i32_e32 v151, 31, v150
	v_lshlrev_b64 v[188:189], 12, v[180:181]
	global_load_dwordx4 v[180:183], v[182:183], off offset:256
	v_lshlrev_b64 v[184:185], 12, v[148:149]
	v_lshlrev_b64 v[186:187], 11, v[150:151]
	v_lshlrev_b64 v[144:145], 2, v[144:145]
	v_lshl_add_u64 v[184:185], s[12:13], 0, v[184:185]
	v_lshl_add_u64 v[190:191], v[146:147], 0, v[186:187]
	v_lshl_add_u64 v[194:195], v[184:185], 0, v[144:145]
	v_lshl_add_u64 v[196:197], s[12:13], 0, v[188:189]
	global_load_dwordx4 v[184:187], v[190:191], off
	s_nop 0
	global_load_dwordx4 v[188:191], v[190:191], off offset:256
	v_lshl_add_u64 v[196:197], v[196:197], 0, v[144:145]
	s_and_b64 vcc, exec, s[0:1]
	s_mov_b32 s41, s38
	s_mov_b32 s40, s39
	s_mov_b64 s[16:17], s[4:5]
	s_mov_b64 s[8:9], s[2:3]
	s_waitcnt vmcnt(0)
	v_lshlrev_b32_e32 v198, 16, v160
	v_and_b32_e32 v199, 0xffff0000, v160
	v_lshlrev_b32_e32 v160, 16, v161
	v_and_b32_e32 v161, 0xffff0000, v161
	v_lshlrev_b32_e32 v200, 16, v162
	v_and_b32_e32 v201, 0xffff0000, v162
	v_lshlrev_b32_e32 v162, 16, v163
	v_and_b32_e32 v163, 0xffff0000, v163
	v_lshlrev_b32_e32 v202, 16, v164
	v_and_b32_e32 v203, 0xffff0000, v164
	v_lshlrev_b32_e32 v164, 16, v165
	v_and_b32_e32 v165, 0xffff0000, v165
	v_lshlrev_b32_e32 v204, 16, v166
	v_and_b32_e32 v205, 0xffff0000, v166
	v_lshlrev_b32_e32 v166, 16, v167
	v_and_b32_e32 v167, 0xffff0000, v167
	v_pk_fma_f32 v[126:127], v[126:127], 0.5, v[160:161] op_sel_hi:[1,0,1]
	v_pk_fma_f32 v[122:123], v[122:123], 0.5, v[162:163] op_sel_hi:[1,0,1]
	v_pk_fma_f32 v[118:119], v[118:119], 0.5, v[164:165] op_sel_hi:[1,0,1]
	v_pk_fma_f32 v[114:115], v[114:115], 0.5, v[166:167] op_sel_hi:[1,0,1]
	v_lshlrev_b32_e32 v160, 16, v168
	v_and_b32_e32 v161, 0xffff0000, v168
	v_lshlrev_b32_e32 v162, 16, v169
	v_and_b32_e32 v163, 0xffff0000, v169
	v_lshlrev_b32_e32 v164, 16, v170
	v_and_b32_e32 v165, 0xffff0000, v170
	v_lshlrev_b32_e32 v166, 16, v171
	v_and_b32_e32 v167, 0xffff0000, v171
	v_lshlrev_b32_e32 v168, 16, v172
	v_and_b32_e32 v169, 0xffff0000, v172
	v_lshlrev_b32_e32 v170, 16, v173
	v_and_b32_e32 v171, 0xffff0000, v173
	v_lshlrev_b32_e32 v172, 16, v174
	v_and_b32_e32 v173, 0xffff0000, v174
	v_pk_fma_f32 v[124:125], v[124:125], 0.5, v[198:199] op_sel_hi:[1,0,1]
	v_lshlrev_b32_e32 v174, 16, v175
	v_and_b32_e32 v175, 0xffff0000, v175
	v_pk_fma_f32 v[110:111], v[110:111], 0.5, v[162:163] op_sel_hi:[1,0,1]
	v_pk_fma_f32 v[108:109], v[108:109], 0.5, v[160:161] op_sel_hi:[1,0,1]
	v_pk_fma_f32 v[96:97], v[96:97], 0.5, v[172:173] op_sel_hi:[1,0,1]
	v_pk_fma_f32 v[120:121], v[120:121], 0.5, v[200:201] op_sel_hi:[1,0,1]
	v_pk_fma_f32 v[116:117], v[116:117], 0.5, v[202:203] op_sel_hi:[1,0,1]
	v_pk_fma_f32 v[112:113], v[112:113], 0.5, v[204:205] op_sel_hi:[1,0,1]
	global_store_dwordx4 v[194:195], v[124:127], off
	global_store_dwordx4 v[194:195], v[120:123], off offset:16
	global_store_dwordx4 v[194:195], v[116:119], off offset:512
	global_store_dwordx4 v[194:195], v[112:115], off offset:528
	v_pk_fma_f32 v[106:107], v[106:107], 0.5, v[166:167] op_sel_hi:[1,0,1]
	v_pk_fma_f32 v[104:105], v[104:105], 0.5, v[164:165] op_sel_hi:[1,0,1]
	v_pk_fma_f32 v[102:103], v[102:103], 0.5, v[170:171] op_sel_hi:[1,0,1]
	v_pk_fma_f32 v[100:101], v[100:101], 0.5, v[168:169] op_sel_hi:[1,0,1]
	v_pk_fma_f32 v[98:99], v[98:99], 0.5, v[174:175] op_sel_hi:[1,0,1]
	global_store_dwordx4 v[196:197], v[108:111], off
	global_store_dwordx4 v[196:197], v[104:107], off offset:16
	global_store_dwordx4 v[196:197], v[100:103], off offset:512
	global_store_dwordx4 v[196:197], v[96:99], off offset:528
	s_nop 0
	v_lshlrev_b32_e32 v100, 16, v178
	v_lshlrev_b32_e32 v96, 16, v176
	v_and_b32_e32 v97, 0xffff0000, v176
	v_pk_fma_f32 v[92:93], v[92:93], 0.5, v[96:97] op_sel_hi:[1,0,1]
	v_lshlrev_b64 v[96:97], 12, v[192:193]
	v_lshlrev_b32_e32 v98, 16, v177
	v_and_b32_e32 v99, 0xffff0000, v177
	v_and_b32_e32 v101, 0xffff0000, v178
	v_lshlrev_b32_e32 v102, 16, v179
	v_and_b32_e32 v103, 0xffff0000, v179
	v_lshl_add_u64 v[96:97], s[12:13], 0, v[96:97]
	v_pk_fma_f32 v[94:95], v[94:95], 0.5, v[98:99] op_sel_hi:[1,0,1]
	v_pk_fma_f32 v[90:91], v[90:91], 0.5, v[102:103] op_sel_hi:[1,0,1]
	v_pk_fma_f32 v[88:89], v[88:89], 0.5, v[100:101] op_sel_hi:[1,0,1]
	v_lshl_add_u64 v[96:97], v[96:97], 0, v[144:145]
	global_store_dwordx4 v[96:97], v[92:95], off
	global_store_dwordx4 v[96:97], v[88:91], off offset:16
	v_add_u32_e32 v98, 0x90, v148
	v_lshlrev_b32_e32 v92, 16, v182
	v_lshlrev_b32_e32 v88, 16, v180
	v_and_b32_e32 v89, 0xffff0000, v180
	v_lshlrev_b32_e32 v90, 16, v181
	v_and_b32_e32 v91, 0xffff0000, v181
	v_and_b32_e32 v93, 0xffff0000, v182
	v_lshlrev_b32_e32 v94, 16, v183
	v_and_b32_e32 v95, 0xffff0000, v183
	v_pk_fma_f32 v[86:87], v[86:87], 0.5, v[90:91] op_sel_hi:[1,0,1]
	v_pk_fma_f32 v[84:85], v[84:85], 0.5, v[88:89] op_sel_hi:[1,0,1]
	v_pk_fma_f32 v[76:77], v[76:77], 0.5, v[92:93] op_sel_hi:[1,0,1]
	v_pk_fma_f32 v[78:79], v[78:79], 0.5, v[94:95] op_sel_hi:[1,0,1]
	global_store_dwordx4 v[96:97], v[84:87], off offset:512
	global_store_dwordx4 v[96:97], v[76:79], off offset:528
	v_add_u32_e32 v96, 0x80, v148
	v_lshlrev_b32_e32 v84, 16, v186
	v_lshlrev_b32_e32 v76, 16, v184
	v_and_b32_e32 v77, 0xffff0000, v184
	v_pk_fma_f32 v[76:77], v[80:81], 0.5, v[76:77] op_sel_hi:[1,0,1]
	v_lshlrev_b64 v[80:81], 12, v[150:151]
	v_lshlrev_b32_e32 v78, 16, v185
	v_and_b32_e32 v79, 0xffff0000, v185
	v_and_b32_e32 v85, 0xffff0000, v186
	v_lshlrev_b32_e32 v86, 16, v187
	v_and_b32_e32 v87, 0xffff0000, v187
	v_lshl_add_u64 v[80:81], s[12:13], 0, v[80:81]
	v_pk_fma_f32 v[78:79], v[82:83], 0.5, v[78:79] op_sel_hi:[1,0,1]
	v_pk_fma_f32 v[74:75], v[74:75], 0.5, v[86:87] op_sel_hi:[1,0,1]
	v_pk_fma_f32 v[72:73], v[72:73], 0.5, v[84:85] op_sel_hi:[1,0,1]
	v_lshl_add_u64 v[80:81], v[80:81], 0, v[144:145]
	global_store_dwordx4 v[80:81], v[76:79], off
	global_store_dwordx4 v[80:81], v[72:75], off offset:16
	v_ashrrev_i32_e32 v97, 31, v96
	v_lshlrev_b32_e32 v76, 16, v190
	v_lshlrev_b32_e32 v72, 16, v188
	v_and_b32_e32 v73, 0xffff0000, v188
	v_lshlrev_b32_e32 v74, 16, v189
	v_and_b32_e32 v75, 0xffff0000, v189
	v_and_b32_e32 v77, 0xffff0000, v190
	v_lshlrev_b32_e32 v78, 16, v191
	v_and_b32_e32 v79, 0xffff0000, v191
	v_pk_fma_f32 v[70:71], v[70:71], 0.5, v[74:75] op_sel_hi:[1,0,1]
	v_pk_fma_f32 v[68:69], v[68:69], 0.5, v[72:73] op_sel_hi:[1,0,1]
	v_pk_fma_f32 v[64:65], v[64:65], 0.5, v[76:77] op_sel_hi:[1,0,1]
	v_pk_fma_f32 v[66:67], v[66:67], 0.5, v[78:79] op_sel_hi:[1,0,1]
	global_store_dwordx4 v[80:81], v[68:71], off offset:512
	global_store_dwordx4 v[80:81], v[64:67], off offset:528
	v_ashrrev_i32_e32 v99, 31, v98
	v_add_u32_e32 v100, 0xa0, v148
	v_lshlrev_b64 v[64:65], 11, v[96:97]
	v_lshl_add_u64 v[64:65], v[146:147], 0, v[64:65]
	global_load_dwordx4 v[68:71], v[64:65], off
	global_load_dwordx4 v[72:75], v[64:65], off offset:256
	v_lshlrev_b64 v[64:65], 11, v[98:99]
	v_lshl_add_u64 v[64:65], v[146:147], 0, v[64:65]
	global_load_dwordx4 v[76:79], v[64:65], off
	global_load_dwordx4 v[80:83], v[64:65], off offset:256
	v_ashrrev_i32_e32 v101, 31, v100
	v_lshlrev_b64 v[64:65], 11, v[100:101]
	v_lshl_add_u64 v[64:65], v[146:147], 0, v[64:65]
	global_load_dwordx4 v[84:87], v[64:65], off
	global_load_dwordx4 v[88:91], v[64:65], off offset:256
	v_add_u32_e32 v102, 0xb0, v148
	v_ashrrev_i32_e32 v103, 31, v102
	v_lshlrev_b64 v[64:65], 11, v[102:103]
	v_lshl_add_u64 v[64:65], v[146:147], 0, v[64:65]
	global_load_dwordx4 v[92:95], v[64:65], off
	s_nop 0
	global_load_dwordx4 v[64:67], v[64:65], off offset:256
	s_waitcnt vmcnt(0)
	v_lshlrev_b32_e32 v104, 16, v68
	v_and_b32_e32 v105, 0xffff0000, v68
	v_lshlrev_b32_e32 v68, 16, v69
	v_and_b32_e32 v69, 0xffff0000, v69
	v_pk_fma_f32 v[62:63], v[62:63], 0.5, v[68:69] op_sel_hi:[1,0,1]
	v_lshlrev_b64 v[68:69], 12, v[96:97]
	v_lshlrev_b32_e32 v106, 16, v70
	v_and_b32_e32 v107, 0xffff0000, v70
	v_lshlrev_b32_e32 v70, 16, v71
	v_and_b32_e32 v71, 0xffff0000, v71
	v_lshl_add_u64 v[68:69], s[12:13], 0, v[68:69]
	v_pk_fma_f32 v[60:61], v[60:61], 0.5, v[104:105] op_sel_hi:[1,0,1]
	v_pk_fma_f32 v[58:59], v[58:59], 0.5, v[70:71] op_sel_hi:[1,0,1]
	v_pk_fma_f32 v[56:57], v[56:57], 0.5, v[106:107] op_sel_hi:[1,0,1]
	v_lshl_add_u64 v[68:69], v[68:69], 0, v[144:145]
	global_store_dwordx4 v[68:69], v[60:63], off
	global_store_dwordx4 v[68:69], v[56:59], off offset:16
	s_nop 0
	v_lshlrev_b32_e32 v60, 16, v74
	v_lshlrev_b32_e32 v56, 16, v72
	v_and_b32_e32 v57, 0xffff0000, v72
	v_lshlrev_b32_e32 v58, 16, v73
	v_and_b32_e32 v59, 0xffff0000, v73
	v_and_b32_e32 v61, 0xffff0000, v74
	v_lshlrev_b32_e32 v62, 16, v75
	v_and_b32_e32 v63, 0xffff0000, v75
	v_pk_fma_f32 v[54:55], v[54:55], 0.5, v[58:59] op_sel_hi:[1,0,1]
	v_pk_fma_f32 v[52:53], v[52:53], 0.5, v[56:57] op_sel_hi:[1,0,1]
	v_pk_fma_f32 v[44:45], v[44:45], 0.5, v[60:61] op_sel_hi:[1,0,1]
	v_pk_fma_f32 v[46:47], v[46:47], 0.5, v[62:63] op_sel_hi:[1,0,1]
	global_store_dwordx4 v[68:69], v[52:55], off offset:512
	global_store_dwordx4 v[68:69], v[44:47], off offset:528
	s_nop 0
	v_lshlrev_b32_e32 v52, 16, v78
	v_lshlrev_b32_e32 v44, 16, v76
	v_and_b32_e32 v45, 0xffff0000, v76
	v_pk_fma_f32 v[44:45], v[48:49], 0.5, v[44:45] op_sel_hi:[1,0,1]
	v_lshlrev_b64 v[48:49], 12, v[98:99]
	v_lshlrev_b32_e32 v46, 16, v77
	v_and_b32_e32 v47, 0xffff0000, v77
	v_and_b32_e32 v53, 0xffff0000, v78
	v_lshlrev_b32_e32 v54, 16, v79
	v_and_b32_e32 v55, 0xffff0000, v79
	v_lshl_add_u64 v[48:49], s[12:13], 0, v[48:49]
	v_pk_fma_f32 v[46:47], v[50:51], 0.5, v[46:47] op_sel_hi:[1,0,1]
	v_pk_fma_f32 v[42:43], v[42:43], 0.5, v[54:55] op_sel_hi:[1,0,1]
	v_pk_fma_f32 v[40:41], v[40:41], 0.5, v[52:53] op_sel_hi:[1,0,1]
	v_lshl_add_u64 v[48:49], v[48:49], 0, v[144:145]
	global_store_dwordx4 v[48:49], v[44:47], off
	global_store_dwordx4 v[48:49], v[40:43], off offset:16
	s_nop 0
	v_lshlrev_b32_e32 v44, 16, v82
	v_lshlrev_b32_e32 v40, 16, v80
	v_and_b32_e32 v41, 0xffff0000, v80
	v_lshlrev_b32_e32 v42, 16, v81
	v_and_b32_e32 v43, 0xffff0000, v81
	v_and_b32_e32 v45, 0xffff0000, v82
	v_lshlrev_b32_e32 v46, 16, v83
	v_and_b32_e32 v47, 0xffff0000, v83
	v_pk_fma_f32 v[38:39], v[38:39], 0.5, v[42:43] op_sel_hi:[1,0,1]
	v_pk_fma_f32 v[36:37], v[36:37], 0.5, v[40:41] op_sel_hi:[1,0,1]
	v_pk_fma_f32 v[28:29], v[28:29], 0.5, v[44:45] op_sel_hi:[1,0,1]
	v_pk_fma_f32 v[30:31], v[30:31], 0.5, v[46:47] op_sel_hi:[1,0,1]
	global_store_dwordx4 v[48:49], v[36:39], off offset:512
	global_store_dwordx4 v[48:49], v[28:31], off offset:528
	s_nop 0
	v_lshlrev_b32_e32 v36, 16, v86
	v_lshlrev_b32_e32 v28, 16, v84
	v_and_b32_e32 v29, 0xffff0000, v84
	v_pk_fma_f32 v[28:29], v[32:33], 0.5, v[28:29] op_sel_hi:[1,0,1]
	v_lshlrev_b64 v[32:33], 12, v[100:101]
	v_lshlrev_b32_e32 v30, 16, v85
	v_and_b32_e32 v31, 0xffff0000, v85
	v_and_b32_e32 v37, 0xffff0000, v86
	v_lshlrev_b32_e32 v38, 16, v87
	v_and_b32_e32 v39, 0xffff0000, v87
	v_lshl_add_u64 v[32:33], s[12:13], 0, v[32:33]
	v_pk_fma_f32 v[30:31], v[34:35], 0.5, v[30:31] op_sel_hi:[1,0,1]
	v_pk_fma_f32 v[26:27], v[26:27], 0.5, v[38:39] op_sel_hi:[1,0,1]
	v_pk_fma_f32 v[24:25], v[24:25], 0.5, v[36:37] op_sel_hi:[1,0,1]
	v_lshl_add_u64 v[32:33], v[32:33], 0, v[144:145]
	global_store_dwordx4 v[32:33], v[28:31], off
	global_store_dwordx4 v[32:33], v[24:27], off offset:16
	s_nop 0
	v_lshlrev_b32_e32 v28, 16, v90
	v_lshlrev_b32_e32 v24, 16, v88
	v_and_b32_e32 v25, 0xffff0000, v88
	v_lshlrev_b32_e32 v26, 16, v89
	v_and_b32_e32 v27, 0xffff0000, v89
	v_and_b32_e32 v29, 0xffff0000, v90
	v_lshlrev_b32_e32 v30, 16, v91
	v_and_b32_e32 v31, 0xffff0000, v91
	v_pk_fma_f32 v[22:23], v[22:23], 0.5, v[26:27] op_sel_hi:[1,0,1]
	v_pk_fma_f32 v[20:21], v[20:21], 0.5, v[24:25] op_sel_hi:[1,0,1]
	v_pk_fma_f32 v[12:13], v[12:13], 0.5, v[28:29] op_sel_hi:[1,0,1]
	v_pk_fma_f32 v[14:15], v[14:15], 0.5, v[30:31] op_sel_hi:[1,0,1]
	global_store_dwordx4 v[32:33], v[20:23], off offset:512
	global_store_dwordx4 v[32:33], v[12:15], off offset:528
	s_nop 0
	v_lshlrev_b32_e32 v20, 16, v94
	v_lshlrev_b32_e32 v12, 16, v92
	v_and_b32_e32 v13, 0xffff0000, v92
	v_pk_fma_f32 v[12:13], v[16:17], 0.5, v[12:13] op_sel_hi:[1,0,1]
	v_lshlrev_b64 v[16:17], 12, v[102:103]
	v_lshlrev_b32_e32 v14, 16, v93
	v_and_b32_e32 v15, 0xffff0000, v93
	v_and_b32_e32 v21, 0xffff0000, v94
	v_lshlrev_b32_e32 v22, 16, v95
	v_and_b32_e32 v23, 0xffff0000, v95
	v_lshl_add_u64 v[16:17], s[12:13], 0, v[16:17]
	v_pk_fma_f32 v[14:15], v[18:19], 0.5, v[14:15] op_sel_hi:[1,0,1]
	v_pk_fma_f32 v[10:11], v[10:11], 0.5, v[22:23] op_sel_hi:[1,0,1]
	v_pk_fma_f32 v[8:9], v[8:9], 0.5, v[20:21] op_sel_hi:[1,0,1]
	v_lshl_add_u64 v[16:17], v[16:17], 0, v[144:145]
	global_store_dwordx4 v[16:17], v[12:15], off
	global_store_dwordx4 v[16:17], v[8:11], off offset:16
	s_nop 0
	v_lshlrev_b32_e32 v12, 16, v66
	v_lshlrev_b32_e32 v8, 16, v64
	v_and_b32_e32 v9, 0xffff0000, v64
	v_lshlrev_b32_e32 v10, 16, v65
	v_and_b32_e32 v11, 0xffff0000, v65
	v_and_b32_e32 v13, 0xffff0000, v66
	v_lshlrev_b32_e32 v14, 16, v67
	v_and_b32_e32 v15, 0xffff0000, v67
	v_pk_fma_f32 v[6:7], v[6:7], 0.5, v[10:11] op_sel_hi:[1,0,1]
	v_pk_fma_f32 v[4:5], v[4:5], 0.5, v[8:9] op_sel_hi:[1,0,1]
	v_pk_fma_f32 v[2:3], v[2:3], 0.5, v[14:15] op_sel_hi:[1,0,1]
	v_pk_fma_f32 v[0:1], v[0:1], 0.5, v[12:13] op_sel_hi:[1,0,1]
	global_store_dwordx4 v[16:17], v[4:7], off offset:512
	global_store_dwordx4 v[16:17], v[0:3], off offset:528
	s_cbranch_vccz .LBB0_696
	s_waitcnt vmcnt(0)
	s_cmpk_gt_u32 s20, 0xff
	s_cbranch_scc1 .LBB0_711
	s_barrier
